# plus: prep_even conv chains unpacked without nop pads; K-loop LOAD m0 wait state via address add, merged waits
# speedup vs baseline: 1.0109x; 1.0109x over previous
.LBB0_120:
	ds_read_b128 v[128:131], v178
	ds_read_b128 v[132:135], v178 offset:1024
	ds_read_b128 v[154:157], v178 offset:2048
	ds_read_b128 v[158:161], v178 offset:3072
	ds_read_b128 v[162:165], v179
	ds_read_b128 v[166:169], v179 offset:1024
	ds_read_b128 v[182:185], v179 offset:2048
	ds_read_b128 v[186:189], v179 offset:3072
	s_add_u32 s67, s88, 0xfffc0080
	s_addc_u32 s68, s89, -1
	s_cmp_eq_u32 s66, 12
	s_cselect_b32 s93, s52, s68
	s_cselect_b32 s92, s53, s67
	s_cselect_b32 s91, s56, s59
	s_cselect_b32 s90, s57, s58
	v_lshl_add_u64 v[170:171], s[88:89], 0, v[144:145]
	s_add_i32 m0, s17, 0xc000
	ds_read_b128 v[190:193], v180
	ds_read_b128 v[194:197], v180 offset:1024
	ds_read_b128 v[198:201], v180 offset:2048
	ds_read_b128 v[202:205], v180 offset:3072
	ds_read_b128 v[206:209], v180 offset:4096
	ds_read_b128 v[210:213], v180 offset:5120
	ds_read_b128 v[214:217], v180 offset:6144
	ds_read_b128 v[218:221], v180 offset:7168
	global_load_lds_dwordx4 v[170:171], off
	s_add_i32 m0, s17, 0xe000
	v_lshl_add_u64 v[170:171], s[88:89], 0, v[148:149]
	global_load_lds_dwordx4 v[170:171], off
	s_cmp_eq_u32 s66, -2
	s_waitcnt vmcnt(8) lgkmcnt(0)
	s_barrier
	s_setprio 1
	s_cbranch_scc1 .Lzv_0_0
	v_mfma_f32_16x16x32_bf16 v[124:127], v[128:131], v[190:193], v[124:127]
	v_mfma_f32_16x16x32_bf16 v[124:127], v[132:135], v[194:197], v[124:127]
	v_mfma_f32_16x16x32_bf16 v[116:119], v[154:157], v[190:193], v[116:119]
	v_mfma_f32_16x16x32_bf16 v[116:119], v[158:161], v[194:197], v[116:119]
	v_mfma_f32_16x16x32_bf16 v[108:111], v[128:131], v[198:201], v[108:111]
	v_mfma_f32_16x16x32_bf16 v[108:111], v[132:135], v[202:205], v[108:111]
	v_mfma_f32_16x16x32_bf16 v[100:103], v[154:157], v[198:201], v[100:103]
	v_mfma_f32_16x16x32_bf16 v[100:103], v[158:161], v[202:205], v[100:103]
	v_mfma_f32_16x16x32_bf16 v[92:95], v[128:131], v[206:209], v[92:95]
	v_mfma_f32_16x16x32_bf16 v[92:95], v[132:135], v[210:213], v[92:95]
	v_mfma_f32_16x16x32_bf16 v[84:87], v[154:157], v[206:209], v[84:87]
	v_mfma_f32_16x16x32_bf16 v[84:87], v[158:161], v[210:213], v[84:87]
	v_mfma_f32_16x16x32_bf16 v[76:79], v[128:131], v[214:217], v[76:79]
	v_mfma_f32_16x16x32_bf16 v[76:79], v[132:135], v[218:221], v[76:79]
	v_mfma_f32_16x16x32_bf16 v[68:71], v[154:157], v[214:217], v[68:71]
	v_mfma_f32_16x16x32_bf16 v[68:71], v[158:161], v[218:221], v[68:71]
	v_mfma_f32_16x16x32_bf16 v[120:123], v[162:165], v[190:193], v[120:123]
	v_mfma_f32_16x16x32_bf16 v[120:123], v[166:169], v[194:197], v[120:123]
	v_mfma_f32_16x16x32_bf16 v[112:115], v[182:185], v[190:193], v[112:115]
	v_mfma_f32_16x16x32_bf16 v[112:115], v[186:189], v[194:197], v[112:115]
	v_mfma_f32_16x16x32_bf16 v[104:107], v[162:165], v[198:201], v[104:107]
	v_mfma_f32_16x16x32_bf16 v[104:107], v[166:169], v[202:205], v[104:107]
	v_mfma_f32_16x16x32_bf16 v[96:99], v[182:185], v[198:201], v[96:99]
	v_mfma_f32_16x16x32_bf16 v[96:99], v[186:189], v[202:205], v[96:99]
	v_mfma_f32_16x16x32_bf16 v[88:91], v[162:165], v[206:209], v[88:91]
	v_mfma_f32_16x16x32_bf16 v[88:91], v[166:169], v[210:213], v[88:91]
	v_mfma_f32_16x16x32_bf16 v[80:83], v[182:185], v[206:209], v[80:83]
	v_mfma_f32_16x16x32_bf16 v[80:83], v[186:189], v[210:213], v[80:83]
	v_mfma_f32_16x16x32_bf16 v[72:75], v[162:165], v[214:217], v[72:75]
	v_mfma_f32_16x16x32_bf16 v[72:75], v[166:169], v[218:221], v[72:75]
	s_setprio 3
	s_barrier
	v_mfma_f32_16x16x32_bf16 v[64:67], v[182:185], v[214:217], v[64:67]
	v_mfma_f32_16x16x32_bf16 v[64:67], v[186:189], v[218:221], v[64:67]
	s_setprio 0
.Lzj_0_0:
	s_add_i32 s67, s25, s16
	v_lshl_add_u64 v[170:171], s[90:91], 0, v[140:141]
	s_mov_b32 m0, s67
	ds_read_b128 v[190:193], v180 offset:16384
	ds_read_b128 v[194:197], v180 offset:17408
	ds_read_b128 v[198:201], v180 offset:18432
	ds_read_b128 v[202:205], v180 offset:19456
	ds_read_b128 v[206:209], v180 offset:20480
	ds_read_b128 v[210:213], v180 offset:21504
	ds_read_b128 v[214:217], v180 offset:22528
	ds_read_b128 v[218:221], v180 offset:23552
	global_load_lds_dwordx4 v[170:171], off
	s_add_i32 m0, s67, 0x2000
	s_add_u32 s68, s90, 0x40000
	v_lshl_add_u64 v[222:223], s[90:91], 0, v[136:137]
	s_addc_u32 s69, s91, 0
	s_add_i32 s67, s26, s16
	global_load_lds_dwordx4 v[222:223], off
	v_lshl_add_u64 v[224:225], s[68:69], 0, v[140:141]
	s_mov_b32 m0, s67
	global_load_lds_dwordx4 v[224:225], off
	s_add_i32 m0, s67, 0x2000
	v_lshl_add_u64 v[224:225], s[68:69], 0, v[136:137]
	global_load_lds_dwordx4 v[224:225], off
	s_mov_b32 m0, s17
	v_lshl_add_u64 v[224:225], s[92:93], 0, v[142:143]
	global_load_lds_dwordx4 v[224:225], off
	s_mov_b32 m0, s18
	v_lshl_add_u64 v[226:227], s[92:93], 0, v[138:139]
	global_load_lds_dwordx4 v[226:227], off
	s_cmp_eq_u32 s66, -2
	s_waitcnt vmcnt(8) lgkmcnt(0)
	s_barrier
	s_setprio 1
	s_cbranch_scc1 .Lzv_0_1
	v_mfma_f32_16x16x32_bf16 v[60:63], v[128:131], v[190:193], v[60:63]
	v_mfma_f32_16x16x32_bf16 v[60:63], v[132:135], v[194:197], v[60:63]
	v_mfma_f32_16x16x32_bf16 v[52:55], v[154:157], v[190:193], v[52:55]
	v_mfma_f32_16x16x32_bf16 v[52:55], v[158:161], v[194:197], v[52:55]
	v_mfma_f32_16x16x32_bf16 v[44:47], v[128:131], v[198:201], v[44:47]
	v_mfma_f32_16x16x32_bf16 v[44:47], v[132:135], v[202:205], v[44:47]
	v_mfma_f32_16x16x32_bf16 v[36:39], v[154:157], v[198:201], v[36:39]
	v_mfma_f32_16x16x32_bf16 v[36:39], v[158:161], v[202:205], v[36:39]
	v_mfma_f32_16x16x32_bf16 v[28:31], v[128:131], v[206:209], v[28:31]
	v_mfma_f32_16x16x32_bf16 v[28:31], v[132:135], v[210:213], v[28:31]
	v_mfma_f32_16x16x32_bf16 v[20:23], v[154:157], v[206:209], v[20:23]
	v_mfma_f32_16x16x32_bf16 v[20:23], v[158:161], v[210:213], v[20:23]
	v_mfma_f32_16x16x32_bf16 v[12:15], v[128:131], v[214:217], v[12:15]
	v_mfma_f32_16x16x32_bf16 v[12:15], v[132:135], v[218:221], v[12:15]
	v_mfma_f32_16x16x32_bf16 v[4:7], v[154:157], v[214:217], v[4:7]
	v_mfma_f32_16x16x32_bf16 v[4:7], v[158:161], v[218:221], v[4:7]
	v_mfma_f32_16x16x32_bf16 v[56:59], v[162:165], v[190:193], v[56:59]
	v_mfma_f32_16x16x32_bf16 v[56:59], v[166:169], v[194:197], v[56:59]
	v_mfma_f32_16x16x32_bf16 v[48:51], v[182:185], v[190:193], v[48:51]
	v_mfma_f32_16x16x32_bf16 v[48:51], v[186:189], v[194:197], v[48:51]
	v_mfma_f32_16x16x32_bf16 v[40:43], v[162:165], v[198:201], v[40:43]
	v_mfma_f32_16x16x32_bf16 v[40:43], v[166:169], v[202:205], v[40:43]
	v_mfma_f32_16x16x32_bf16 v[32:35], v[182:185], v[198:201], v[32:35]
	v_mfma_f32_16x16x32_bf16 v[32:35], v[186:189], v[202:205], v[32:35]
	v_mfma_f32_16x16x32_bf16 v[24:27], v[162:165], v[206:209], v[24:27]
	v_mfma_f32_16x16x32_bf16 v[24:27], v[166:169], v[210:213], v[24:27]
	v_mfma_f32_16x16x32_bf16 v[16:19], v[182:185], v[206:209], v[16:19]
	v_mfma_f32_16x16x32_bf16 v[16:19], v[186:189], v[210:213], v[16:19]
	v_mfma_f32_16x16x32_bf16 v[8:11], v[162:165], v[214:217], v[8:11]
	v_mfma_f32_16x16x32_bf16 v[8:11], v[166:169], v[218:221], v[8:11]
	s_setprio 3
	s_barrier
	v_mfma_f32_16x16x32_bf16 v[0:3], v[182:185], v[214:217], v[0:3]
	v_mfma_f32_16x16x32_bf16 v[0:3], v[186:189], v[218:221], v[0:3]
	s_setprio 0
.Lzj_0_1:
	s_add_i32 s67, 0, 0x18000
	s_add_i32 s73, 0, 0x1c000
	v_add_u32_e32 v158, s67, v175
	v_add_u32_e32 v186, s73, v175
	ds_read_b128 v[128:131], v158
	ds_read_b128 v[132:135], v158 offset:1024
	ds_read_b128 v[154:157], v158 offset:2048
	ds_read_b128 v[158:161], v158 offset:3072
	ds_read_b128 v[162:165], v186
	ds_read_b128 v[166:169], v186 offset:1024
	ds_read_b128 v[182:185], v186 offset:2048
	ds_read_b128 v[186:189], v186 offset:3072
	s_add_u32 s68, s92, 0x40000
	s_addc_u32 s69, s93, 0
	s_mov_b32 m0, s19
	v_lshl_add_u64 v[228:229], s[68:69], 0, v[142:143]
	ds_read_b128 v[190:193], v180 offset:32768
	ds_read_b128 v[194:197], v180 offset:33792
	ds_read_b128 v[198:201], v180 offset:34816
	ds_read_b128 v[202:205], v180 offset:35840
	ds_read_b128 v[206:209], v180 offset:36864
	ds_read_b128 v[210:213], v180 offset:37888
	ds_read_b128 v[214:217], v180 offset:38912
	ds_read_b128 v[218:221], v180 offset:39936
	global_load_lds_dwordx4 v[228:229], off
	s_mov_b32 m0, s20
	v_lshl_add_u64 v[228:229], s[68:69], 0, v[138:139]
	global_load_lds_dwordx4 v[228:229], off
	s_waitcnt vmcnt(8) lgkmcnt(0)
	s_barrier
	s_setprio 1
	v_mfma_f32_16x16x32_bf16 v[124:127], v[128:131], v[190:193], v[124:127]
	v_mfma_f32_16x16x32_bf16 v[124:127], v[132:135], v[194:197], v[124:127]
	v_mfma_f32_16x16x32_bf16 v[116:119], v[154:157], v[190:193], v[116:119]
	v_mfma_f32_16x16x32_bf16 v[116:119], v[158:161], v[194:197], v[116:119]
	v_mfma_f32_16x16x32_bf16 v[108:111], v[128:131], v[198:201], v[108:111]
	v_mfma_f32_16x16x32_bf16 v[108:111], v[132:135], v[202:205], v[108:111]
	v_mfma_f32_16x16x32_bf16 v[100:103], v[154:157], v[198:201], v[100:103]
	v_mfma_f32_16x16x32_bf16 v[100:103], v[158:161], v[202:205], v[100:103]
	v_mfma_f32_16x16x32_bf16 v[92:95], v[128:131], v[206:209], v[92:95]
	v_mfma_f32_16x16x32_bf16 v[92:95], v[132:135], v[210:213], v[92:95]
	v_mfma_f32_16x16x32_bf16 v[84:87], v[154:157], v[206:209], v[84:87]
	v_mfma_f32_16x16x32_bf16 v[84:87], v[158:161], v[210:213], v[84:87]
	v_mfma_f32_16x16x32_bf16 v[76:79], v[128:131], v[214:217], v[76:79]
	v_mfma_f32_16x16x32_bf16 v[76:79], v[132:135], v[218:221], v[76:79]
	v_mfma_f32_16x16x32_bf16 v[68:71], v[154:157], v[214:217], v[68:71]
	v_mfma_f32_16x16x32_bf16 v[68:71], v[158:161], v[218:221], v[68:71]
	v_mfma_f32_16x16x32_bf16 v[120:123], v[162:165], v[190:193], v[120:123]
	v_mfma_f32_16x16x32_bf16 v[120:123], v[166:169], v[194:197], v[120:123]
	v_mfma_f32_16x16x32_bf16 v[112:115], v[182:185], v[190:193], v[112:115]
	v_mfma_f32_16x16x32_bf16 v[112:115], v[186:189], v[194:197], v[112:115]
	v_mfma_f32_16x16x32_bf16 v[104:107], v[162:165], v[198:201], v[104:107]
	v_mfma_f32_16x16x32_bf16 v[104:107], v[166:169], v[202:205], v[104:107]
	v_mfma_f32_16x16x32_bf16 v[96:99], v[182:185], v[198:201], v[96:99]
	v_mfma_f32_16x16x32_bf16 v[96:99], v[186:189], v[202:205], v[96:99]
	v_mfma_f32_16x16x32_bf16 v[88:91], v[162:165], v[206:209], v[88:91]
	v_mfma_f32_16x16x32_bf16 v[88:91], v[166:169], v[210:213], v[88:91]
	v_mfma_f32_16x16x32_bf16 v[80:83], v[182:185], v[206:209], v[80:83]
	v_mfma_f32_16x16x32_bf16 v[80:83], v[186:189], v[210:213], v[80:83]
	v_mfma_f32_16x16x32_bf16 v[72:75], v[162:165], v[214:217], v[72:75]
	v_mfma_f32_16x16x32_bf16 v[72:75], v[166:169], v[218:221], v[72:75]
	s_setprio 3
	s_barrier
	v_mfma_f32_16x16x32_bf16 v[64:67], v[182:185], v[214:217], v[64:67]
	v_mfma_f32_16x16x32_bf16 v[64:67], v[186:189], v[218:221], v[64:67]
	s_setprio 0
	s_add_i32 s67, s67, s16
	v_lshl_add_u64 v[170:171], v[170:171], 0, s[74:75]
	s_mov_b32 m0, s67
	ds_read_b128 v[190:193], v180 offset:49152
	ds_read_b128 v[194:197], v180 offset:50176
	ds_read_b128 v[198:201], v180 offset:51200
	ds_read_b128 v[202:205], v180 offset:52224
	ds_read_b128 v[206:209], v180 offset:53248
	ds_read_b128 v[210:213], v180 offset:54272
	ds_read_b128 v[214:217], v180 offset:55296
	ds_read_b128 v[218:221], v180 offset:56320
	global_load_lds_dwordx4 v[170:171], off
	s_add_i32 m0, s67, 0x2000
	s_add_u32 s68, s90, 0x40080
	v_lshl_add_u64 v[170:171], v[222:223], 0, s[74:75]
	s_addc_u32 s69, s91, 0
	s_add_i32 s67, s73, s16
	global_load_lds_dwordx4 v[170:171], off
	s_mov_b32 m0, s67
	v_lshl_add_u64 v[170:171], s[68:69], 0, v[140:141]
	global_load_lds_dwordx4 v[170:171], off
	s_add_i32 m0, s67, 0x2000
	v_lshl_add_u64 v[170:171], s[68:69], 0, v[136:137]
	global_load_lds_dwordx4 v[170:171], off
	s_mov_b32 m0, s23
	v_lshl_add_u64 v[170:171], v[224:225], 0, s[74:75]
	global_load_lds_dwordx4 v[170:171], off
	s_mov_b32 m0, s24
	v_lshl_add_u64 v[170:171], v[226:227], 0, s[74:75]
	global_load_lds_dwordx4 v[170:171], off
	s_waitcnt vmcnt(8) lgkmcnt(0)
	s_barrier
	s_setprio 1
	v_mfma_f32_16x16x32_bf16 v[60:63], v[128:131], v[190:193], v[60:63]
	v_mfma_f32_16x16x32_bf16 v[60:63], v[132:135], v[194:197], v[60:63]
	v_mfma_f32_16x16x32_bf16 v[52:55], v[154:157], v[190:193], v[52:55]
	v_mfma_f32_16x16x32_bf16 v[52:55], v[158:161], v[194:197], v[52:55]
	v_mfma_f32_16x16x32_bf16 v[44:47], v[128:131], v[198:201], v[44:47]
	v_mfma_f32_16x16x32_bf16 v[44:47], v[132:135], v[202:205], v[44:47]
	v_mfma_f32_16x16x32_bf16 v[36:39], v[154:157], v[198:201], v[36:39]
	v_mfma_f32_16x16x32_bf16 v[36:39], v[158:161], v[202:205], v[36:39]
	v_mfma_f32_16x16x32_bf16 v[28:31], v[128:131], v[206:209], v[28:31]
	v_mfma_f32_16x16x32_bf16 v[28:31], v[132:135], v[210:213], v[28:31]
	v_mfma_f32_16x16x32_bf16 v[20:23], v[154:157], v[206:209], v[20:23]
	v_mfma_f32_16x16x32_bf16 v[20:23], v[158:161], v[210:213], v[20:23]
	v_mfma_f32_16x16x32_bf16 v[12:15], v[128:131], v[214:217], v[12:15]
	v_mfma_f32_16x16x32_bf16 v[12:15], v[132:135], v[218:221], v[12:15]
	v_mfma_f32_16x16x32_bf16 v[4:7], v[154:157], v[214:217], v[4:7]
	v_mfma_f32_16x16x32_bf16 v[4:7], v[158:161], v[218:221], v[4:7]
	v_mfma_f32_16x16x32_bf16 v[56:59], v[162:165], v[190:193], v[56:59]
	v_mfma_f32_16x16x32_bf16 v[56:59], v[166:169], v[194:197], v[56:59]
	v_mfma_f32_16x16x32_bf16 v[48:51], v[182:185], v[190:193], v[48:51]
	v_mfma_f32_16x16x32_bf16 v[48:51], v[186:189], v[194:197], v[48:51]
	v_mfma_f32_16x16x32_bf16 v[40:43], v[162:165], v[198:201], v[40:43]
	v_mfma_f32_16x16x32_bf16 v[40:43], v[166:169], v[202:205], v[40:43]
	v_mfma_f32_16x16x32_bf16 v[32:35], v[182:185], v[198:201], v[32:35]
	v_mfma_f32_16x16x32_bf16 v[32:35], v[186:189], v[202:205], v[32:35]
	v_mfma_f32_16x16x32_bf16 v[24:27], v[162:165], v[206:209], v[24:27]
	v_mfma_f32_16x16x32_bf16 v[24:27], v[166:169], v[210:213], v[24:27]
	v_mfma_f32_16x16x32_bf16 v[16:19], v[182:185], v[206:209], v[16:19]
	v_mfma_f32_16x16x32_bf16 v[16:19], v[186:189], v[210:213], v[16:19]
	v_mfma_f32_16x16x32_bf16 v[8:11], v[162:165], v[214:217], v[8:11]
	v_mfma_f32_16x16x32_bf16 v[8:11], v[166:169], v[218:221], v[8:11]
	s_setprio 3
	s_barrier
	v_mfma_f32_16x16x32_bf16 v[0:3], v[182:185], v[214:217], v[0:3]
	v_mfma_f32_16x16x32_bf16 v[0:3], v[186:189], v[218:221], v[0:3]
	s_setprio 0
	s_add_i32 s66, s66, 2
	s_add_u32 s88, s88, 0x100
	s_addc_u32 s89, s89, 0
	s_add_u32 s58, s58, 0x100
	s_addc_u32 s59, s59, 0
	s_cmp_gt_u32 s66, 13
	s_cbranch_scc0 .LBB0_120
	s_branch .Lzskip_0

.LBB0_272:
	ds_read_b128 v[120:123], v245
	ds_read_b128 v[124:127], v245 offset:1024
	ds_read_b128 v[128:131], v245 offset:2048
	ds_read_b128 v[132:135], v245 offset:3072
	ds_read_b128 v[144:147], v246
	ds_read_b128 v[148:151], v246 offset:1024
	ds_read_b128 v[152:155], v246 offset:2048
	ds_read_b128 v[156:159], v246 offset:3072
	s_add_u32 s59, s86, 0xfff50080
	s_addc_u32 s66, s87, -1
	s_cmp_eq_u32 s58, 40
	s_cselect_b32 s91, s11, s66
	s_cselect_b32 s90, s10, s59
	s_cselect_b32 s89, s85, s57
	s_cselect_b32 s88, s84, s56
	v_lshl_add_u64 v[204:205], s[86:87], 0, v[200:201]
	s_add_i32 m0, s16, 0xc000
	ds_read_b128 v[160:163], v247
	ds_read_b128 v[164:167], v247 offset:1024
	ds_read_b128 v[168:171], v247 offset:2048
	ds_read_b128 v[172:175], v247 offset:3072
	ds_read_b128 v[176:179], v247 offset:4096
	ds_read_b128 v[180:183], v247 offset:5120
	ds_read_b128 v[184:187], v247 offset:6144
	ds_read_b128 v[188:191], v247 offset:7168
	global_load_lds_dwordx4 v[204:205], off
	s_add_i32 m0, s16, 0xe000
	v_lshl_add_u64 v[204:205], s[86:87], 0, v[202:203]
	global_load_lds_dwordx4 v[204:205], off
	s_cmp_eq_u32 s58, -2
	s_waitcnt vmcnt(8) lgkmcnt(0)
	s_barrier
	s_setprio 1
	s_cbranch_scc1 .Lzv_1_0
	v_mfma_f32_16x16x32_bf16 v[140:143], v[120:123], v[160:163], v[140:143]
	v_mfma_f32_16x16x32_bf16 v[140:143], v[124:127], v[164:167], v[140:143]
	v_mfma_f32_16x16x32_bf16 v[136:139], v[128:131], v[160:163], v[136:139]
	v_mfma_f32_16x16x32_bf16 v[136:139], v[132:135], v[164:167], v[136:139]
	v_mfma_f32_16x16x32_bf16 v[108:111], v[120:123], v[168:171], v[108:111]
	v_mfma_f32_16x16x32_bf16 v[108:111], v[124:127], v[172:175], v[108:111]
	v_mfma_f32_16x16x32_bf16 v[104:107], v[128:131], v[168:171], v[104:107]
	v_mfma_f32_16x16x32_bf16 v[104:107], v[132:135], v[172:175], v[104:107]
	v_mfma_f32_16x16x32_bf16 v[92:95], v[120:123], v[176:179], v[92:95]
	v_mfma_f32_16x16x32_bf16 v[92:95], v[124:127], v[180:183], v[92:95]
	v_mfma_f32_16x16x32_bf16 v[88:91], v[128:131], v[176:179], v[88:91]
	v_mfma_f32_16x16x32_bf16 v[88:91], v[132:135], v[180:183], v[88:91]
	v_mfma_f32_16x16x32_bf16 v[76:79], v[120:123], v[184:187], v[76:79]
	v_mfma_f32_16x16x32_bf16 v[76:79], v[124:127], v[188:191], v[76:79]
	v_mfma_f32_16x16x32_bf16 v[72:75], v[128:131], v[184:187], v[72:75]
	v_mfma_f32_16x16x32_bf16 v[72:75], v[132:135], v[188:191], v[72:75]
	v_mfma_f32_16x16x32_bf16 v[116:119], v[144:147], v[160:163], v[116:119]
	v_mfma_f32_16x16x32_bf16 v[116:119], v[148:151], v[164:167], v[116:119]
	v_mfma_f32_16x16x32_bf16 v[112:115], v[152:155], v[160:163], v[112:115]
	v_mfma_f32_16x16x32_bf16 v[112:115], v[156:159], v[164:167], v[112:115]
	v_mfma_f32_16x16x32_bf16 v[100:103], v[144:147], v[168:171], v[100:103]
	v_mfma_f32_16x16x32_bf16 v[100:103], v[148:151], v[172:175], v[100:103]
	v_mfma_f32_16x16x32_bf16 v[96:99], v[152:155], v[168:171], v[96:99]
	v_mfma_f32_16x16x32_bf16 v[96:99], v[156:159], v[172:175], v[96:99]
	v_mfma_f32_16x16x32_bf16 v[84:87], v[144:147], v[176:179], v[84:87]
	v_mfma_f32_16x16x32_bf16 v[84:87], v[148:151], v[180:183], v[84:87]
	v_mfma_f32_16x16x32_bf16 v[80:83], v[152:155], v[176:179], v[80:83]
	v_mfma_f32_16x16x32_bf16 v[80:83], v[156:159], v[180:183], v[80:83]
	v_mfma_f32_16x16x32_bf16 v[68:71], v[144:147], v[184:187], v[68:71]
	v_mfma_f32_16x16x32_bf16 v[68:71], v[148:151], v[188:191], v[68:71]
	s_setprio 3
	s_barrier
	v_mfma_f32_16x16x32_bf16 v[64:67], v[152:155], v[184:187], v[64:67]
	v_mfma_f32_16x16x32_bf16 v[64:67], v[156:159], v[188:191], v[64:67]
	s_setprio 0
.Lzj_1_0:
	s_add_i32 s59, s26, s15
	v_lshl_add_u64 v[204:205], s[88:89], 0, v[194:195]
	s_mov_b32 m0, s59
	ds_read_b128 v[160:163], v247 offset:16384
	ds_read_b128 v[164:167], v247 offset:17408
	ds_read_b128 v[168:171], v247 offset:18432
	ds_read_b128 v[172:175], v247 offset:19456
	ds_read_b128 v[176:179], v247 offset:20480
	ds_read_b128 v[180:183], v247 offset:21504
	ds_read_b128 v[184:187], v247 offset:22528
	ds_read_b128 v[188:191], v247 offset:23552
	global_load_lds_dwordx4 v[204:205], off
	s_add_i32 m0, s59, 0x2000
	s_add_u32 s66, s88, 0xb0000
	v_lshl_add_u64 v[206:207], s[88:89], 0, v[198:199]
	s_addc_u32 s67, s89, 0
	s_add_i32 s59, s27, s15
	global_load_lds_dwordx4 v[206:207], off
	v_lshl_add_u64 v[208:209], s[66:67], 0, v[194:195]
	s_mov_b32 m0, s59
	global_load_lds_dwordx4 v[208:209], off
	s_add_i32 m0, s59, 0x2000
	v_lshl_add_u64 v[208:209], s[66:67], 0, v[198:199]
	global_load_lds_dwordx4 v[208:209], off
	s_mov_b32 m0, s16
	v_lshl_add_u64 v[208:209], s[90:91], 0, v[192:193]
	global_load_lds_dwordx4 v[208:209], off
	s_mov_b32 m0, s17
	v_lshl_add_u64 v[210:211], s[90:91], 0, v[196:197]
	global_load_lds_dwordx4 v[210:211], off
	s_cmp_eq_u32 s58, -2
	s_waitcnt vmcnt(8) lgkmcnt(0)
	s_barrier
	s_setprio 1
	s_cbranch_scc1 .Lzv_1_1
	v_mfma_f32_16x16x32_bf16 v[60:63], v[120:123], v[160:163], v[60:63]
	v_mfma_f32_16x16x32_bf16 v[60:63], v[124:127], v[164:167], v[60:63]
	v_mfma_f32_16x16x32_bf16 v[56:59], v[128:131], v[160:163], v[56:59]
	v_mfma_f32_16x16x32_bf16 v[56:59], v[132:135], v[164:167], v[56:59]
	v_mfma_f32_16x16x32_bf16 v[44:47], v[120:123], v[168:171], v[44:47]
	v_mfma_f32_16x16x32_bf16 v[44:47], v[124:127], v[172:175], v[44:47]
	v_mfma_f32_16x16x32_bf16 v[40:43], v[128:131], v[168:171], v[40:43]
	v_mfma_f32_16x16x32_bf16 v[40:43], v[132:135], v[172:175], v[40:43]
	v_mfma_f32_16x16x32_bf16 v[28:31], v[120:123], v[176:179], v[28:31]
	v_mfma_f32_16x16x32_bf16 v[28:31], v[124:127], v[180:183], v[28:31]
	v_mfma_f32_16x16x32_bf16 v[24:27], v[128:131], v[176:179], v[24:27]
	v_mfma_f32_16x16x32_bf16 v[24:27], v[132:135], v[180:183], v[24:27]
	v_mfma_f32_16x16x32_bf16 v[12:15], v[120:123], v[184:187], v[12:15]
	v_mfma_f32_16x16x32_bf16 v[12:15], v[124:127], v[188:191], v[12:15]
	v_mfma_f32_16x16x32_bf16 v[8:11], v[128:131], v[184:187], v[8:11]
	v_mfma_f32_16x16x32_bf16 v[8:11], v[132:135], v[188:191], v[8:11]
	v_mfma_f32_16x16x32_bf16 v[52:55], v[144:147], v[160:163], v[52:55]
	v_mfma_f32_16x16x32_bf16 v[52:55], v[148:151], v[164:167], v[52:55]
	v_mfma_f32_16x16x32_bf16 v[48:51], v[152:155], v[160:163], v[48:51]
	v_mfma_f32_16x16x32_bf16 v[48:51], v[156:159], v[164:167], v[48:51]
	v_mfma_f32_16x16x32_bf16 v[36:39], v[144:147], v[168:171], v[36:39]
	v_mfma_f32_16x16x32_bf16 v[36:39], v[148:151], v[172:175], v[36:39]
	v_mfma_f32_16x16x32_bf16 v[32:35], v[152:155], v[168:171], v[32:35]
	v_mfma_f32_16x16x32_bf16 v[32:35], v[156:159], v[172:175], v[32:35]
	v_mfma_f32_16x16x32_bf16 v[20:23], v[144:147], v[176:179], v[20:23]
	v_mfma_f32_16x16x32_bf16 v[20:23], v[148:151], v[180:183], v[20:23]
	v_mfma_f32_16x16x32_bf16 v[16:19], v[152:155], v[176:179], v[16:19]
	v_mfma_f32_16x16x32_bf16 v[16:19], v[156:159], v[180:183], v[16:19]
	v_mfma_f32_16x16x32_bf16 v[4:7], v[144:147], v[184:187], v[4:7]
	v_mfma_f32_16x16x32_bf16 v[4:7], v[148:151], v[188:191], v[4:7]
	s_setprio 3
	s_barrier
	v_mfma_f32_16x16x32_bf16 v[0:3], v[152:155], v[184:187], v[0:3]
	v_mfma_f32_16x16x32_bf16 v[0:3], v[156:159], v[188:191], v[0:3]
	s_setprio 0
.Lzj_1_1:
	s_add_i32 s59, 0, 0x18000
	s_add_i32 s68, 0, 0x1c000
	v_add_u32_e32 v132, s59, v243
	v_add_u32_e32 v156, s68, v243
	ds_read_b128 v[120:123], v132
	ds_read_b128 v[124:127], v132 offset:1024
	ds_read_b128 v[128:131], v132 offset:2048
	ds_read_b128 v[132:135], v132 offset:3072
	ds_read_b128 v[144:147], v156
	ds_read_b128 v[148:151], v156 offset:1024
	ds_read_b128 v[152:155], v156 offset:2048
	ds_read_b128 v[156:159], v156 offset:3072
	s_add_u32 s66, s90, 0xb0000
	s_addc_u32 s67, s91, 0
	s_mov_b32 m0, s18
	v_lshl_add_u64 v[212:213], s[66:67], 0, v[192:193]
	ds_read_b128 v[160:163], v247 offset:32768
	ds_read_b128 v[164:167], v247 offset:33792
	ds_read_b128 v[168:171], v247 offset:34816
	ds_read_b128 v[172:175], v247 offset:35840
	ds_read_b128 v[176:179], v247 offset:36864
	ds_read_b128 v[180:183], v247 offset:37888
	ds_read_b128 v[184:187], v247 offset:38912
	ds_read_b128 v[188:191], v247 offset:39936
	global_load_lds_dwordx4 v[212:213], off
	s_mov_b32 m0, s19
	v_lshl_add_u64 v[212:213], s[66:67], 0, v[196:197]
	global_load_lds_dwordx4 v[212:213], off
	s_waitcnt vmcnt(8) lgkmcnt(0)
	s_barrier
	s_setprio 1
	v_mfma_f32_16x16x32_bf16 v[140:143], v[120:123], v[160:163], v[140:143]
	v_mfma_f32_16x16x32_bf16 v[140:143], v[124:127], v[164:167], v[140:143]
	v_mfma_f32_16x16x32_bf16 v[136:139], v[128:131], v[160:163], v[136:139]
	v_mfma_f32_16x16x32_bf16 v[136:139], v[132:135], v[164:167], v[136:139]
	v_mfma_f32_16x16x32_bf16 v[108:111], v[120:123], v[168:171], v[108:111]
	v_mfma_f32_16x16x32_bf16 v[108:111], v[124:127], v[172:175], v[108:111]
	v_mfma_f32_16x16x32_bf16 v[104:107], v[128:131], v[168:171], v[104:107]
	v_mfma_f32_16x16x32_bf16 v[104:107], v[132:135], v[172:175], v[104:107]
	v_mfma_f32_16x16x32_bf16 v[92:95], v[120:123], v[176:179], v[92:95]
	v_mfma_f32_16x16x32_bf16 v[92:95], v[124:127], v[180:183], v[92:95]
	v_mfma_f32_16x16x32_bf16 v[88:91], v[128:131], v[176:179], v[88:91]
	v_mfma_f32_16x16x32_bf16 v[88:91], v[132:135], v[180:183], v[88:91]
	v_mfma_f32_16x16x32_bf16 v[76:79], v[120:123], v[184:187], v[76:79]
	v_mfma_f32_16x16x32_bf16 v[76:79], v[124:127], v[188:191], v[76:79]
	v_mfma_f32_16x16x32_bf16 v[72:75], v[128:131], v[184:187], v[72:75]
	v_mfma_f32_16x16x32_bf16 v[72:75], v[132:135], v[188:191], v[72:75]
	v_mfma_f32_16x16x32_bf16 v[116:119], v[144:147], v[160:163], v[116:119]
	v_mfma_f32_16x16x32_bf16 v[116:119], v[148:151], v[164:167], v[116:119]
	v_mfma_f32_16x16x32_bf16 v[112:115], v[152:155], v[160:163], v[112:115]
	v_mfma_f32_16x16x32_bf16 v[112:115], v[156:159], v[164:167], v[112:115]
	v_mfma_f32_16x16x32_bf16 v[100:103], v[144:147], v[168:171], v[100:103]
	v_mfma_f32_16x16x32_bf16 v[100:103], v[148:151], v[172:175], v[100:103]
	v_mfma_f32_16x16x32_bf16 v[96:99], v[152:155], v[168:171], v[96:99]
	v_mfma_f32_16x16x32_bf16 v[96:99], v[156:159], v[172:175], v[96:99]
	v_mfma_f32_16x16x32_bf16 v[84:87], v[144:147], v[176:179], v[84:87]
	v_mfma_f32_16x16x32_bf16 v[84:87], v[148:151], v[180:183], v[84:87]
	v_mfma_f32_16x16x32_bf16 v[80:83], v[152:155], v[176:179], v[80:83]
	v_mfma_f32_16x16x32_bf16 v[80:83], v[156:159], v[180:183], v[80:83]
	v_mfma_f32_16x16x32_bf16 v[68:71], v[144:147], v[184:187], v[68:71]
	v_mfma_f32_16x16x32_bf16 v[68:71], v[148:151], v[188:191], v[68:71]
	s_setprio 3
	s_barrier
	v_mfma_f32_16x16x32_bf16 v[64:67], v[152:155], v[184:187], v[64:67]
	v_mfma_f32_16x16x32_bf16 v[64:67], v[156:159], v[188:191], v[64:67]
	s_setprio 0
	s_add_i32 s59, s59, s15
	v_lshl_add_u64 v[204:205], v[204:205], 0, s[80:81]
	s_mov_b32 m0, s59
	ds_read_b128 v[160:163], v247 offset:49152
	ds_read_b128 v[164:167], v247 offset:50176
	ds_read_b128 v[168:171], v247 offset:51200
	ds_read_b128 v[172:175], v247 offset:52224
	ds_read_b128 v[176:179], v247 offset:53248
	ds_read_b128 v[180:183], v247 offset:54272
	ds_read_b128 v[184:187], v247 offset:55296
	ds_read_b128 v[188:191], v247 offset:56320
	global_load_lds_dwordx4 v[204:205], off
	s_add_i32 m0, s59, 0x2000
	s_add_u32 s66, s88, 0xb0080
	v_lshl_add_u64 v[204:205], v[206:207], 0, s[80:81]
	s_addc_u32 s67, s89, 0
	s_add_i32 s59, s68, s15
	global_load_lds_dwordx4 v[204:205], off
	s_mov_b32 m0, s59
	v_lshl_add_u64 v[204:205], s[66:67], 0, v[194:195]
	global_load_lds_dwordx4 v[204:205], off
	s_add_i32 m0, s59, 0x2000
	v_lshl_add_u64 v[204:205], s[66:67], 0, v[198:199]
	global_load_lds_dwordx4 v[204:205], off
	s_mov_b32 m0, s21
	v_lshl_add_u64 v[204:205], v[208:209], 0, s[80:81]
	global_load_lds_dwordx4 v[204:205], off
	s_mov_b32 m0, s22
	v_lshl_add_u64 v[204:205], v[210:211], 0, s[80:81]
	global_load_lds_dwordx4 v[204:205], off
	s_waitcnt vmcnt(8) lgkmcnt(0)
	s_barrier
	s_setprio 1
	v_mfma_f32_16x16x32_bf16 v[60:63], v[120:123], v[160:163], v[60:63]
	v_mfma_f32_16x16x32_bf16 v[60:63], v[124:127], v[164:167], v[60:63]
	v_mfma_f32_16x16x32_bf16 v[56:59], v[128:131], v[160:163], v[56:59]
	v_mfma_f32_16x16x32_bf16 v[56:59], v[132:135], v[164:167], v[56:59]
	v_mfma_f32_16x16x32_bf16 v[44:47], v[120:123], v[168:171], v[44:47]
	v_mfma_f32_16x16x32_bf16 v[44:47], v[124:127], v[172:175], v[44:47]
	v_mfma_f32_16x16x32_bf16 v[40:43], v[128:131], v[168:171], v[40:43]
	v_mfma_f32_16x16x32_bf16 v[40:43], v[132:135], v[172:175], v[40:43]
	v_mfma_f32_16x16x32_bf16 v[28:31], v[120:123], v[176:179], v[28:31]
	v_mfma_f32_16x16x32_bf16 v[28:31], v[124:127], v[180:183], v[28:31]
	v_mfma_f32_16x16x32_bf16 v[24:27], v[128:131], v[176:179], v[24:27]
	v_mfma_f32_16x16x32_bf16 v[24:27], v[132:135], v[180:183], v[24:27]
	v_mfma_f32_16x16x32_bf16 v[12:15], v[120:123], v[184:187], v[12:15]
	v_mfma_f32_16x16x32_bf16 v[12:15], v[124:127], v[188:191], v[12:15]
	v_mfma_f32_16x16x32_bf16 v[8:11], v[128:131], v[184:187], v[8:11]
	v_mfma_f32_16x16x32_bf16 v[8:11], v[132:135], v[188:191], v[8:11]
	v_mfma_f32_16x16x32_bf16 v[52:55], v[144:147], v[160:163], v[52:55]
	v_mfma_f32_16x16x32_bf16 v[52:55], v[148:151], v[164:167], v[52:55]
	v_mfma_f32_16x16x32_bf16 v[48:51], v[152:155], v[160:163], v[48:51]
	v_mfma_f32_16x16x32_bf16 v[48:51], v[156:159], v[164:167], v[48:51]
	v_mfma_f32_16x16x32_bf16 v[36:39], v[144:147], v[168:171], v[36:39]
	v_mfma_f32_16x16x32_bf16 v[36:39], v[148:151], v[172:175], v[36:39]
	v_mfma_f32_16x16x32_bf16 v[32:35], v[152:155], v[168:171], v[32:35]
	v_mfma_f32_16x16x32_bf16 v[32:35], v[156:159], v[172:175], v[32:35]
	v_mfma_f32_16x16x32_bf16 v[20:23], v[144:147], v[176:179], v[20:23]
	v_mfma_f32_16x16x32_bf16 v[20:23], v[148:151], v[180:183], v[20:23]
	v_mfma_f32_16x16x32_bf16 v[16:19], v[152:155], v[176:179], v[16:19]
	v_mfma_f32_16x16x32_bf16 v[16:19], v[156:159], v[180:183], v[16:19]
	v_mfma_f32_16x16x32_bf16 v[4:7], v[144:147], v[184:187], v[4:7]
	v_mfma_f32_16x16x32_bf16 v[4:7], v[148:151], v[188:191], v[4:7]
	s_setprio 3
	s_barrier
	v_mfma_f32_16x16x32_bf16 v[0:3], v[152:155], v[184:187], v[0:3]
	v_mfma_f32_16x16x32_bf16 v[0:3], v[156:159], v[188:191], v[0:3]
	s_setprio 0
	s_add_i32 s58, s58, 2
	s_add_u32 s86, s86, 0x100
	s_addc_u32 s87, s87, 0
	s_add_u32 s56, s56, 0x100
	s_addc_u32 s57, s57, 0
	s_cmp_gt_u32 s58, 41
	s_cbranch_scc0 .LBB0_272
	s_branch .Lzskip_1

.LBB0_429:
	ds_read_b128 v[128:131], v203
	ds_read_b128 v[132:135], v203 offset:1024
	ds_read_b128 v[136:139], v203 offset:2048
	ds_read_b128 v[164:167], v203 offset:3072
	ds_read_b128 v[168:171], v204
	ds_read_b128 v[172:175], v204 offset:1024
	ds_read_b128 v[176:179], v204 offset:2048
	ds_read_b128 v[180:183], v204 offset:3072
	s_add_u32 s6, s88, 0xfffc0080
	s_addc_u32 s7, s89, -1
	s_cmp_eq_u32 s21, 12
	s_cselect_b32 vcc_hi, s15, s7
	s_cselect_b32 vcc_lo, s16, s6
	s_cselect_b32 s7, s17, s20
	s_cselect_b32 s6, s18, s19
	v_lshl_add_u64 v[196:197], s[88:89], 0, v[156:157]
	s_add_i32 m0, s58, 0xc000
	ds_read_b128 v[184:187], v205
	ds_read_b128 v[188:191], v205 offset:1024
	ds_read_b128 v[192:195], v205 offset:2048
	ds_read_b128 v[212:215], v205 offset:3072
	ds_read_b128 v[216:219], v205 offset:4096
	ds_read_b128 v[220:223], v205 offset:5120
	ds_read_b128 v[224:227], v205 offset:6144
	ds_read_b128 v[228:231], v205 offset:7168
	global_load_lds_dwordx4 v[196:197], off
	s_add_i32 m0, s58, 0xe000
	v_lshl_add_u64 v[196:197], s[88:89], 0, v[158:159]
	global_load_lds_dwordx4 v[196:197], off
	s_cmp_eq_u32 s21, -2
	s_waitcnt vmcnt(8) lgkmcnt(0)
	s_barrier
	s_setprio 1
	s_cbranch_scc1 .Lzv_2_0
	v_mfma_f32_16x16x32_bf16 v[124:127], v[128:131], v[184:187], v[124:127]
	v_mfma_f32_16x16x32_bf16 v[124:127], v[132:135], v[188:191], v[124:127]
	v_mfma_f32_16x16x32_bf16 v[116:119], v[136:139], v[184:187], v[116:119]
	v_mfma_f32_16x16x32_bf16 v[116:119], v[164:167], v[188:191], v[116:119]
	v_mfma_f32_16x16x32_bf16 v[108:111], v[128:131], v[192:195], v[108:111]
	v_mfma_f32_16x16x32_bf16 v[108:111], v[132:135], v[212:215], v[108:111]
	v_mfma_f32_16x16x32_bf16 v[100:103], v[136:139], v[192:195], v[100:103]
	v_mfma_f32_16x16x32_bf16 v[100:103], v[164:167], v[212:215], v[100:103]
	v_mfma_f32_16x16x32_bf16 v[92:95], v[128:131], v[216:219], v[92:95]
	v_mfma_f32_16x16x32_bf16 v[92:95], v[132:135], v[220:223], v[92:95]
	v_mfma_f32_16x16x32_bf16 v[84:87], v[136:139], v[216:219], v[84:87]
	v_mfma_f32_16x16x32_bf16 v[84:87], v[164:167], v[220:223], v[84:87]
	v_mfma_f32_16x16x32_bf16 v[76:79], v[128:131], v[224:227], v[76:79]
	v_mfma_f32_16x16x32_bf16 v[76:79], v[132:135], v[228:231], v[76:79]
	v_mfma_f32_16x16x32_bf16 v[68:71], v[136:139], v[224:227], v[68:71]
	v_mfma_f32_16x16x32_bf16 v[68:71], v[164:167], v[228:231], v[68:71]
	v_mfma_f32_16x16x32_bf16 v[120:123], v[168:171], v[184:187], v[120:123]
	v_mfma_f32_16x16x32_bf16 v[120:123], v[172:175], v[188:191], v[120:123]
	v_mfma_f32_16x16x32_bf16 v[112:115], v[176:179], v[184:187], v[112:115]
	v_mfma_f32_16x16x32_bf16 v[112:115], v[180:183], v[188:191], v[112:115]
	v_mfma_f32_16x16x32_bf16 v[104:107], v[168:171], v[192:195], v[104:107]
	v_mfma_f32_16x16x32_bf16 v[104:107], v[172:175], v[212:215], v[104:107]
	v_mfma_f32_16x16x32_bf16 v[96:99], v[176:179], v[192:195], v[96:99]
	v_mfma_f32_16x16x32_bf16 v[96:99], v[180:183], v[212:215], v[96:99]
	v_mfma_f32_16x16x32_bf16 v[88:91], v[168:171], v[216:219], v[88:91]
	v_mfma_f32_16x16x32_bf16 v[88:91], v[172:175], v[220:223], v[88:91]
	v_mfma_f32_16x16x32_bf16 v[80:83], v[176:179], v[216:219], v[80:83]
	v_mfma_f32_16x16x32_bf16 v[80:83], v[180:183], v[220:223], v[80:83]
	v_mfma_f32_16x16x32_bf16 v[72:75], v[168:171], v[224:227], v[72:75]
	v_mfma_f32_16x16x32_bf16 v[72:75], v[172:175], v[228:231], v[72:75]
	s_setprio 3
	s_barrier
	v_mfma_f32_16x16x32_bf16 v[64:67], v[176:179], v[224:227], v[64:67]
	v_mfma_f32_16x16x32_bf16 v[64:67], v[180:183], v[228:231], v[64:67]
	s_setprio 0
.Lzj_2_0:
	s_add_i32 s22, s76, s57
	v_lshl_add_u64 v[196:197], s[6:7], 0, v[142:143]
	s_mov_b32 m0, s22
	ds_read_b128 v[184:187], v205 offset:16384
	ds_read_b128 v[188:191], v205 offset:17408
	ds_read_b128 v[192:195], v205 offset:18432
	ds_read_b128 v[212:215], v205 offset:19456
	ds_read_b128 v[216:219], v205 offset:20480
	ds_read_b128 v[220:223], v205 offset:21504
	ds_read_b128 v[224:227], v205 offset:22528
	ds_read_b128 v[228:231], v205 offset:23552
	global_load_lds_dwordx4 v[196:197], off
	s_add_i32 m0, s22, 0x2000
	s_add_u32 s22, s6, 0x40000
	v_lshl_add_u64 v[232:233], s[6:7], 0, v[146:147]
	s_addc_u32 s23, s7, 0
	s_add_i32 s24, s77, s57
	global_load_lds_dwordx4 v[232:233], off
	v_lshl_add_u64 v[234:235], s[22:23], 0, v[142:143]
	s_mov_b32 m0, s24
	global_load_lds_dwordx4 v[234:235], off
	s_add_i32 m0, s24, 0x2000
	v_lshl_add_u64 v[234:235], s[22:23], 0, v[146:147]
	global_load_lds_dwordx4 v[234:235], off
	s_mov_b32 m0, s58
	v_lshl_add_u64 v[234:235], vcc, 0, v[140:141]
	global_load_lds_dwordx4 v[234:235], off
	s_mov_b32 m0, s59
	v_lshl_add_u64 v[236:237], vcc, 0, v[144:145]
	global_load_lds_dwordx4 v[236:237], off
	s_cmp_eq_u32 s21, -2
	s_waitcnt vmcnt(8) lgkmcnt(0)
	s_barrier
	s_setprio 1
	s_cbranch_scc1 .Lzv_2_1
	v_mfma_f32_16x16x32_bf16 v[60:63], v[128:131], v[184:187], v[60:63]
	v_mfma_f32_16x16x32_bf16 v[60:63], v[132:135], v[188:191], v[60:63]
	v_mfma_f32_16x16x32_bf16 v[52:55], v[136:139], v[184:187], v[52:55]
	v_mfma_f32_16x16x32_bf16 v[52:55], v[164:167], v[188:191], v[52:55]
	v_mfma_f32_16x16x32_bf16 v[44:47], v[128:131], v[192:195], v[44:47]
	v_mfma_f32_16x16x32_bf16 v[44:47], v[132:135], v[212:215], v[44:47]
	v_mfma_f32_16x16x32_bf16 v[36:39], v[136:139], v[192:195], v[36:39]
	v_mfma_f32_16x16x32_bf16 v[36:39], v[164:167], v[212:215], v[36:39]
	v_mfma_f32_16x16x32_bf16 v[28:31], v[128:131], v[216:219], v[28:31]
	v_mfma_f32_16x16x32_bf16 v[28:31], v[132:135], v[220:223], v[28:31]
	v_mfma_f32_16x16x32_bf16 v[20:23], v[136:139], v[216:219], v[20:23]
	v_mfma_f32_16x16x32_bf16 v[20:23], v[164:167], v[220:223], v[20:23]
	v_mfma_f32_16x16x32_bf16 v[12:15], v[128:131], v[224:227], v[12:15]
	v_mfma_f32_16x16x32_bf16 v[12:15], v[132:135], v[228:231], v[12:15]
	v_mfma_f32_16x16x32_bf16 v[4:7], v[136:139], v[224:227], v[4:7]
	v_mfma_f32_16x16x32_bf16 v[4:7], v[164:167], v[228:231], v[4:7]
	v_mfma_f32_16x16x32_bf16 v[56:59], v[168:171], v[184:187], v[56:59]
	v_mfma_f32_16x16x32_bf16 v[56:59], v[172:175], v[188:191], v[56:59]
	v_mfma_f32_16x16x32_bf16 v[48:51], v[176:179], v[184:187], v[48:51]
	v_mfma_f32_16x16x32_bf16 v[48:51], v[180:183], v[188:191], v[48:51]
	v_mfma_f32_16x16x32_bf16 v[40:43], v[168:171], v[192:195], v[40:43]
	v_mfma_f32_16x16x32_bf16 v[40:43], v[172:175], v[212:215], v[40:43]
	v_mfma_f32_16x16x32_bf16 v[32:35], v[176:179], v[192:195], v[32:35]
	v_mfma_f32_16x16x32_bf16 v[32:35], v[180:183], v[212:215], v[32:35]
	v_mfma_f32_16x16x32_bf16 v[24:27], v[168:171], v[216:219], v[24:27]
	v_mfma_f32_16x16x32_bf16 v[24:27], v[172:175], v[220:223], v[24:27]
	v_mfma_f32_16x16x32_bf16 v[16:19], v[176:179], v[216:219], v[16:19]
	v_mfma_f32_16x16x32_bf16 v[16:19], v[180:183], v[220:223], v[16:19]
	v_mfma_f32_16x16x32_bf16 v[8:11], v[168:171], v[224:227], v[8:11]
	v_mfma_f32_16x16x32_bf16 v[8:11], v[172:175], v[228:231], v[8:11]
	s_setprio 3
	s_barrier
	v_mfma_f32_16x16x32_bf16 v[0:3], v[176:179], v[224:227], v[0:3]
	v_mfma_f32_16x16x32_bf16 v[0:3], v[180:183], v[228:231], v[0:3]
	s_setprio 0
.Lzj_2_1:
	s_add_i32 s24, 0, 0x18000
	v_add_u32_e32 v150, s24, v200
	s_add_i32 s25, 0, 0x1c000
	ds_read_b128 v[128:131], v150
	ds_read_b128 v[132:135], v150 offset:1024
	ds_read_b128 v[136:139], v150 offset:2048
	ds_read_b128 v[164:167], v150 offset:3072
	v_add_u32_e32 v150, s25, v200
	ds_read_b128 v[168:171], v150
	ds_read_b128 v[172:175], v150 offset:1024
	ds_read_b128 v[176:179], v150 offset:2048
	ds_read_b128 v[180:183], v150 offset:3072
	s_add_u32 s22, vcc_lo, 0x40000
	s_addc_u32 s23, vcc_hi, 0
	s_mov_b32 m0, s66
	v_lshl_add_u64 v[238:239], s[22:23], 0, v[140:141]
	ds_read_b128 v[184:187], v205 offset:32768
	ds_read_b128 v[188:191], v205 offset:33792
	ds_read_b128 v[192:195], v205 offset:34816
	ds_read_b128 v[212:215], v205 offset:35840
	ds_read_b128 v[216:219], v205 offset:36864
	ds_read_b128 v[220:223], v205 offset:37888
	ds_read_b128 v[224:227], v205 offset:38912
	ds_read_b128 v[228:231], v205 offset:39936
	global_load_lds_dwordx4 v[238:239], off
	s_mov_b32 m0, s67
	v_lshl_add_u64 v[238:239], s[22:23], 0, v[144:145]
	global_load_lds_dwordx4 v[238:239], off
	s_waitcnt vmcnt(8) lgkmcnt(0)
	s_barrier
	s_setprio 1
	v_mfma_f32_16x16x32_bf16 v[124:127], v[128:131], v[184:187], v[124:127]
	v_mfma_f32_16x16x32_bf16 v[124:127], v[132:135], v[188:191], v[124:127]
	v_mfma_f32_16x16x32_bf16 v[116:119], v[136:139], v[184:187], v[116:119]
	v_mfma_f32_16x16x32_bf16 v[116:119], v[164:167], v[188:191], v[116:119]
	v_mfma_f32_16x16x32_bf16 v[108:111], v[128:131], v[192:195], v[108:111]
	v_mfma_f32_16x16x32_bf16 v[108:111], v[132:135], v[212:215], v[108:111]
	v_mfma_f32_16x16x32_bf16 v[100:103], v[136:139], v[192:195], v[100:103]
	v_mfma_f32_16x16x32_bf16 v[100:103], v[164:167], v[212:215], v[100:103]
	v_mfma_f32_16x16x32_bf16 v[92:95], v[128:131], v[216:219], v[92:95]
	v_mfma_f32_16x16x32_bf16 v[92:95], v[132:135], v[220:223], v[92:95]
	v_mfma_f32_16x16x32_bf16 v[84:87], v[136:139], v[216:219], v[84:87]
	v_mfma_f32_16x16x32_bf16 v[84:87], v[164:167], v[220:223], v[84:87]
	v_mfma_f32_16x16x32_bf16 v[76:79], v[128:131], v[224:227], v[76:79]
	v_mfma_f32_16x16x32_bf16 v[76:79], v[132:135], v[228:231], v[76:79]
	v_mfma_f32_16x16x32_bf16 v[68:71], v[136:139], v[224:227], v[68:71]
	v_mfma_f32_16x16x32_bf16 v[68:71], v[164:167], v[228:231], v[68:71]
	v_mfma_f32_16x16x32_bf16 v[120:123], v[168:171], v[184:187], v[120:123]
	v_mfma_f32_16x16x32_bf16 v[120:123], v[172:175], v[188:191], v[120:123]
	v_mfma_f32_16x16x32_bf16 v[112:115], v[176:179], v[184:187], v[112:115]
	v_mfma_f32_16x16x32_bf16 v[112:115], v[180:183], v[188:191], v[112:115]
	v_mfma_f32_16x16x32_bf16 v[104:107], v[168:171], v[192:195], v[104:107]
	v_mfma_f32_16x16x32_bf16 v[104:107], v[172:175], v[212:215], v[104:107]
	v_mfma_f32_16x16x32_bf16 v[96:99], v[176:179], v[192:195], v[96:99]
	v_mfma_f32_16x16x32_bf16 v[96:99], v[180:183], v[212:215], v[96:99]
	v_mfma_f32_16x16x32_bf16 v[88:91], v[168:171], v[216:219], v[88:91]
	v_mfma_f32_16x16x32_bf16 v[88:91], v[172:175], v[220:223], v[88:91]
	v_mfma_f32_16x16x32_bf16 v[80:83], v[176:179], v[216:219], v[80:83]
	v_mfma_f32_16x16x32_bf16 v[80:83], v[180:183], v[220:223], v[80:83]
	v_mfma_f32_16x16x32_bf16 v[72:75], v[168:171], v[224:227], v[72:75]
	v_mfma_f32_16x16x32_bf16 v[72:75], v[172:175], v[228:231], v[72:75]
	s_setprio 3
	s_barrier
	v_mfma_f32_16x16x32_bf16 v[64:67], v[176:179], v[224:227], v[64:67]
	v_mfma_f32_16x16x32_bf16 v[64:67], v[180:183], v[228:231], v[64:67]
	s_setprio 0
	s_add_i32 s22, s24, s57
	v_lshl_add_u64 v[196:197], v[196:197], 0, s[80:81]
	s_mov_b32 m0, s22
	ds_read_b128 v[184:187], v205 offset:49152
	ds_read_b128 v[188:191], v205 offset:50176
	ds_read_b128 v[192:195], v205 offset:51200
	ds_read_b128 v[212:215], v205 offset:52224
	ds_read_b128 v[216:219], v205 offset:53248
	ds_read_b128 v[220:223], v205 offset:54272
	ds_read_b128 v[224:227], v205 offset:55296
	ds_read_b128 v[228:231], v205 offset:56320
	global_load_lds_dwordx4 v[196:197], off
	s_add_i32 m0, s22, 0x2000
	s_add_u32 s6, s6, 0x40080
	v_lshl_add_u64 v[196:197], v[232:233], 0, s[80:81]
	s_addc_u32 s7, s7, 0
	s_add_i32 s22, s25, s57
	global_load_lds_dwordx4 v[196:197], off
	s_mov_b32 m0, s22
	v_lshl_add_u64 v[196:197], s[6:7], 0, v[142:143]
	global_load_lds_dwordx4 v[196:197], off
	s_add_i32 m0, s22, 0x2000
	v_lshl_add_u64 v[196:197], s[6:7], 0, v[146:147]
	global_load_lds_dwordx4 v[196:197], off
	s_mov_b32 m0, s93
	v_lshl_add_u64 v[196:197], v[234:235], 0, s[80:81]
	global_load_lds_dwordx4 v[196:197], off
	s_mov_b32 m0, s69
	v_lshl_add_u64 v[196:197], v[236:237], 0, s[80:81]
	global_load_lds_dwordx4 v[196:197], off
	s_waitcnt vmcnt(8) lgkmcnt(0)
	s_barrier
	s_setprio 1
	v_mfma_f32_16x16x32_bf16 v[60:63], v[128:131], v[184:187], v[60:63]
	v_mfma_f32_16x16x32_bf16 v[60:63], v[132:135], v[188:191], v[60:63]
	v_mfma_f32_16x16x32_bf16 v[52:55], v[136:139], v[184:187], v[52:55]
	v_mfma_f32_16x16x32_bf16 v[52:55], v[164:167], v[188:191], v[52:55]
	v_mfma_f32_16x16x32_bf16 v[44:47], v[128:131], v[192:195], v[44:47]
	v_mfma_f32_16x16x32_bf16 v[44:47], v[132:135], v[212:215], v[44:47]
	v_mfma_f32_16x16x32_bf16 v[36:39], v[136:139], v[192:195], v[36:39]
	v_mfma_f32_16x16x32_bf16 v[36:39], v[164:167], v[212:215], v[36:39]
	v_mfma_f32_16x16x32_bf16 v[28:31], v[128:131], v[216:219], v[28:31]
	v_mfma_f32_16x16x32_bf16 v[28:31], v[132:135], v[220:223], v[28:31]
	v_mfma_f32_16x16x32_bf16 v[20:23], v[136:139], v[216:219], v[20:23]
	v_mfma_f32_16x16x32_bf16 v[20:23], v[164:167], v[220:223], v[20:23]
	v_mfma_f32_16x16x32_bf16 v[12:15], v[128:131], v[224:227], v[12:15]
	v_mfma_f32_16x16x32_bf16 v[12:15], v[132:135], v[228:231], v[12:15]
	v_mfma_f32_16x16x32_bf16 v[4:7], v[136:139], v[224:227], v[4:7]
	v_mfma_f32_16x16x32_bf16 v[4:7], v[164:167], v[228:231], v[4:7]
	v_mfma_f32_16x16x32_bf16 v[56:59], v[168:171], v[184:187], v[56:59]
	v_mfma_f32_16x16x32_bf16 v[56:59], v[172:175], v[188:191], v[56:59]
	v_mfma_f32_16x16x32_bf16 v[48:51], v[176:179], v[184:187], v[48:51]
	v_mfma_f32_16x16x32_bf16 v[48:51], v[180:183], v[188:191], v[48:51]
	v_mfma_f32_16x16x32_bf16 v[40:43], v[168:171], v[192:195], v[40:43]
	v_mfma_f32_16x16x32_bf16 v[40:43], v[172:175], v[212:215], v[40:43]
	v_mfma_f32_16x16x32_bf16 v[32:35], v[176:179], v[192:195], v[32:35]
	v_mfma_f32_16x16x32_bf16 v[32:35], v[180:183], v[212:215], v[32:35]
	v_mfma_f32_16x16x32_bf16 v[24:27], v[168:171], v[216:219], v[24:27]
	v_mfma_f32_16x16x32_bf16 v[24:27], v[172:175], v[220:223], v[24:27]
	v_mfma_f32_16x16x32_bf16 v[16:19], v[176:179], v[216:219], v[16:19]
	v_mfma_f32_16x16x32_bf16 v[16:19], v[180:183], v[220:223], v[16:19]
	v_mfma_f32_16x16x32_bf16 v[8:11], v[168:171], v[224:227], v[8:11]
	v_mfma_f32_16x16x32_bf16 v[8:11], v[172:175], v[228:231], v[8:11]
	s_setprio 3
	s_barrier
	v_mfma_f32_16x16x32_bf16 v[0:3], v[176:179], v[224:227], v[0:3]
	v_mfma_f32_16x16x32_bf16 v[0:3], v[180:183], v[228:231], v[0:3]
	s_setprio 0
	s_add_i32 s21, s21, 2
	s_add_u32 s88, s88, 0x100
	s_addc_u32 s89, s89, 0
	s_add_u32 s19, s19, 0x100
	s_addc_u32 s20, s20, 0
	s_cmp_gt_u32 s21, 13
	s_cbranch_scc0 .LBB0_429
	s_branch .Lzskip_2

.LBB0_620:
	v_or_b32_e32 v25, s16, v178
	v_lshl_add_u32 v203, v25, 10, v179
	s_waitcnt lgkmcnt(0)
	ds_read2st64_b32 v[104:105], v203 offset1:4
	ds_read2st64_b32 v[106:107], v203 offset0:8 offset1:12
	ds_read2st64_b32 v[112:113], v203 offset0:40 offset1:44
	ds_read2st64_b32 v[116:117], v203 offset0:48 offset1:52
	ds_read2st64_b32 v[120:121], v203 offset0:56 offset1:60
	s_waitcnt lgkmcnt(4)
	v_lshlrev_b32_e32 v108, 16, v104
	v_and_b32_e32 v109, 0xffff0000, v104
	v_lshlrev_b32_e32 v160, 16, v105
	v_and_b32_e32 v161, 0xffff0000, v105
	v_fma_f32 v104, v76, v108, v78
	v_fma_f32 v105, v77, v109, v79
	ds_read2st64_b32 v[108:109], v203 offset0:16 offset1:20
	s_waitcnt lgkmcnt(4)
	v_lshlrev_b32_e32 v164, 16, v106
	v_and_b32_e32 v165, 0xffff0000, v106
	v_lshlrev_b32_e32 v162, 16, v107
	v_and_b32_e32 v163, 0xffff0000, v107
	ds_read2st64_b32 v[106:107], v203 offset0:24 offset1:28
	v_fma_f32 v104, v34, v160, v104
	v_fma_f32 v105, v35, v161, v105
	s_waitcnt lgkmcnt(1)
	v_lshlrev_b32_e32 v158, 16, v108
	v_fma_f32 v104, v92, v164, v104
	v_fma_f32 v105, v93, v165, v105
	v_and_b32_e32 v159, 0xffff0000, v108
	v_lshlrev_b32_e32 v142, 16, v109
	v_and_b32_e32 v143, 0xffff0000, v109
	ds_read2st64_b32 v[108:109], v203 offset0:32 offset1:36
	v_fma_f32 v104, v52, v162, v104
	v_fma_f32 v105, v53, v163, v105
	s_waitcnt lgkmcnt(1)
	v_lshlrev_b32_e32 v122, 16, v106
	v_fma_f32 v104, v36, v158, v104
	v_fma_f32 v105, v37, v159, v105
	v_and_b32_e32 v123, 0xffff0000, v106
	v_fma_f32 v104, v38, v142, v104
	v_fma_f32 v105, v39, v143, v105
	s_waitcnt lgkmcnt(0)
	v_lshlrev_b32_e32 v106, 16, v108
	v_fma_f32 v110, v40, v122, v104
	v_fma_f32 v111, v41, v123, v105
	v_lshlrev_b32_e32 v104, 16, v107
	v_and_b32_e32 v105, 0xffff0000, v107
	v_fma_f32 v110, v54, v104, v110
	v_fma_f32 v111, v55, v105, v111
	v_and_b32_e32 v107, 0xffff0000, v108
	v_fma_f32 v110, v42, v106, v110
	v_fma_f32 v111, v43, v107, v111
	v_lshlrev_b32_e32 v108, 16, v109
	v_and_b32_e32 v109, 0xffff0000, v109
	v_fma_f32 v114, v44, v108, v110
	v_fma_f32 v115, v45, v109, v111
	v_lshlrev_b32_e32 v110, 16, v112
	v_and_b32_e32 v111, 0xffff0000, v112
	v_fma_f32 v114, v46, v110, v114
	v_fma_f32 v115, v47, v111, v115
	v_lshlrev_b32_e32 v112, 16, v113
	v_and_b32_e32 v113, 0xffff0000, v113
	ds_read2st64_b32 v[126:127], v203 offset0:64 offset1:68
	v_fma_f32 v118, v56, v112, v114
	v_fma_f32 v119, v57, v113, v115
	v_lshlrev_b32_e32 v114, 16, v116
	v_and_b32_e32 v115, 0xffff0000, v116
	v_fma_f32 v118, v48, v114, v118
	v_fma_f32 v119, v49, v115, v119
	v_lshlrev_b32_e32 v116, 16, v117
	v_and_b32_e32 v117, 0xffff0000, v117
	ds_read2st64_b32 v[130:131], v203 offset0:72 offset1:76
	v_fma_f32 v124, v50, v116, v118
	v_fma_f32 v125, v51, v117, v119
	v_lshlrev_b32_e32 v118, 16, v120
	v_and_b32_e32 v119, 0xffff0000, v120
	v_fma_f32 v124, v60, v118, v124
	v_fma_f32 v125, v61, v119, v125
	v_lshlrev_b32_e32 v120, 16, v121
	v_and_b32_e32 v121, 0xffff0000, v121
	ds_read2st64_b32 v[134:135], v203 offset0:80 offset1:84
	v_fma_f32 v128, v58, v120, v124
	v_fma_f32 v129, v59, v121, v125
	s_waitcnt lgkmcnt(2)
	v_lshlrev_b32_e32 v124, 16, v126
	v_and_b32_e32 v125, 0xffff0000, v126
	v_fma_f32 v128, v62, v124, v128
	v_fma_f32 v129, v63, v125, v129
	v_lshlrev_b32_e32 v126, 16, v127
	v_and_b32_e32 v127, 0xffff0000, v127
	ds_read2st64_b32 v[138:139], v203 offset0:88 offset1:92
	v_fma_f32 v132, v64, v126, v128
	v_fma_f32 v133, v65, v127, v129
	s_waitcnt lgkmcnt(2)
	v_lshlrev_b32_e32 v128, 16, v130
	v_and_b32_e32 v129, 0xffff0000, v130
	v_fma_f32 v132, v66, v128, v132
	v_fma_f32 v133, v67, v129, v133
	v_lshlrev_b32_e32 v130, 16, v131
	v_and_b32_e32 v131, 0xffff0000, v131
	ds_read2st64_b32 v[144:145], v203 offset0:96 offset1:100
	v_fma_f32 v136, v84, v130, v132
	v_fma_f32 v137, v85, v131, v133
	s_waitcnt lgkmcnt(2)
	v_lshlrev_b32_e32 v132, 16, v134
	v_and_b32_e32 v133, 0xffff0000, v134
	v_fma_f32 v136, v68, v132, v136
	v_fma_f32 v137, v69, v133, v137
	v_lshlrev_b32_e32 v134, 16, v135
	v_and_b32_e32 v135, 0xffff0000, v135
	ds_read2st64_b32 v[148:149], v203 offset0:104 offset1:108
	v_fma_f32 v140, v70, v134, v136
	v_fma_f32 v141, v71, v135, v137
	s_waitcnt lgkmcnt(2)
	v_lshlrev_b32_e32 v136, 16, v138
	v_and_b32_e32 v137, 0xffff0000, v138
	v_fma_f32 v140, v72, v136, v140
	v_fma_f32 v141, v73, v137, v141
	v_lshlrev_b32_e32 v138, 16, v139
	v_and_b32_e32 v139, 0xffff0000, v139
	ds_read2st64_b32 v[152:153], v203 offset0:112 offset1:116
	v_fma_f32 v146, v86, v138, v140
	v_fma_f32 v147, v87, v139, v141
	s_waitcnt lgkmcnt(2)
	v_lshlrev_b32_e32 v140, 16, v144
	v_and_b32_e32 v141, 0xffff0000, v144
	v_fma_f32 v146, v74, v140, v146
	v_fma_f32 v147, v75, v141, v147
	v_lshlrev_b32_e32 v144, 16, v145
	v_and_b32_e32 v145, 0xffff0000, v145
	ds_read2st64_b32 v[170:171], v203 offset0:120 offset1:124
	v_fma_f32 v150, v82, v144, v146
	v_fma_f32 v151, v83, v145, v147
	s_waitcnt lgkmcnt(2)
	v_lshlrev_b32_e32 v146, 16, v148
	v_and_b32_e32 v147, 0xffff0000, v148
	v_fma_f32 v150, v88, v146, v150
	v_fma_f32 v151, v89, v147, v151
	v_lshlrev_b32_e32 v148, 16, v149
	v_and_b32_e32 v149, 0xffff0000, v149
	v_fma_f32 v154, v90, v148, v150
	v_fma_f32 v155, v91, v149, v151
	s_waitcnt lgkmcnt(1)
	v_lshlrev_b32_e32 v150, 16, v152
	v_and_b32_e32 v151, 0xffff0000, v152
	v_fma_f32 v154, v94, v150, v154
	v_fma_f32 v155, v95, v151, v155
	v_lshlrev_b32_e32 v152, 16, v153
	v_and_b32_e32 v153, 0xffff0000, v153
	v_fma_f32 v156, v96, v152, v154
	v_fma_f32 v157, v97, v153, v155
	s_waitcnt lgkmcnt(0)
	v_lshlrev_b32_e32 v154, 16, v170
	v_and_b32_e32 v155, 0xffff0000, v170
	v_fma_f32 v204, v98, v154, v156
	v_fma_f32 v205, v99, v155, v157
	v_mul_f32_e32 v156, v204, v204
	v_mul_f32_e32 v157, v205, v205
	v_add_f32_e32 v156, v156, v157
	s_waitcnt lgkmcnt(0)
	s_nop 1
	v_add_f32_dpp v156, v156, v156 quad_perm:[1,0,3,2] row_mask:0xf bank_mask:0xf
	s_nop 1
	v_add_f32_dpp v156, v156, v156 quad_perm:[2,3,0,1] row_mask:0xf bank_mask:0xf
	s_nop 1
	v_add_f32_dpp v156, v156, v156 row_ror:4 row_mask:0xf bank_mask:0xf
	s_nop 1
	v_add_f32_dpp v156, v156, v156 row_ror:8 row_mask:0xf bank_mask:0xf
	s_nop 1
	v_add_f32_dpp v156, v156, v156 row_bcast:15 row_mask:0xa bank_mask:0xf
	s_nop 1
	v_add_f32_dpp v156, v156, v156 row_bcast:31 row_mask:0xc bank_mask:0xf
	s_nop 1
	v_readlane_b32 s98, v156, 63
	ds_read2st64_b32 v[168:169], v203 offset0:128 offset1:132
	ds_read2st64_b32 v[166:167], v203 offset0:136 offset1:140
	ds_read2st64_b32 v[156:157], v203 offset0:144 offset1:148
	v_lshl_add_u32 v206, v25, 11, v180
	ds_write_b64 v206, v[204:205] offset:63488
	s_and_saveexec_b64 s[48:49], s[6:7]
	s_cbranch_execz .LBB0_622
	s_waitcnt lgkmcnt(1)
	v_mov_b32_e32 v170, s98
	v_lshl_add_u32 v203, v25, 4, s3
	ds_write_b32 v203, v170
.LBB0_622:
	s_or_b64 exec, exec, s[48:49]
	v_fma_f32 v160, v76, v160, v78
	v_fma_f32 v161, v77, v161, v79
	v_fma_f32 v160, v34, v164, v160
	v_fma_f32 v161, v35, v165, v161
	v_fma_f32 v160, v92, v162, v160
	v_fma_f32 v161, v93, v163, v161
	v_fma_f32 v160, v52, v158, v160
	v_fma_f32 v161, v53, v159, v161
	v_fma_f32 v160, v36, v142, v160
	v_fma_f32 v161, v37, v143, v161
	v_fma_f32 v160, v38, v122, v160
	v_fma_f32 v161, v39, v123, v161
	v_fma_f32 v160, v40, v104, v160
	v_fma_f32 v161, v41, v105, v161
	v_fma_f32 v160, v54, v106, v160
	v_fma_f32 v161, v55, v107, v161
	v_fma_f32 v160, v42, v108, v160
	v_fma_f32 v161, v43, v109, v161
	v_fma_f32 v160, v44, v110, v160
	v_fma_f32 v161, v45, v111, v161
	v_fma_f32 v160, v46, v112, v160
	v_fma_f32 v161, v47, v113, v161
	v_fma_f32 v160, v56, v114, v160
	v_fma_f32 v161, v57, v115, v161
	v_fma_f32 v160, v48, v116, v160
	v_fma_f32 v161, v49, v117, v161
	v_fma_f32 v160, v50, v118, v160
	v_fma_f32 v161, v51, v119, v161
	v_fma_f32 v160, v60, v120, v160
	v_fma_f32 v161, v61, v121, v161
	v_fma_f32 v160, v58, v124, v160
	v_fma_f32 v161, v59, v125, v161
	v_fma_f32 v160, v62, v126, v160
	v_fma_f32 v161, v63, v127, v161
	v_fma_f32 v160, v64, v128, v160
	v_fma_f32 v161, v65, v129, v161
	v_fma_f32 v160, v66, v130, v160
	v_fma_f32 v161, v67, v131, v161
	v_fma_f32 v160, v84, v132, v160
	v_fma_f32 v161, v85, v133, v161
	v_fma_f32 v160, v68, v134, v160
	v_fma_f32 v161, v69, v135, v161
	v_fma_f32 v160, v70, v136, v160
	v_fma_f32 v161, v71, v137, v161
	v_fma_f32 v160, v72, v138, v160
	v_fma_f32 v161, v73, v139, v161
	v_fma_f32 v160, v86, v140, v160
	v_fma_f32 v161, v87, v141, v161
	v_fma_f32 v160, v74, v144, v160
	v_fma_f32 v161, v75, v145, v161
	v_fma_f32 v160, v82, v146, v160
	v_fma_f32 v161, v83, v147, v161
	v_fma_f32 v160, v88, v148, v160
	v_fma_f32 v161, v89, v149, v161
	v_fma_f32 v160, v90, v150, v160
	v_fma_f32 v161, v91, v151, v161
	v_fma_f32 v160, v94, v152, v160
	v_fma_f32 v161, v95, v153, v161
	v_fma_f32 v204, v96, v154, v160
	v_fma_f32 v205, v97, v155, v161
	v_lshlrev_b32_e32 v160, 16, v171
	v_and_b32_e32 v161, 0xffff0000, v171
	v_fma_f32 v204, v98, v160, v204
	v_fma_f32 v205, v99, v161, v205
	v_mul_f32_e32 v170, v204, v204
	v_mul_f32_e32 v171, v205, v205
	v_add_f32_e32 v170, v170, v171
	s_waitcnt lgkmcnt(0)
	s_nop 1
	v_add_f32_dpp v170, v170, v170 quad_perm:[1,0,3,2] row_mask:0xf bank_mask:0xf
	s_nop 1
	v_add_f32_dpp v170, v170, v170 quad_perm:[2,3,0,1] row_mask:0xf bank_mask:0xf
	s_nop 1
	v_add_f32_dpp v170, v170, v170 row_ror:4 row_mask:0xf bank_mask:0xf
	s_nop 1
	v_add_f32_dpp v170, v170, v170 row_ror:8 row_mask:0xf bank_mask:0xf
	s_nop 1
	v_add_f32_dpp v170, v170, v170 row_bcast:15 row_mask:0xa bank_mask:0xf
	s_nop 1
	v_add_f32_dpp v170, v170, v170 row_bcast:31 row_mask:0xc bank_mask:0xf
	s_nop 1
	v_readlane_b32 s98, v170, 63
	v_or_b32_e32 v171, 1, v25
	v_lshl_add_u32 v206, v171, 11, v180
	ds_write_b64 v206, v[204:205] offset:63488
	s_and_saveexec_b64 s[48:49], s[6:7]
	s_cbranch_execz .LBB0_624
	s_waitcnt lgkmcnt(1)
	v_mov_b32_e32 v170, s98
	v_lshl_add_u32 v171, v171, 4, s3
	ds_write_b32 v171, v170
.LBB0_624:
	s_or_b64 exec, exec, s[48:49]
	v_fma_f32 v164, v76, v164, v78
	v_fma_f32 v165, v77, v165, v79
	v_fma_f32 v164, v34, v162, v164
	v_fma_f32 v165, v35, v163, v165
	v_fma_f32 v164, v92, v158, v164
	v_fma_f32 v165, v93, v159, v165
	v_fma_f32 v164, v52, v142, v164
	v_fma_f32 v165, v53, v143, v165
	v_fma_f32 v164, v36, v122, v164
	v_fma_f32 v165, v37, v123, v165
	v_fma_f32 v164, v38, v104, v164
	v_fma_f32 v165, v39, v105, v165
	v_fma_f32 v164, v40, v106, v164
	v_fma_f32 v165, v41, v107, v165
	v_fma_f32 v164, v54, v108, v164
	v_fma_f32 v165, v55, v109, v165
	v_fma_f32 v164, v42, v110, v164
	v_fma_f32 v165, v43, v111, v165
	v_fma_f32 v164, v44, v112, v164
	v_fma_f32 v165, v45, v113, v165
	v_fma_f32 v164, v46, v114, v164
	v_fma_f32 v165, v47, v115, v165
	v_fma_f32 v164, v56, v116, v164
	v_fma_f32 v165, v57, v117, v165
	v_fma_f32 v164, v48, v118, v164
	v_fma_f32 v165, v49, v119, v165
	v_fma_f32 v164, v50, v120, v164
	v_fma_f32 v165, v51, v121, v165
	v_fma_f32 v164, v60, v124, v164
	v_fma_f32 v165, v61, v125, v165
	v_fma_f32 v164, v58, v126, v164
	v_fma_f32 v165, v59, v127, v165
	v_fma_f32 v164, v62, v128, v164
	v_fma_f32 v165, v63, v129, v165
	v_fma_f32 v164, v64, v130, v164
	v_fma_f32 v165, v65, v131, v165
	v_fma_f32 v164, v66, v132, v164
	v_fma_f32 v165, v67, v133, v165
	v_fma_f32 v164, v84, v134, v164
	v_fma_f32 v165, v85, v135, v165
	v_fma_f32 v164, v68, v136, v164
	v_fma_f32 v165, v69, v137, v165
	v_fma_f32 v164, v70, v138, v164
	v_fma_f32 v165, v71, v139, v165
	v_fma_f32 v164, v72, v140, v164
	v_fma_f32 v165, v73, v141, v165
	v_fma_f32 v164, v86, v144, v164
	v_fma_f32 v165, v87, v145, v165
	v_fma_f32 v164, v74, v146, v164
	v_fma_f32 v165, v75, v147, v165
	v_fma_f32 v164, v82, v148, v164
	v_fma_f32 v165, v83, v149, v165
	v_fma_f32 v164, v88, v150, v164
	v_fma_f32 v165, v89, v151, v165
	v_fma_f32 v164, v90, v152, v164
	v_fma_f32 v165, v91, v153, v165
	v_fma_f32 v164, v94, v154, v164
	v_fma_f32 v165, v95, v155, v165
	v_fma_f32 v170, v96, v160, v164
	v_fma_f32 v171, v97, v161, v165
	v_lshlrev_b32_e32 v164, 16, v168
	v_and_b32_e32 v165, 0xffff0000, v168
	v_fma_f32 v204, v98, v164, v170
	v_fma_f32 v205, v99, v165, v171
	v_mul_f32_e32 v170, v204, v204
	v_mul_f32_e32 v171, v205, v205
	v_add_f32_e32 v168, v170, v171
	s_waitcnt lgkmcnt(0)
	s_nop 1
	v_add_f32_dpp v168, v168, v168 quad_perm:[1,0,3,2] row_mask:0xf bank_mask:0xf
	s_nop 1
	v_add_f32_dpp v168, v168, v168 quad_perm:[2,3,0,1] row_mask:0xf bank_mask:0xf
	s_nop 1
	v_add_f32_dpp v168, v168, v168 row_ror:4 row_mask:0xf bank_mask:0xf
	s_nop 1
	v_add_f32_dpp v168, v168, v168 row_ror:8 row_mask:0xf bank_mask:0xf
	s_nop 1
	v_add_f32_dpp v168, v168, v168 row_bcast:15 row_mask:0xa bank_mask:0xf
	s_nop 1
	v_add_f32_dpp v168, v168, v168 row_bcast:31 row_mask:0xc bank_mask:0xf
	s_nop 1
	v_readlane_b32 s98, v168, 63
	v_or_b32_e32 v170, 2, v25
	v_lshl_add_u32 v203, v170, 11, v180
	ds_write_b64 v203, v[204:205] offset:63488
	s_and_saveexec_b64 s[48:49], s[6:7]
	s_cbranch_execz .LBB0_626
	s_waitcnt lgkmcnt(1)
	v_mov_b32_e32 v168, s98
	v_lshl_add_u32 v170, v170, 4, s3
	ds_write_b32 v170, v168
.LBB0_626:
	s_or_b64 exec, exec, s[48:49]
	v_fma_f32 v162, v76, v162, v78
	v_fma_f32 v163, v77, v163, v79
	v_fma_f32 v162, v34, v158, v162
	v_fma_f32 v163, v35, v159, v163
	v_fma_f32 v162, v92, v142, v162
	v_fma_f32 v163, v93, v143, v163
	v_fma_f32 v162, v52, v122, v162
	v_fma_f32 v163, v53, v123, v163
	v_fma_f32 v162, v36, v104, v162
	v_fma_f32 v163, v37, v105, v163
	v_fma_f32 v162, v38, v106, v162
	v_fma_f32 v163, v39, v107, v163
	v_fma_f32 v162, v40, v108, v162
	v_fma_f32 v163, v41, v109, v163
	v_fma_f32 v162, v54, v110, v162
	v_fma_f32 v163, v55, v111, v163
	v_fma_f32 v162, v42, v112, v162
	v_fma_f32 v163, v43, v113, v163
	v_fma_f32 v162, v44, v114, v162
	v_fma_f32 v163, v45, v115, v163
	v_fma_f32 v162, v46, v116, v162
	v_fma_f32 v163, v47, v117, v163
	v_fma_f32 v162, v56, v118, v162
	v_fma_f32 v163, v57, v119, v163
	v_fma_f32 v162, v48, v120, v162
	v_fma_f32 v163, v49, v121, v163
	v_fma_f32 v162, v50, v124, v162
	v_fma_f32 v163, v51, v125, v163
	v_fma_f32 v162, v60, v126, v162
	v_fma_f32 v163, v61, v127, v163
	v_fma_f32 v162, v58, v128, v162
	v_fma_f32 v163, v59, v129, v163
	v_fma_f32 v162, v62, v130, v162
	v_fma_f32 v163, v63, v131, v163
	v_fma_f32 v162, v64, v132, v162
	v_fma_f32 v163, v65, v133, v163
	v_fma_f32 v162, v66, v134, v162
	v_fma_f32 v163, v67, v135, v163
	v_fma_f32 v162, v84, v136, v162
	v_fma_f32 v163, v85, v137, v163
	v_fma_f32 v162, v68, v138, v162
	v_fma_f32 v163, v69, v139, v163
	v_fma_f32 v162, v70, v140, v162
	v_fma_f32 v163, v71, v141, v163
	v_fma_f32 v162, v72, v144, v162
	v_fma_f32 v163, v73, v145, v163
	v_fma_f32 v162, v86, v146, v162
	v_fma_f32 v163, v87, v147, v163
	v_fma_f32 v162, v74, v148, v162
	v_fma_f32 v163, v75, v149, v163
	v_fma_f32 v162, v82, v150, v162
	v_fma_f32 v163, v83, v151, v163
	v_fma_f32 v162, v88, v152, v162
	v_fma_f32 v163, v89, v153, v163
	v_fma_f32 v162, v90, v154, v162
	v_fma_f32 v163, v91, v155, v163
	v_fma_f32 v162, v94, v160, v162
	v_fma_f32 v163, v95, v161, v163
	s_waitcnt lgkmcnt(1)
	v_fma_f32 v170, v96, v164, v162
	v_fma_f32 v171, v97, v165, v163
	v_lshlrev_b32_e32 v162, 16, v169
	v_and_b32_e32 v163, 0xffff0000, v169
	v_fma_f32 v204, v98, v162, v170
	v_fma_f32 v205, v99, v163, v171
	v_mul_f32_e32 v168, v204, v204
	v_mul_f32_e32 v169, v205, v205
	v_add_f32_e32 v168, v168, v169
	s_waitcnt lgkmcnt(0)
	s_nop 1
	v_add_f32_dpp v168, v168, v168 quad_perm:[1,0,3,2] row_mask:0xf bank_mask:0xf
	s_nop 1
	v_add_f32_dpp v168, v168, v168 quad_perm:[2,3,0,1] row_mask:0xf bank_mask:0xf
	s_nop 1
	v_add_f32_dpp v168, v168, v168 row_ror:4 row_mask:0xf bank_mask:0xf
	s_nop 1
	v_add_f32_dpp v168, v168, v168 row_ror:8 row_mask:0xf bank_mask:0xf
	s_nop 1
	v_add_f32_dpp v168, v168, v168 row_bcast:15 row_mask:0xa bank_mask:0xf
	s_nop 1
	v_add_f32_dpp v168, v168, v168 row_bcast:31 row_mask:0xc bank_mask:0xf
	s_nop 1
	v_readlane_b32 s98, v168, 63
	v_or_b32_e32 v169, 3, v25
	v_lshl_add_u32 v171, v169, 11, v180
	ds_write_b64 v171, v[204:205] offset:63488
	s_and_saveexec_b64 s[48:49], s[6:7]
	s_cbranch_execz .LBB0_628
	s_waitcnt lgkmcnt(1)
	v_mov_b32_e32 v168, s98
	v_lshl_add_u32 v169, v169, 4, s3
	ds_write_b32 v169, v168
.LBB0_628:
	s_or_b64 exec, exec, s[48:49]
	v_fma_f32 v158, v76, v158, v78
	v_fma_f32 v159, v77, v159, v79
	v_fma_f32 v158, v34, v142, v158
	v_fma_f32 v159, v35, v143, v159
	v_fma_f32 v158, v92, v122, v158
	v_fma_f32 v159, v93, v123, v159
	v_fma_f32 v158, v52, v104, v158
	v_fma_f32 v159, v53, v105, v159
	v_fma_f32 v158, v36, v106, v158
	v_fma_f32 v159, v37, v107, v159
	v_fma_f32 v158, v38, v108, v158
	v_fma_f32 v159, v39, v109, v159
	v_fma_f32 v158, v40, v110, v158
	v_fma_f32 v159, v41, v111, v159
	v_fma_f32 v158, v54, v112, v158
	v_fma_f32 v159, v55, v113, v159
	v_fma_f32 v158, v42, v114, v158
	v_fma_f32 v159, v43, v115, v159
	v_fma_f32 v158, v44, v116, v158
	v_fma_f32 v159, v45, v117, v159
	v_fma_f32 v158, v46, v118, v158
	v_fma_f32 v159, v47, v119, v159
	v_fma_f32 v158, v56, v120, v158
	v_fma_f32 v159, v57, v121, v159
	v_fma_f32 v158, v48, v124, v158
	v_fma_f32 v159, v49, v125, v159
	v_fma_f32 v158, v50, v126, v158
	v_fma_f32 v159, v51, v127, v159
	v_fma_f32 v158, v60, v128, v158
	v_fma_f32 v159, v61, v129, v159
	v_fma_f32 v158, v58, v130, v158
	v_fma_f32 v159, v59, v131, v159
	v_fma_f32 v158, v62, v132, v158
	v_fma_f32 v159, v63, v133, v159
	v_fma_f32 v158, v64, v134, v158
	v_fma_f32 v159, v65, v135, v159
	v_fma_f32 v158, v66, v136, v158
	v_fma_f32 v159, v67, v137, v159
	v_fma_f32 v158, v84, v138, v158
	v_fma_f32 v159, v85, v139, v159
	v_fma_f32 v158, v68, v140, v158
	v_fma_f32 v159, v69, v141, v159
	v_fma_f32 v158, v70, v144, v158
	v_fma_f32 v159, v71, v145, v159
	v_fma_f32 v158, v72, v146, v158
	v_fma_f32 v159, v73, v147, v159
	v_fma_f32 v158, v86, v148, v158
	v_fma_f32 v159, v87, v149, v159
	v_fma_f32 v158, v74, v150, v158
	v_fma_f32 v159, v75, v151, v159
	v_fma_f32 v158, v82, v152, v158
	v_fma_f32 v159, v83, v153, v159
	v_fma_f32 v158, v88, v154, v158
	v_fma_f32 v159, v89, v155, v159
	v_fma_f32 v158, v90, v160, v158
	v_fma_f32 v159, v91, v161, v159
	v_fma_f32 v158, v94, v164, v158
	v_fma_f32 v159, v95, v165, v159
	v_fma_f32 v168, v96, v162, v158
	v_fma_f32 v169, v97, v163, v159
	v_lshlrev_b32_e32 v158, 16, v166
	v_and_b32_e32 v159, 0xffff0000, v166
	s_waitcnt lgkmcnt(1)
	v_fma_f32 v170, v98, v158, v168
	v_fma_f32 v171, v99, v159, v169
	v_mul_f32_e32 v168, v170, v170
	v_mul_f32_e32 v169, v171, v171
	v_add_f32_e32 v166, v168, v169
	s_waitcnt lgkmcnt(0)
	s_nop 1
	v_add_f32_dpp v166, v166, v166 quad_perm:[1,0,3,2] row_mask:0xf bank_mask:0xf
	s_nop 1
	v_add_f32_dpp v166, v166, v166 quad_perm:[2,3,0,1] row_mask:0xf bank_mask:0xf
	s_nop 1
	v_add_f32_dpp v166, v166, v166 row_ror:4 row_mask:0xf bank_mask:0xf
	s_nop 1
	v_add_f32_dpp v166, v166, v166 row_ror:8 row_mask:0xf bank_mask:0xf
	s_nop 1
	v_add_f32_dpp v166, v166, v166 row_bcast:15 row_mask:0xa bank_mask:0xf
	s_nop 1
	v_add_f32_dpp v166, v166, v166 row_bcast:31 row_mask:0xc bank_mask:0xf
	s_nop 1
	v_readlane_b32 s98, v166, 63
	v_or_b32_e32 v168, 4, v25
	v_lshl_add_u32 v203, v168, 11, v180
	ds_write_b64 v203, v[170:171] offset:63488
	s_and_saveexec_b64 s[48:49], s[6:7]
	s_cbranch_execz .LBB0_630
	s_waitcnt lgkmcnt(1)
	v_mov_b32_e32 v166, s98
	v_lshl_add_u32 v168, v168, 4, s3
	ds_write_b32 v168, v166
.LBB0_630:
	s_or_b64 exec, exec, s[48:49]
	v_fma_f32 v142, v76, v142, v78
	v_fma_f32 v143, v77, v143, v79
	v_fma_f32 v142, v34, v122, v142
	v_fma_f32 v143, v35, v123, v143
	v_fma_f32 v142, v92, v104, v142
	v_fma_f32 v143, v93, v105, v143
	v_fma_f32 v142, v52, v106, v142
	v_fma_f32 v143, v53, v107, v143
	v_fma_f32 v142, v36, v108, v142
	v_fma_f32 v143, v37, v109, v143
	v_fma_f32 v142, v38, v110, v142
	v_fma_f32 v143, v39, v111, v143
	v_fma_f32 v142, v40, v112, v142
	v_fma_f32 v143, v41, v113, v143
	v_fma_f32 v142, v54, v114, v142
	v_fma_f32 v143, v55, v115, v143
	v_fma_f32 v142, v42, v116, v142
	v_fma_f32 v143, v43, v117, v143
	v_fma_f32 v142, v44, v118, v142
	v_fma_f32 v143, v45, v119, v143
	v_fma_f32 v142, v46, v120, v142
	v_fma_f32 v143, v47, v121, v143
	v_fma_f32 v142, v56, v124, v142
	v_fma_f32 v143, v57, v125, v143
	v_fma_f32 v142, v48, v126, v142
	v_fma_f32 v143, v49, v127, v143
	v_fma_f32 v142, v50, v128, v142
	v_fma_f32 v143, v51, v129, v143
	v_fma_f32 v142, v60, v130, v142
	v_fma_f32 v143, v61, v131, v143
	v_fma_f32 v142, v58, v132, v142
	v_fma_f32 v143, v59, v133, v143
	v_fma_f32 v142, v62, v134, v142
	v_fma_f32 v143, v63, v135, v143
	v_fma_f32 v142, v64, v136, v142
	v_fma_f32 v143, v65, v137, v143
	v_fma_f32 v142, v66, v138, v142
	v_fma_f32 v143, v67, v139, v143
	v_fma_f32 v142, v84, v140, v142
	v_fma_f32 v143, v85, v141, v143
	v_fma_f32 v142, v68, v144, v142
	v_fma_f32 v143, v69, v145, v143
	v_fma_f32 v142, v70, v146, v142
	v_fma_f32 v143, v71, v147, v143
	v_fma_f32 v142, v72, v148, v142
	v_fma_f32 v143, v73, v149, v143
	v_fma_f32 v142, v86, v150, v142
	v_fma_f32 v143, v87, v151, v143
	v_fma_f32 v142, v74, v152, v142
	v_fma_f32 v143, v75, v153, v143
	v_fma_f32 v142, v82, v154, v142
	v_fma_f32 v143, v83, v155, v143
	v_fma_f32 v142, v88, v160, v142
	v_fma_f32 v143, v89, v161, v143
	v_fma_f32 v142, v90, v164, v142
	v_fma_f32 v143, v91, v165, v143
	v_fma_f32 v142, v94, v162, v142
	v_fma_f32 v143, v95, v163, v143
	s_waitcnt lgkmcnt(1)
	v_fma_f32 v168, v96, v158, v142
	v_fma_f32 v169, v97, v159, v143
	v_lshlrev_b32_e32 v142, 16, v167
	v_and_b32_e32 v143, 0xffff0000, v167
	v_fma_f32 v170, v98, v142, v168
	v_fma_f32 v171, v99, v143, v169
	v_mul_f32_e32 v166, v170, v170
	v_mul_f32_e32 v167, v171, v171
	v_add_f32_e32 v166, v166, v167
	s_waitcnt lgkmcnt(0)
	s_nop 1
	v_add_f32_dpp v166, v166, v166 quad_perm:[1,0,3,2] row_mask:0xf bank_mask:0xf
	s_nop 1
	v_add_f32_dpp v166, v166, v166 quad_perm:[2,3,0,1] row_mask:0xf bank_mask:0xf
	s_nop 1
	v_add_f32_dpp v166, v166, v166 row_ror:4 row_mask:0xf bank_mask:0xf
	s_nop 1
	v_add_f32_dpp v166, v166, v166 row_ror:8 row_mask:0xf bank_mask:0xf
	s_nop 1
	v_add_f32_dpp v166, v166, v166 row_bcast:15 row_mask:0xa bank_mask:0xf
	s_nop 1
	v_add_f32_dpp v166, v166, v166 row_bcast:31 row_mask:0xc bank_mask:0xf
	s_nop 1
	v_readlane_b32 s98, v166, 63
	v_or_b32_e32 v167, 5, v25
	v_lshl_add_u32 v169, v167, 11, v180
	ds_write_b64 v169, v[170:171] offset:63488
	s_and_saveexec_b64 s[48:49], s[6:7]
	s_cbranch_execz .LBB0_632
	s_waitcnt lgkmcnt(1)
	v_mov_b32_e32 v166, s98
	v_lshl_add_u32 v167, v167, 4, s3
	ds_write_b32 v167, v166
.LBB0_632:
	s_or_b64 exec, exec, s[48:49]
	v_fma_f32 v122, v76, v122, v78
	v_fma_f32 v123, v77, v123, v79
	v_fma_f32 v122, v34, v104, v122
	v_fma_f32 v123, v35, v105, v123
	v_fma_f32 v122, v92, v106, v122
	v_fma_f32 v123, v93, v107, v123
	v_fma_f32 v122, v52, v108, v122
	v_fma_f32 v123, v53, v109, v123
	v_fma_f32 v122, v36, v110, v122
	v_fma_f32 v123, v37, v111, v123
	v_fma_f32 v122, v38, v112, v122
	v_fma_f32 v123, v39, v113, v123
	v_fma_f32 v122, v40, v114, v122
	v_fma_f32 v123, v41, v115, v123
	v_fma_f32 v122, v54, v116, v122
	v_fma_f32 v123, v55, v117, v123
	v_fma_f32 v122, v42, v118, v122
	v_fma_f32 v123, v43, v119, v123
	v_fma_f32 v122, v44, v120, v122
	v_fma_f32 v123, v45, v121, v123
	v_fma_f32 v122, v46, v124, v122
	v_fma_f32 v123, v47, v125, v123
	v_fma_f32 v122, v56, v126, v122
	v_fma_f32 v123, v57, v127, v123
	v_fma_f32 v122, v48, v128, v122
	v_fma_f32 v123, v49, v129, v123
	v_fma_f32 v122, v50, v130, v122
	v_fma_f32 v123, v51, v131, v123
	v_fma_f32 v122, v60, v132, v122
	v_fma_f32 v123, v61, v133, v123
	v_fma_f32 v122, v58, v134, v122
	v_fma_f32 v123, v59, v135, v123
	v_fma_f32 v122, v62, v136, v122
	v_fma_f32 v123, v63, v137, v123
	v_fma_f32 v122, v64, v138, v122
	v_fma_f32 v123, v65, v139, v123
	v_fma_f32 v122, v66, v140, v122
	v_fma_f32 v123, v67, v141, v123
	v_fma_f32 v122, v84, v144, v122
	v_fma_f32 v123, v85, v145, v123
	v_fma_f32 v122, v68, v146, v122
	v_fma_f32 v123, v69, v147, v123
	v_fma_f32 v122, v70, v148, v122
	v_fma_f32 v123, v71, v149, v123
	v_fma_f32 v122, v72, v150, v122
	v_fma_f32 v123, v73, v151, v123
	v_fma_f32 v122, v86, v152, v122
	v_fma_f32 v123, v87, v153, v123
	v_fma_f32 v122, v74, v154, v122
	v_fma_f32 v123, v75, v155, v123
	v_fma_f32 v122, v82, v160, v122
	v_fma_f32 v123, v83, v161, v123
	v_fma_f32 v122, v88, v164, v122
	v_fma_f32 v123, v89, v165, v123
	v_fma_f32 v122, v90, v162, v122
	v_fma_f32 v123, v91, v163, v123
	v_fma_f32 v122, v94, v158, v122
	v_fma_f32 v123, v95, v159, v123
	v_fma_f32 v166, v96, v142, v122
	v_fma_f32 v167, v97, v143, v123
	v_lshlrev_b32_e32 v122, 16, v156
	v_and_b32_e32 v123, 0xffff0000, v156
	s_waitcnt lgkmcnt(1)
	v_fma_f32 v168, v98, v122, v166
	v_fma_f32 v169, v99, v123, v167
	v_mul_f32_e32 v166, v168, v168
	v_mul_f32_e32 v167, v169, v169
	v_add_f32_e32 v156, v166, v167
	s_waitcnt lgkmcnt(0)
	s_nop 1
	v_add_f32_dpp v156, v156, v156 quad_perm:[1,0,3,2] row_mask:0xf bank_mask:0xf
	s_nop 1
	v_add_f32_dpp v156, v156, v156 quad_perm:[2,3,0,1] row_mask:0xf bank_mask:0xf
	s_nop 1
	v_add_f32_dpp v156, v156, v156 row_ror:4 row_mask:0xf bank_mask:0xf
	s_nop 1
	v_add_f32_dpp v156, v156, v156 row_ror:8 row_mask:0xf bank_mask:0xf
	s_nop 1
	v_add_f32_dpp v156, v156, v156 row_bcast:15 row_mask:0xa bank_mask:0xf
	s_nop 1
	v_add_f32_dpp v156, v156, v156 row_bcast:31 row_mask:0xc bank_mask:0xf
	s_nop 1
	v_readlane_b32 s98, v156, 63
	v_or_b32_e32 v166, 6, v25
	v_lshl_add_u32 v170, v166, 11, v180
	ds_write_b64 v170, v[168:169] offset:63488
	s_and_saveexec_b64 s[48:49], s[6:7]
	s_cbranch_execz .LBB0_634
	s_waitcnt lgkmcnt(1)
	v_mov_b32_e32 v156, s98
	v_lshl_add_u32 v166, v166, 4, s3
	ds_write_b32 v166, v156
.LBB0_634:
	s_or_b64 exec, exec, s[48:49]
	v_fma_f32 v104, v76, v104, v78
	v_fma_f32 v105, v77, v105, v79
	v_or_b32_e32 v25, 7, v25
	v_fma_f32 v104, v34, v106, v104
	v_fma_f32 v105, v35, v107, v105
	v_lshlrev_b32_e32 v106, 16, v157
	v_fma_f32 v104, v92, v108, v104
	v_fma_f32 v105, v93, v109, v105
	v_and_b32_e32 v107, 0xffff0000, v157
	v_fma_f32 v104, v52, v110, v104
	v_fma_f32 v105, v53, v111, v105
	v_lshl_add_u32 v108, v25, 11, v180
	v_fma_f32 v104, v36, v112, v104
	v_fma_f32 v105, v37, v113, v105
	v_fma_f32 v104, v38, v114, v104
	v_fma_f32 v105, v39, v115, v105
	v_fma_f32 v104, v40, v116, v104
	v_fma_f32 v105, v41, v117, v105
	v_fma_f32 v104, v54, v118, v104
	v_fma_f32 v105, v55, v119, v105
	v_fma_f32 v104, v42, v120, v104
	v_fma_f32 v105, v43, v121, v105
	v_fma_f32 v104, v44, v124, v104
	v_fma_f32 v105, v45, v125, v105
	v_fma_f32 v104, v46, v126, v104
	v_fma_f32 v105, v47, v127, v105
	v_fma_f32 v104, v56, v128, v104
	v_fma_f32 v105, v57, v129, v105
	v_fma_f32 v104, v48, v130, v104
	v_fma_f32 v105, v49, v131, v105
	v_fma_f32 v104, v50, v132, v104
	v_fma_f32 v105, v51, v133, v105
	v_fma_f32 v104, v60, v134, v104
	v_fma_f32 v105, v61, v135, v105
	v_fma_f32 v104, v58, v136, v104
	v_fma_f32 v105, v59, v137, v105
	v_fma_f32 v104, v62, v138, v104
	v_fma_f32 v105, v63, v139, v105
	v_fma_f32 v104, v64, v140, v104
	v_fma_f32 v105, v65, v141, v105
	v_fma_f32 v104, v66, v144, v104
	v_fma_f32 v105, v67, v145, v105
	v_fma_f32 v104, v84, v146, v104
	v_fma_f32 v105, v85, v147, v105
	v_fma_f32 v104, v68, v148, v104
	v_fma_f32 v105, v69, v149, v105
	v_fma_f32 v104, v70, v150, v104
	v_fma_f32 v105, v71, v151, v105
	v_fma_f32 v104, v72, v152, v104
	v_fma_f32 v105, v73, v153, v105
	v_fma_f32 v104, v86, v154, v104
	v_fma_f32 v105, v87, v155, v105
	v_fma_f32 v104, v74, v160, v104
	v_fma_f32 v105, v75, v161, v105
	v_fma_f32 v104, v82, v164, v104
	v_fma_f32 v105, v83, v165, v105
	v_fma_f32 v104, v88, v162, v104
	v_fma_f32 v105, v89, v163, v105
	v_fma_f32 v104, v90, v158, v104
	v_fma_f32 v105, v91, v159, v105
	v_fma_f32 v104, v94, v142, v104
	v_fma_f32 v105, v95, v143, v105
	v_fma_f32 v104, v96, v122, v104
	v_fma_f32 v105, v97, v123, v105
	v_fma_f32 v106, v98, v106, v104
	v_fma_f32 v107, v99, v107, v105
	ds_write_b64 v108, v[106:107] offset:63488
	v_mul_f32_e32 v104, v106, v106
	v_mul_f32_e32 v105, v107, v107
	v_add_f32_e32 v104, v104, v105
	s_waitcnt lgkmcnt(0)
	s_nop 1
	v_add_f32_dpp v104, v104, v104 quad_perm:[1,0,3,2] row_mask:0xf bank_mask:0xf
	s_nop 1
	v_add_f32_dpp v104, v104, v104 quad_perm:[2,3,0,1] row_mask:0xf bank_mask:0xf
	s_nop 1
	v_add_f32_dpp v104, v104, v104 row_ror:4 row_mask:0xf bank_mask:0xf
	s_nop 1
	v_add_f32_dpp v104, v104, v104 row_ror:8 row_mask:0xf bank_mask:0xf
	s_nop 1
	v_add_f32_dpp v104, v104, v104 row_bcast:15 row_mask:0xa bank_mask:0xf
	s_nop 1
	v_add_f32_dpp v104, v104, v104 row_bcast:31 row_mask:0xc bank_mask:0xf
	s_nop 1
	v_readlane_b32 s98, v104, 63
	s_and_saveexec_b64 s[48:49], s[6:7]
	s_cbranch_execz .LBB0_619
	s_waitcnt lgkmcnt(0)
	v_mov_b32_e32 v104, s98
	v_lshl_add_u32 v25, v25, 4, s3
	ds_write_b32 v25, v104
	s_branch .LBB0_619

.LBB0_993:
	ds_read_b128 v[120:123], v245
	ds_read_b128 v[124:127], v245 offset:1024
	ds_read_b128 v[128:131], v245 offset:2048
	ds_read_b128 v[132:135], v245 offset:3072
	ds_read_b128 v[144:147], v246
	ds_read_b128 v[148:151], v246 offset:1024
	ds_read_b128 v[152:155], v246 offset:2048
	ds_read_b128 v[156:159], v246 offset:3072
	s_add_u32 s59, s82, 0xfffc0080
	s_addc_u32 s66, s83, -1
	s_cmp_eq_u32 s58, 12
	s_cselect_b32 s87, s53, s66
	s_cselect_b32 s86, s54, s59
	s_cselect_b32 s85, s51, s57
	s_cselect_b32 s84, s55, s56
	v_lshl_add_u64 v[204:205], s[82:83], 0, v[200:201]
	s_add_i32 m0, s16, 0xc000
	ds_read_b128 v[160:163], v247
	ds_read_b128 v[164:167], v247 offset:1024
	ds_read_b128 v[168:171], v247 offset:2048
	ds_read_b128 v[172:175], v247 offset:3072
	ds_read_b128 v[176:179], v247 offset:4096
	ds_read_b128 v[180:183], v247 offset:5120
	ds_read_b128 v[184:187], v247 offset:6144
	ds_read_b128 v[188:191], v247 offset:7168
	global_load_lds_dwordx4 v[204:205], off
	s_add_i32 m0, s16, 0xe000
	v_lshl_add_u64 v[204:205], s[82:83], 0, v[202:203]
	global_load_lds_dwordx4 v[204:205], off
	s_cmp_eq_u32 s58, -2
	s_waitcnt vmcnt(8) lgkmcnt(0)
	s_barrier
	s_setprio 1
	s_cbranch_scc1 .Lzv_3_0
	v_mfma_f32_16x16x32_bf16 v[140:143], v[120:123], v[160:163], v[140:143]
	v_mfma_f32_16x16x32_bf16 v[140:143], v[124:127], v[164:167], v[140:143]
	v_mfma_f32_16x16x32_bf16 v[136:139], v[128:131], v[160:163], v[136:139]
	v_mfma_f32_16x16x32_bf16 v[136:139], v[132:135], v[164:167], v[136:139]
	v_mfma_f32_16x16x32_bf16 v[108:111], v[120:123], v[168:171], v[108:111]
	v_mfma_f32_16x16x32_bf16 v[108:111], v[124:127], v[172:175], v[108:111]
	v_mfma_f32_16x16x32_bf16 v[104:107], v[128:131], v[168:171], v[104:107]
	v_mfma_f32_16x16x32_bf16 v[104:107], v[132:135], v[172:175], v[104:107]
	v_mfma_f32_16x16x32_bf16 v[92:95], v[120:123], v[176:179], v[92:95]
	v_mfma_f32_16x16x32_bf16 v[92:95], v[124:127], v[180:183], v[92:95]
	v_mfma_f32_16x16x32_bf16 v[88:91], v[128:131], v[176:179], v[88:91]
	v_mfma_f32_16x16x32_bf16 v[88:91], v[132:135], v[180:183], v[88:91]
	v_mfma_f32_16x16x32_bf16 v[76:79], v[120:123], v[184:187], v[76:79]
	v_mfma_f32_16x16x32_bf16 v[76:79], v[124:127], v[188:191], v[76:79]
	v_mfma_f32_16x16x32_bf16 v[72:75], v[128:131], v[184:187], v[72:75]
	v_mfma_f32_16x16x32_bf16 v[72:75], v[132:135], v[188:191], v[72:75]
	v_mfma_f32_16x16x32_bf16 v[116:119], v[144:147], v[160:163], v[116:119]
	v_mfma_f32_16x16x32_bf16 v[116:119], v[148:151], v[164:167], v[116:119]
	v_mfma_f32_16x16x32_bf16 v[112:115], v[152:155], v[160:163], v[112:115]
	v_mfma_f32_16x16x32_bf16 v[112:115], v[156:159], v[164:167], v[112:115]
	v_mfma_f32_16x16x32_bf16 v[100:103], v[144:147], v[168:171], v[100:103]
	v_mfma_f32_16x16x32_bf16 v[100:103], v[148:151], v[172:175], v[100:103]
	v_mfma_f32_16x16x32_bf16 v[96:99], v[152:155], v[168:171], v[96:99]
	v_mfma_f32_16x16x32_bf16 v[96:99], v[156:159], v[172:175], v[96:99]
	v_mfma_f32_16x16x32_bf16 v[84:87], v[144:147], v[176:179], v[84:87]
	v_mfma_f32_16x16x32_bf16 v[84:87], v[148:151], v[180:183], v[84:87]
	v_mfma_f32_16x16x32_bf16 v[80:83], v[152:155], v[176:179], v[80:83]
	v_mfma_f32_16x16x32_bf16 v[80:83], v[156:159], v[180:183], v[80:83]
	v_mfma_f32_16x16x32_bf16 v[68:71], v[144:147], v[184:187], v[68:71]
	v_mfma_f32_16x16x32_bf16 v[68:71], v[148:151], v[188:191], v[68:71]
	s_setprio 3
	s_barrier
	v_mfma_f32_16x16x32_bf16 v[64:67], v[152:155], v[184:187], v[64:67]
	v_mfma_f32_16x16x32_bf16 v[64:67], v[156:159], v[188:191], v[64:67]
	s_setprio 0
.Lzj_3_0:
	s_add_i32 s59, s26, s15
	v_lshl_add_u64 v[204:205], s[84:85], 0, v[194:195]
	s_mov_b32 m0, s59
	ds_read_b128 v[160:163], v247 offset:16384
	ds_read_b128 v[164:167], v247 offset:17408
	ds_read_b128 v[168:171], v247 offset:18432
	ds_read_b128 v[172:175], v247 offset:19456
	ds_read_b128 v[176:179], v247 offset:20480
	ds_read_b128 v[180:183], v247 offset:21504
	ds_read_b128 v[184:187], v247 offset:22528
	ds_read_b128 v[188:191], v247 offset:23552
	global_load_lds_dwordx4 v[204:205], off
	s_add_i32 m0, s59, 0x2000
	s_add_u32 s66, s84, 0x40000
	v_lshl_add_u64 v[206:207], s[84:85], 0, v[198:199]
	s_addc_u32 s67, s85, 0
	s_add_i32 s59, s27, s15
	global_load_lds_dwordx4 v[206:207], off
	v_lshl_add_u64 v[208:209], s[66:67], 0, v[194:195]
	s_mov_b32 m0, s59
	global_load_lds_dwordx4 v[208:209], off
	s_add_i32 m0, s59, 0x2000
	v_lshl_add_u64 v[208:209], s[66:67], 0, v[198:199]
	global_load_lds_dwordx4 v[208:209], off
	s_mov_b32 m0, s16
	v_lshl_add_u64 v[208:209], s[86:87], 0, v[192:193]
	global_load_lds_dwordx4 v[208:209], off
	s_mov_b32 m0, s17
	v_lshl_add_u64 v[210:211], s[86:87], 0, v[196:197]
	global_load_lds_dwordx4 v[210:211], off
	s_cmp_eq_u32 s58, -2
	s_waitcnt vmcnt(8) lgkmcnt(0)
	s_barrier
	s_setprio 1
	s_cbranch_scc1 .Lzv_3_1
	v_mfma_f32_16x16x32_bf16 v[60:63], v[120:123], v[160:163], v[60:63]
	v_mfma_f32_16x16x32_bf16 v[60:63], v[124:127], v[164:167], v[60:63]
	v_mfma_f32_16x16x32_bf16 v[56:59], v[128:131], v[160:163], v[56:59]
	v_mfma_f32_16x16x32_bf16 v[56:59], v[132:135], v[164:167], v[56:59]
	v_mfma_f32_16x16x32_bf16 v[44:47], v[120:123], v[168:171], v[44:47]
	v_mfma_f32_16x16x32_bf16 v[44:47], v[124:127], v[172:175], v[44:47]
	v_mfma_f32_16x16x32_bf16 v[40:43], v[128:131], v[168:171], v[40:43]
	v_mfma_f32_16x16x32_bf16 v[40:43], v[132:135], v[172:175], v[40:43]
	v_mfma_f32_16x16x32_bf16 v[28:31], v[120:123], v[176:179], v[28:31]
	v_mfma_f32_16x16x32_bf16 v[28:31], v[124:127], v[180:183], v[28:31]
	v_mfma_f32_16x16x32_bf16 v[24:27], v[128:131], v[176:179], v[24:27]
	v_mfma_f32_16x16x32_bf16 v[24:27], v[132:135], v[180:183], v[24:27]
	v_mfma_f32_16x16x32_bf16 v[12:15], v[120:123], v[184:187], v[12:15]
	v_mfma_f32_16x16x32_bf16 v[12:15], v[124:127], v[188:191], v[12:15]
	v_mfma_f32_16x16x32_bf16 v[8:11], v[128:131], v[184:187], v[8:11]
	v_mfma_f32_16x16x32_bf16 v[8:11], v[132:135], v[188:191], v[8:11]
	v_mfma_f32_16x16x32_bf16 v[52:55], v[144:147], v[160:163], v[52:55]
	v_mfma_f32_16x16x32_bf16 v[52:55], v[148:151], v[164:167], v[52:55]
	v_mfma_f32_16x16x32_bf16 v[48:51], v[152:155], v[160:163], v[48:51]
	v_mfma_f32_16x16x32_bf16 v[48:51], v[156:159], v[164:167], v[48:51]
	v_mfma_f32_16x16x32_bf16 v[36:39], v[144:147], v[168:171], v[36:39]
	v_mfma_f32_16x16x32_bf16 v[36:39], v[148:151], v[172:175], v[36:39]
	v_mfma_f32_16x16x32_bf16 v[32:35], v[152:155], v[168:171], v[32:35]
	v_mfma_f32_16x16x32_bf16 v[32:35], v[156:159], v[172:175], v[32:35]
	v_mfma_f32_16x16x32_bf16 v[20:23], v[144:147], v[176:179], v[20:23]
	v_mfma_f32_16x16x32_bf16 v[20:23], v[148:151], v[180:183], v[20:23]
	v_mfma_f32_16x16x32_bf16 v[16:19], v[152:155], v[176:179], v[16:19]
	v_mfma_f32_16x16x32_bf16 v[16:19], v[156:159], v[180:183], v[16:19]
	v_mfma_f32_16x16x32_bf16 v[4:7], v[144:147], v[184:187], v[4:7]
	v_mfma_f32_16x16x32_bf16 v[4:7], v[148:151], v[188:191], v[4:7]
	s_setprio 3
	s_barrier
	v_mfma_f32_16x16x32_bf16 v[0:3], v[152:155], v[184:187], v[0:3]
	v_mfma_f32_16x16x32_bf16 v[0:3], v[156:159], v[188:191], v[0:3]
	s_setprio 0
.Lzj_3_1:
	s_add_i32 s59, 0, 0x18000
	s_add_i32 s68, 0, 0x1c000
	v_add_u32_e32 v132, s59, v243
	v_add_u32_e32 v156, s68, v243
	ds_read_b128 v[120:123], v132
	ds_read_b128 v[124:127], v132 offset:1024
	ds_read_b128 v[128:131], v132 offset:2048
	ds_read_b128 v[132:135], v132 offset:3072
	ds_read_b128 v[144:147], v156
	ds_read_b128 v[148:151], v156 offset:1024
	ds_read_b128 v[152:155], v156 offset:2048
	ds_read_b128 v[156:159], v156 offset:3072
	s_add_u32 s66, s86, 0x40000
	s_addc_u32 s67, s87, 0
	s_mov_b32 m0, s18
	v_lshl_add_u64 v[212:213], s[66:67], 0, v[192:193]
	ds_read_b128 v[160:163], v247 offset:32768
	ds_read_b128 v[164:167], v247 offset:33792
	ds_read_b128 v[168:171], v247 offset:34816
	ds_read_b128 v[172:175], v247 offset:35840
	ds_read_b128 v[176:179], v247 offset:36864
	ds_read_b128 v[180:183], v247 offset:37888
	ds_read_b128 v[184:187], v247 offset:38912
	ds_read_b128 v[188:191], v247 offset:39936
	global_load_lds_dwordx4 v[212:213], off
	s_mov_b32 m0, s19
	v_lshl_add_u64 v[212:213], s[66:67], 0, v[196:197]
	global_load_lds_dwordx4 v[212:213], off
	s_waitcnt vmcnt(8) lgkmcnt(0)
	s_barrier
	s_setprio 1
	v_mfma_f32_16x16x32_bf16 v[140:143], v[120:123], v[160:163], v[140:143]
	v_mfma_f32_16x16x32_bf16 v[140:143], v[124:127], v[164:167], v[140:143]
	v_mfma_f32_16x16x32_bf16 v[136:139], v[128:131], v[160:163], v[136:139]
	v_mfma_f32_16x16x32_bf16 v[136:139], v[132:135], v[164:167], v[136:139]
	v_mfma_f32_16x16x32_bf16 v[108:111], v[120:123], v[168:171], v[108:111]
	v_mfma_f32_16x16x32_bf16 v[108:111], v[124:127], v[172:175], v[108:111]
	v_mfma_f32_16x16x32_bf16 v[104:107], v[128:131], v[168:171], v[104:107]
	v_mfma_f32_16x16x32_bf16 v[104:107], v[132:135], v[172:175], v[104:107]
	v_mfma_f32_16x16x32_bf16 v[92:95], v[120:123], v[176:179], v[92:95]
	v_mfma_f32_16x16x32_bf16 v[92:95], v[124:127], v[180:183], v[92:95]
	v_mfma_f32_16x16x32_bf16 v[88:91], v[128:131], v[176:179], v[88:91]
	v_mfma_f32_16x16x32_bf16 v[88:91], v[132:135], v[180:183], v[88:91]
	v_mfma_f32_16x16x32_bf16 v[76:79], v[120:123], v[184:187], v[76:79]
	v_mfma_f32_16x16x32_bf16 v[76:79], v[124:127], v[188:191], v[76:79]
	v_mfma_f32_16x16x32_bf16 v[72:75], v[128:131], v[184:187], v[72:75]
	v_mfma_f32_16x16x32_bf16 v[72:75], v[132:135], v[188:191], v[72:75]
	v_mfma_f32_16x16x32_bf16 v[116:119], v[144:147], v[160:163], v[116:119]
	v_mfma_f32_16x16x32_bf16 v[116:119], v[148:151], v[164:167], v[116:119]
	v_mfma_f32_16x16x32_bf16 v[112:115], v[152:155], v[160:163], v[112:115]
	v_mfma_f32_16x16x32_bf16 v[112:115], v[156:159], v[164:167], v[112:115]
	v_mfma_f32_16x16x32_bf16 v[100:103], v[144:147], v[168:171], v[100:103]
	v_mfma_f32_16x16x32_bf16 v[100:103], v[148:151], v[172:175], v[100:103]
	v_mfma_f32_16x16x32_bf16 v[96:99], v[152:155], v[168:171], v[96:99]
	v_mfma_f32_16x16x32_bf16 v[96:99], v[156:159], v[172:175], v[96:99]
	v_mfma_f32_16x16x32_bf16 v[84:87], v[144:147], v[176:179], v[84:87]
	v_mfma_f32_16x16x32_bf16 v[84:87], v[148:151], v[180:183], v[84:87]
	v_mfma_f32_16x16x32_bf16 v[80:83], v[152:155], v[176:179], v[80:83]
	v_mfma_f32_16x16x32_bf16 v[80:83], v[156:159], v[180:183], v[80:83]
	v_mfma_f32_16x16x32_bf16 v[68:71], v[144:147], v[184:187], v[68:71]
	v_mfma_f32_16x16x32_bf16 v[68:71], v[148:151], v[188:191], v[68:71]
	s_setprio 3
	s_barrier
	v_mfma_f32_16x16x32_bf16 v[64:67], v[152:155], v[184:187], v[64:67]
	v_mfma_f32_16x16x32_bf16 v[64:67], v[156:159], v[188:191], v[64:67]
	s_setprio 0
	s_add_i32 s59, s59, s15
	v_lshl_add_u64 v[204:205], v[204:205], 0, s[46:47]
	s_mov_b32 m0, s59
	ds_read_b128 v[160:163], v247 offset:49152
	ds_read_b128 v[164:167], v247 offset:50176
	ds_read_b128 v[168:171], v247 offset:51200
	ds_read_b128 v[172:175], v247 offset:52224
	ds_read_b128 v[176:179], v247 offset:53248
	ds_read_b128 v[180:183], v247 offset:54272
	ds_read_b128 v[184:187], v247 offset:55296
	ds_read_b128 v[188:191], v247 offset:56320
	global_load_lds_dwordx4 v[204:205], off
	s_add_i32 m0, s59, 0x2000
	s_add_u32 s66, s84, 0x40080
	v_lshl_add_u64 v[204:205], v[206:207], 0, s[46:47]
	s_addc_u32 s67, s85, 0
	s_add_i32 s59, s68, s15
	global_load_lds_dwordx4 v[204:205], off
	s_mov_b32 m0, s59
	v_lshl_add_u64 v[204:205], s[66:67], 0, v[194:195]
	global_load_lds_dwordx4 v[204:205], off
	s_add_i32 m0, s59, 0x2000
	v_lshl_add_u64 v[204:205], s[66:67], 0, v[198:199]
	global_load_lds_dwordx4 v[204:205], off
	s_mov_b32 m0, s21
	v_lshl_add_u64 v[204:205], v[208:209], 0, s[46:47]
	global_load_lds_dwordx4 v[204:205], off
	s_mov_b32 m0, s22
	v_lshl_add_u64 v[204:205], v[210:211], 0, s[46:47]
	global_load_lds_dwordx4 v[204:205], off
	s_waitcnt vmcnt(8) lgkmcnt(0)
	s_barrier
	s_setprio 1
	v_mfma_f32_16x16x32_bf16 v[60:63], v[120:123], v[160:163], v[60:63]
	v_mfma_f32_16x16x32_bf16 v[60:63], v[124:127], v[164:167], v[60:63]
	v_mfma_f32_16x16x32_bf16 v[56:59], v[128:131], v[160:163], v[56:59]
	v_mfma_f32_16x16x32_bf16 v[56:59], v[132:135], v[164:167], v[56:59]
	v_mfma_f32_16x16x32_bf16 v[44:47], v[120:123], v[168:171], v[44:47]
	v_mfma_f32_16x16x32_bf16 v[44:47], v[124:127], v[172:175], v[44:47]
	v_mfma_f32_16x16x32_bf16 v[40:43], v[128:131], v[168:171], v[40:43]
	v_mfma_f32_16x16x32_bf16 v[40:43], v[132:135], v[172:175], v[40:43]
	v_mfma_f32_16x16x32_bf16 v[28:31], v[120:123], v[176:179], v[28:31]
	v_mfma_f32_16x16x32_bf16 v[28:31], v[124:127], v[180:183], v[28:31]
	v_mfma_f32_16x16x32_bf16 v[24:27], v[128:131], v[176:179], v[24:27]
	v_mfma_f32_16x16x32_bf16 v[24:27], v[132:135], v[180:183], v[24:27]
	v_mfma_f32_16x16x32_bf16 v[12:15], v[120:123], v[184:187], v[12:15]
	v_mfma_f32_16x16x32_bf16 v[12:15], v[124:127], v[188:191], v[12:15]
	v_mfma_f32_16x16x32_bf16 v[8:11], v[128:131], v[184:187], v[8:11]
	v_mfma_f32_16x16x32_bf16 v[8:11], v[132:135], v[188:191], v[8:11]
	v_mfma_f32_16x16x32_bf16 v[52:55], v[144:147], v[160:163], v[52:55]
	v_mfma_f32_16x16x32_bf16 v[52:55], v[148:151], v[164:167], v[52:55]
	v_mfma_f32_16x16x32_bf16 v[48:51], v[152:155], v[160:163], v[48:51]
	v_mfma_f32_16x16x32_bf16 v[48:51], v[156:159], v[164:167], v[48:51]
	v_mfma_f32_16x16x32_bf16 v[36:39], v[144:147], v[168:171], v[36:39]
	v_mfma_f32_16x16x32_bf16 v[36:39], v[148:151], v[172:175], v[36:39]
	v_mfma_f32_16x16x32_bf16 v[32:35], v[152:155], v[168:171], v[32:35]
	v_mfma_f32_16x16x32_bf16 v[32:35], v[156:159], v[172:175], v[32:35]
	v_mfma_f32_16x16x32_bf16 v[20:23], v[144:147], v[176:179], v[20:23]
	v_mfma_f32_16x16x32_bf16 v[20:23], v[148:151], v[180:183], v[20:23]
	v_mfma_f32_16x16x32_bf16 v[16:19], v[152:155], v[176:179], v[16:19]
	v_mfma_f32_16x16x32_bf16 v[16:19], v[156:159], v[180:183], v[16:19]
	v_mfma_f32_16x16x32_bf16 v[4:7], v[144:147], v[184:187], v[4:7]
	v_mfma_f32_16x16x32_bf16 v[4:7], v[148:151], v[188:191], v[4:7]
	s_setprio 3
	s_barrier
	v_mfma_f32_16x16x32_bf16 v[0:3], v[152:155], v[184:187], v[0:3]
	v_mfma_f32_16x16x32_bf16 v[0:3], v[156:159], v[188:191], v[0:3]
	s_setprio 0
	s_add_i32 s58, s58, 2
	s_add_u32 s82, s82, 0x100
	s_addc_u32 s83, s83, 0
	s_add_u32 s56, s56, 0x100
	s_addc_u32 s57, s57, 0
	s_cmp_gt_u32 s58, 13
	s_cbranch_scc0 .LBB0_993
	s_branch .Lzskip_3

.LBB0_1148:
	ds_read_b128 v[146:149], v174
	ds_read_b128 v[150:153], v174 offset:1024
	ds_read_b128 v[154:157], v174 offset:2048
	ds_read_b128 v[158:161], v174 offset:3072
	ds_read_b128 v[162:165], v175
	ds_read_b128 v[178:181], v175 offset:1024
	ds_read_b128 v[182:185], v175 offset:2048
	ds_read_b128 v[186:189], v175 offset:3072
	s_add_u32 s67, s78, 0xfffc0080
	s_addc_u32 s68, s79, -1
	s_cmp_eq_u32 s66, 12
	s_cselect_b32 s83, s49, s68
	s_cselect_b32 s82, s54, s67
	s_cselect_b32 s81, s47, s59
	s_cselect_b32 s80, s55, s58
	v_lshl_add_u64 v[166:167], s[78:79], 0, v[136:137]
	s_add_i32 m0, s17, 0xc000
	ds_read_b128 v[190:193], v176
	ds_read_b128 v[194:197], v176 offset:1024
	ds_read_b128 v[198:201], v176 offset:2048
	ds_read_b128 v[202:205], v176 offset:3072
	ds_read_b128 v[206:209], v176 offset:4096
	ds_read_b128 v[210:213], v176 offset:5120
	ds_read_b128 v[214:217], v176 offset:6144
	ds_read_b128 v[218:221], v176 offset:7168
	global_load_lds_dwordx4 v[166:167], off
	s_add_i32 m0, s17, 0xe000
	v_lshl_add_u64 v[166:167], s[78:79], 0, v[140:141]
	global_load_lds_dwordx4 v[166:167], off
	s_cmp_eq_u32 s66, -2
	s_waitcnt vmcnt(8) lgkmcnt(0)
	s_barrier
	s_setprio 1
	s_cbranch_scc1 .Lzv_4_0
	v_mfma_f32_16x16x32_bf16 v[124:127], v[146:149], v[190:193], v[124:127]
	v_mfma_f32_16x16x32_bf16 v[124:127], v[150:153], v[194:197], v[124:127]
	v_mfma_f32_16x16x32_bf16 v[116:119], v[154:157], v[190:193], v[116:119]
	v_mfma_f32_16x16x32_bf16 v[116:119], v[158:161], v[194:197], v[116:119]
	v_mfma_f32_16x16x32_bf16 v[108:111], v[146:149], v[198:201], v[108:111]
	v_mfma_f32_16x16x32_bf16 v[108:111], v[150:153], v[202:205], v[108:111]
	v_mfma_f32_16x16x32_bf16 v[100:103], v[154:157], v[198:201], v[100:103]
	v_mfma_f32_16x16x32_bf16 v[100:103], v[158:161], v[202:205], v[100:103]
	v_mfma_f32_16x16x32_bf16 v[92:95], v[146:149], v[206:209], v[92:95]
	v_mfma_f32_16x16x32_bf16 v[92:95], v[150:153], v[210:213], v[92:95]
	v_mfma_f32_16x16x32_bf16 v[84:87], v[154:157], v[206:209], v[84:87]
	v_mfma_f32_16x16x32_bf16 v[84:87], v[158:161], v[210:213], v[84:87]
	v_mfma_f32_16x16x32_bf16 v[76:79], v[146:149], v[214:217], v[76:79]
	v_mfma_f32_16x16x32_bf16 v[76:79], v[150:153], v[218:221], v[76:79]
	v_mfma_f32_16x16x32_bf16 v[68:71], v[154:157], v[214:217], v[68:71]
	v_mfma_f32_16x16x32_bf16 v[68:71], v[158:161], v[218:221], v[68:71]
	v_mfma_f32_16x16x32_bf16 v[120:123], v[162:165], v[190:193], v[120:123]
	v_mfma_f32_16x16x32_bf16 v[120:123], v[178:181], v[194:197], v[120:123]
	v_mfma_f32_16x16x32_bf16 v[112:115], v[182:185], v[190:193], v[112:115]
	v_mfma_f32_16x16x32_bf16 v[112:115], v[186:189], v[194:197], v[112:115]
	v_mfma_f32_16x16x32_bf16 v[104:107], v[162:165], v[198:201], v[104:107]
	v_mfma_f32_16x16x32_bf16 v[104:107], v[178:181], v[202:205], v[104:107]
	v_mfma_f32_16x16x32_bf16 v[96:99], v[182:185], v[198:201], v[96:99]
	v_mfma_f32_16x16x32_bf16 v[96:99], v[186:189], v[202:205], v[96:99]
	v_mfma_f32_16x16x32_bf16 v[88:91], v[162:165], v[206:209], v[88:91]
	v_mfma_f32_16x16x32_bf16 v[88:91], v[178:181], v[210:213], v[88:91]
	v_mfma_f32_16x16x32_bf16 v[80:83], v[182:185], v[206:209], v[80:83]
	v_mfma_f32_16x16x32_bf16 v[80:83], v[186:189], v[210:213], v[80:83]
	v_mfma_f32_16x16x32_bf16 v[72:75], v[162:165], v[214:217], v[72:75]
	v_mfma_f32_16x16x32_bf16 v[72:75], v[178:181], v[218:221], v[72:75]
	s_setprio 3
	s_barrier
	v_mfma_f32_16x16x32_bf16 v[64:67], v[182:185], v[214:217], v[64:67]
	v_mfma_f32_16x16x32_bf16 v[64:67], v[186:189], v[218:221], v[64:67]
	s_setprio 0
.Lzj_4_0:
	s_add_i32 s67, s25, s16
	v_lshl_add_u64 v[166:167], s[80:81], 0, v[132:133]
	s_mov_b32 m0, s67
	ds_read_b128 v[190:193], v176 offset:16384
	ds_read_b128 v[194:197], v176 offset:17408
	ds_read_b128 v[198:201], v176 offset:18432
	ds_read_b128 v[202:205], v176 offset:19456
	ds_read_b128 v[206:209], v176 offset:20480
	ds_read_b128 v[210:213], v176 offset:21504
	ds_read_b128 v[214:217], v176 offset:22528
	ds_read_b128 v[218:221], v176 offset:23552
	global_load_lds_dwordx4 v[166:167], off
	s_add_i32 m0, s67, 0x2000
	s_add_u32 s68, s80, 0x40000
	v_lshl_add_u64 v[222:223], s[80:81], 0, v[128:129]
	s_addc_u32 s69, s81, 0
	s_add_i32 s67, s26, s16
	global_load_lds_dwordx4 v[222:223], off
	v_lshl_add_u64 v[224:225], s[68:69], 0, v[132:133]
	s_mov_b32 m0, s67
	global_load_lds_dwordx4 v[224:225], off
	s_add_i32 m0, s67, 0x2000
	v_lshl_add_u64 v[224:225], s[68:69], 0, v[128:129]
	global_load_lds_dwordx4 v[224:225], off
	s_mov_b32 m0, s17
	v_lshl_add_u64 v[224:225], s[82:83], 0, v[134:135]
	global_load_lds_dwordx4 v[224:225], off
	s_mov_b32 m0, s18
	v_lshl_add_u64 v[226:227], s[82:83], 0, v[130:131]
	global_load_lds_dwordx4 v[226:227], off
	s_cmp_eq_u32 s66, -2
	s_waitcnt vmcnt(8) lgkmcnt(0)
	s_barrier
	s_setprio 1
	s_cbranch_scc1 .Lzv_4_1
	v_mfma_f32_16x16x32_bf16 v[60:63], v[146:149], v[190:193], v[60:63]
	v_mfma_f32_16x16x32_bf16 v[60:63], v[150:153], v[194:197], v[60:63]
	v_mfma_f32_16x16x32_bf16 v[52:55], v[154:157], v[190:193], v[52:55]
	v_mfma_f32_16x16x32_bf16 v[52:55], v[158:161], v[194:197], v[52:55]
	v_mfma_f32_16x16x32_bf16 v[44:47], v[146:149], v[198:201], v[44:47]
	v_mfma_f32_16x16x32_bf16 v[44:47], v[150:153], v[202:205], v[44:47]
	v_mfma_f32_16x16x32_bf16 v[36:39], v[154:157], v[198:201], v[36:39]
	v_mfma_f32_16x16x32_bf16 v[36:39], v[158:161], v[202:205], v[36:39]
	v_mfma_f32_16x16x32_bf16 v[28:31], v[146:149], v[206:209], v[28:31]
	v_mfma_f32_16x16x32_bf16 v[28:31], v[150:153], v[210:213], v[28:31]
	v_mfma_f32_16x16x32_bf16 v[20:23], v[154:157], v[206:209], v[20:23]
	v_mfma_f32_16x16x32_bf16 v[20:23], v[158:161], v[210:213], v[20:23]
	v_mfma_f32_16x16x32_bf16 v[12:15], v[146:149], v[214:217], v[12:15]
	v_mfma_f32_16x16x32_bf16 v[12:15], v[150:153], v[218:221], v[12:15]
	v_mfma_f32_16x16x32_bf16 v[4:7], v[154:157], v[214:217], v[4:7]
	v_mfma_f32_16x16x32_bf16 v[4:7], v[158:161], v[218:221], v[4:7]
	v_mfma_f32_16x16x32_bf16 v[56:59], v[162:165], v[190:193], v[56:59]
	v_mfma_f32_16x16x32_bf16 v[56:59], v[178:181], v[194:197], v[56:59]
	v_mfma_f32_16x16x32_bf16 v[48:51], v[182:185], v[190:193], v[48:51]
	v_mfma_f32_16x16x32_bf16 v[48:51], v[186:189], v[194:197], v[48:51]
	v_mfma_f32_16x16x32_bf16 v[40:43], v[162:165], v[198:201], v[40:43]
	v_mfma_f32_16x16x32_bf16 v[40:43], v[178:181], v[202:205], v[40:43]
	v_mfma_f32_16x16x32_bf16 v[32:35], v[182:185], v[198:201], v[32:35]
	v_mfma_f32_16x16x32_bf16 v[32:35], v[186:189], v[202:205], v[32:35]
	v_mfma_f32_16x16x32_bf16 v[24:27], v[162:165], v[206:209], v[24:27]
	v_mfma_f32_16x16x32_bf16 v[24:27], v[178:181], v[210:213], v[24:27]
	v_mfma_f32_16x16x32_bf16 v[16:19], v[182:185], v[206:209], v[16:19]
	v_mfma_f32_16x16x32_bf16 v[16:19], v[186:189], v[210:213], v[16:19]
	v_mfma_f32_16x16x32_bf16 v[8:11], v[162:165], v[214:217], v[8:11]
	v_mfma_f32_16x16x32_bf16 v[8:11], v[178:181], v[218:221], v[8:11]
	s_setprio 3
	s_barrier
	v_mfma_f32_16x16x32_bf16 v[0:3], v[182:185], v[214:217], v[0:3]
	v_mfma_f32_16x16x32_bf16 v[0:3], v[186:189], v[218:221], v[0:3]
	s_setprio 0
.Lzj_4_1:
	s_add_i32 s67, 0, 0x18000
	s_add_i32 s73, 0, 0x1c000
	v_add_u32_e32 v158, s67, v171
	v_add_u32_e32 v186, s73, v171
	ds_read_b128 v[146:149], v158
	ds_read_b128 v[150:153], v158 offset:1024
	ds_read_b128 v[154:157], v158 offset:2048
	ds_read_b128 v[158:161], v158 offset:3072
	ds_read_b128 v[162:165], v186
	ds_read_b128 v[178:181], v186 offset:1024
	ds_read_b128 v[182:185], v186 offset:2048
	ds_read_b128 v[186:189], v186 offset:3072
	s_add_u32 s68, s82, 0x40000
	s_addc_u32 s69, s83, 0
	s_mov_b32 m0, s19
	v_lshl_add_u64 v[228:229], s[68:69], 0, v[134:135]
	ds_read_b128 v[190:193], v176 offset:32768
	ds_read_b128 v[194:197], v176 offset:33792
	ds_read_b128 v[198:201], v176 offset:34816
	ds_read_b128 v[202:205], v176 offset:35840
	ds_read_b128 v[206:209], v176 offset:36864
	ds_read_b128 v[210:213], v176 offset:37888
	ds_read_b128 v[214:217], v176 offset:38912
	ds_read_b128 v[218:221], v176 offset:39936
	global_load_lds_dwordx4 v[228:229], off
	s_mov_b32 m0, s20
	v_lshl_add_u64 v[228:229], s[68:69], 0, v[130:131]
	global_load_lds_dwordx4 v[228:229], off
	s_waitcnt vmcnt(8) lgkmcnt(0)
	s_barrier
	s_setprio 1
	v_mfma_f32_16x16x32_bf16 v[124:127], v[146:149], v[190:193], v[124:127]
	v_mfma_f32_16x16x32_bf16 v[124:127], v[150:153], v[194:197], v[124:127]
	v_mfma_f32_16x16x32_bf16 v[116:119], v[154:157], v[190:193], v[116:119]
	v_mfma_f32_16x16x32_bf16 v[116:119], v[158:161], v[194:197], v[116:119]
	v_mfma_f32_16x16x32_bf16 v[108:111], v[146:149], v[198:201], v[108:111]
	v_mfma_f32_16x16x32_bf16 v[108:111], v[150:153], v[202:205], v[108:111]
	v_mfma_f32_16x16x32_bf16 v[100:103], v[154:157], v[198:201], v[100:103]
	v_mfma_f32_16x16x32_bf16 v[100:103], v[158:161], v[202:205], v[100:103]
	v_mfma_f32_16x16x32_bf16 v[92:95], v[146:149], v[206:209], v[92:95]
	v_mfma_f32_16x16x32_bf16 v[92:95], v[150:153], v[210:213], v[92:95]
	v_mfma_f32_16x16x32_bf16 v[84:87], v[154:157], v[206:209], v[84:87]
	v_mfma_f32_16x16x32_bf16 v[84:87], v[158:161], v[210:213], v[84:87]
	v_mfma_f32_16x16x32_bf16 v[76:79], v[146:149], v[214:217], v[76:79]
	v_mfma_f32_16x16x32_bf16 v[76:79], v[150:153], v[218:221], v[76:79]
	v_mfma_f32_16x16x32_bf16 v[68:71], v[154:157], v[214:217], v[68:71]
	v_mfma_f32_16x16x32_bf16 v[68:71], v[158:161], v[218:221], v[68:71]
	v_mfma_f32_16x16x32_bf16 v[120:123], v[162:165], v[190:193], v[120:123]
	v_mfma_f32_16x16x32_bf16 v[120:123], v[178:181], v[194:197], v[120:123]
	v_mfma_f32_16x16x32_bf16 v[112:115], v[182:185], v[190:193], v[112:115]
	v_mfma_f32_16x16x32_bf16 v[112:115], v[186:189], v[194:197], v[112:115]
	v_mfma_f32_16x16x32_bf16 v[104:107], v[162:165], v[198:201], v[104:107]
	v_mfma_f32_16x16x32_bf16 v[104:107], v[178:181], v[202:205], v[104:107]
	v_mfma_f32_16x16x32_bf16 v[96:99], v[182:185], v[198:201], v[96:99]
	v_mfma_f32_16x16x32_bf16 v[96:99], v[186:189], v[202:205], v[96:99]
	v_mfma_f32_16x16x32_bf16 v[88:91], v[162:165], v[206:209], v[88:91]
	v_mfma_f32_16x16x32_bf16 v[88:91], v[178:181], v[210:213], v[88:91]
	v_mfma_f32_16x16x32_bf16 v[80:83], v[182:185], v[206:209], v[80:83]
	v_mfma_f32_16x16x32_bf16 v[80:83], v[186:189], v[210:213], v[80:83]
	v_mfma_f32_16x16x32_bf16 v[72:75], v[162:165], v[214:217], v[72:75]
	v_mfma_f32_16x16x32_bf16 v[72:75], v[178:181], v[218:221], v[72:75]
	s_setprio 3
	s_barrier
	v_mfma_f32_16x16x32_bf16 v[64:67], v[182:185], v[214:217], v[64:67]
	v_mfma_f32_16x16x32_bf16 v[64:67], v[186:189], v[218:221], v[64:67]
	s_setprio 0
	s_add_i32 s67, s67, s16
	v_lshl_add_u64 v[166:167], v[166:167], 0, s[10:11]
	s_mov_b32 m0, s67
	ds_read_b128 v[190:193], v176 offset:49152
	ds_read_b128 v[194:197], v176 offset:50176
	ds_read_b128 v[198:201], v176 offset:51200
	ds_read_b128 v[202:205], v176 offset:52224
	ds_read_b128 v[206:209], v176 offset:53248
	ds_read_b128 v[210:213], v176 offset:54272
	ds_read_b128 v[214:217], v176 offset:55296
	ds_read_b128 v[218:221], v176 offset:56320
	global_load_lds_dwordx4 v[166:167], off
	s_add_i32 m0, s67, 0x2000
	s_add_u32 s68, s80, 0x40080
	v_lshl_add_u64 v[166:167], v[222:223], 0, s[10:11]
	s_addc_u32 s69, s81, 0
	s_add_i32 s67, s73, s16
	global_load_lds_dwordx4 v[166:167], off
	s_mov_b32 m0, s67
	v_lshl_add_u64 v[166:167], s[68:69], 0, v[132:133]
	global_load_lds_dwordx4 v[166:167], off
	s_add_i32 m0, s67, 0x2000
	v_lshl_add_u64 v[166:167], s[68:69], 0, v[128:129]
	global_load_lds_dwordx4 v[166:167], off
	s_mov_b32 m0, s23
	v_lshl_add_u64 v[166:167], v[224:225], 0, s[10:11]
	global_load_lds_dwordx4 v[166:167], off
	s_mov_b32 m0, s24
	v_lshl_add_u64 v[166:167], v[226:227], 0, s[10:11]
	global_load_lds_dwordx4 v[166:167], off
	s_waitcnt vmcnt(8) lgkmcnt(0)
	s_barrier
	s_setprio 1
	v_mfma_f32_16x16x32_bf16 v[60:63], v[146:149], v[190:193], v[60:63]
	v_mfma_f32_16x16x32_bf16 v[60:63], v[150:153], v[194:197], v[60:63]
	v_mfma_f32_16x16x32_bf16 v[52:55], v[154:157], v[190:193], v[52:55]
	v_mfma_f32_16x16x32_bf16 v[52:55], v[158:161], v[194:197], v[52:55]
	v_mfma_f32_16x16x32_bf16 v[44:47], v[146:149], v[198:201], v[44:47]
	v_mfma_f32_16x16x32_bf16 v[44:47], v[150:153], v[202:205], v[44:47]
	v_mfma_f32_16x16x32_bf16 v[36:39], v[154:157], v[198:201], v[36:39]
	v_mfma_f32_16x16x32_bf16 v[36:39], v[158:161], v[202:205], v[36:39]
	v_mfma_f32_16x16x32_bf16 v[28:31], v[146:149], v[206:209], v[28:31]
	v_mfma_f32_16x16x32_bf16 v[28:31], v[150:153], v[210:213], v[28:31]
	v_mfma_f32_16x16x32_bf16 v[20:23], v[154:157], v[206:209], v[20:23]
	v_mfma_f32_16x16x32_bf16 v[20:23], v[158:161], v[210:213], v[20:23]
	v_mfma_f32_16x16x32_bf16 v[12:15], v[146:149], v[214:217], v[12:15]
	v_mfma_f32_16x16x32_bf16 v[12:15], v[150:153], v[218:221], v[12:15]
	v_mfma_f32_16x16x32_bf16 v[4:7], v[154:157], v[214:217], v[4:7]
	v_mfma_f32_16x16x32_bf16 v[4:7], v[158:161], v[218:221], v[4:7]
	v_mfma_f32_16x16x32_bf16 v[56:59], v[162:165], v[190:193], v[56:59]
	v_mfma_f32_16x16x32_bf16 v[56:59], v[178:181], v[194:197], v[56:59]
	v_mfma_f32_16x16x32_bf16 v[48:51], v[182:185], v[190:193], v[48:51]
	v_mfma_f32_16x16x32_bf16 v[48:51], v[186:189], v[194:197], v[48:51]
	v_mfma_f32_16x16x32_bf16 v[40:43], v[162:165], v[198:201], v[40:43]
	v_mfma_f32_16x16x32_bf16 v[40:43], v[178:181], v[202:205], v[40:43]
	v_mfma_f32_16x16x32_bf16 v[32:35], v[182:185], v[198:201], v[32:35]
	v_mfma_f32_16x16x32_bf16 v[32:35], v[186:189], v[202:205], v[32:35]
	v_mfma_f32_16x16x32_bf16 v[24:27], v[162:165], v[206:209], v[24:27]
	v_mfma_f32_16x16x32_bf16 v[24:27], v[178:181], v[210:213], v[24:27]
	v_mfma_f32_16x16x32_bf16 v[16:19], v[182:185], v[206:209], v[16:19]
	v_mfma_f32_16x16x32_bf16 v[16:19], v[186:189], v[210:213], v[16:19]
	v_mfma_f32_16x16x32_bf16 v[8:11], v[162:165], v[214:217], v[8:11]
	v_mfma_f32_16x16x32_bf16 v[8:11], v[178:181], v[218:221], v[8:11]
	s_setprio 3
	s_barrier
	v_mfma_f32_16x16x32_bf16 v[0:3], v[182:185], v[214:217], v[0:3]
	v_mfma_f32_16x16x32_bf16 v[0:3], v[186:189], v[218:221], v[0:3]
	s_setprio 0
	s_add_i32 s66, s66, 2
	s_add_u32 s78, s78, 0x100
	s_addc_u32 s79, s79, 0
	s_add_u32 s58, s58, 0x100
	s_addc_u32 s59, s59, 0
	s_cmp_gt_u32 s66, 13
	s_cbranch_scc0 .LBB0_1148
	s_branch .Lzskip_4

.LBB0_1299:
	ds_read_b128 v[120:123], v245
	ds_read_b128 v[124:127], v245 offset:1024
	ds_read_b128 v[128:131], v245 offset:2048
	ds_read_b128 v[132:135], v245 offset:3072
	ds_read_b128 v[144:147], v246
	ds_read_b128 v[148:151], v246 offset:1024
	ds_read_b128 v[152:155], v246 offset:2048
	ds_read_b128 v[156:159], v246 offset:3072
	s_add_u32 s66, s76, 0xfff50080
	s_addc_u32 s67, s77, -1
	s_cmp_eq_u32 s59, 40
	s_cselect_b32 s81, s9, s67
	s_cselect_b32 s80, s8, s66
	s_cselect_b32 s79, s53, s58
	s_cselect_b32 s78, s52, s55
	v_lshl_add_u64 v[204:205], s[76:77], 0, v[200:201]
	s_add_i32 m0, s16, 0xc000
	ds_read_b128 v[160:163], v247
	ds_read_b128 v[164:167], v247 offset:1024
	ds_read_b128 v[168:171], v247 offset:2048
	ds_read_b128 v[172:175], v247 offset:3072
	ds_read_b128 v[176:179], v247 offset:4096
	ds_read_b128 v[180:183], v247 offset:5120
	ds_read_b128 v[184:187], v247 offset:6144
	ds_read_b128 v[188:191], v247 offset:7168
	global_load_lds_dwordx4 v[204:205], off
	s_add_i32 m0, s16, 0xe000
	v_lshl_add_u64 v[204:205], s[76:77], 0, v[202:203]
	global_load_lds_dwordx4 v[204:205], off
	s_cmp_eq_u32 s59, -2
	s_waitcnt vmcnt(8) lgkmcnt(0)
	s_barrier
	s_setprio 1
	s_cbranch_scc1 .Lzv_5_0
	v_mfma_f32_16x16x32_bf16 v[140:143], v[120:123], v[160:163], v[140:143]
	v_mfma_f32_16x16x32_bf16 v[140:143], v[124:127], v[164:167], v[140:143]
	v_mfma_f32_16x16x32_bf16 v[136:139], v[128:131], v[160:163], v[136:139]
	v_mfma_f32_16x16x32_bf16 v[136:139], v[132:135], v[164:167], v[136:139]
	v_mfma_f32_16x16x32_bf16 v[108:111], v[120:123], v[168:171], v[108:111]
	v_mfma_f32_16x16x32_bf16 v[108:111], v[124:127], v[172:175], v[108:111]
	v_mfma_f32_16x16x32_bf16 v[104:107], v[128:131], v[168:171], v[104:107]
	v_mfma_f32_16x16x32_bf16 v[104:107], v[132:135], v[172:175], v[104:107]
	v_mfma_f32_16x16x32_bf16 v[92:95], v[120:123], v[176:179], v[92:95]
	v_mfma_f32_16x16x32_bf16 v[92:95], v[124:127], v[180:183], v[92:95]
	v_mfma_f32_16x16x32_bf16 v[88:91], v[128:131], v[176:179], v[88:91]
	v_mfma_f32_16x16x32_bf16 v[88:91], v[132:135], v[180:183], v[88:91]
	v_mfma_f32_16x16x32_bf16 v[76:79], v[120:123], v[184:187], v[76:79]
	v_mfma_f32_16x16x32_bf16 v[76:79], v[124:127], v[188:191], v[76:79]
	v_mfma_f32_16x16x32_bf16 v[72:75], v[128:131], v[184:187], v[72:75]
	v_mfma_f32_16x16x32_bf16 v[72:75], v[132:135], v[188:191], v[72:75]
	v_mfma_f32_16x16x32_bf16 v[116:119], v[144:147], v[160:163], v[116:119]
	v_mfma_f32_16x16x32_bf16 v[116:119], v[148:151], v[164:167], v[116:119]
	v_mfma_f32_16x16x32_bf16 v[112:115], v[152:155], v[160:163], v[112:115]
	v_mfma_f32_16x16x32_bf16 v[112:115], v[156:159], v[164:167], v[112:115]
	v_mfma_f32_16x16x32_bf16 v[100:103], v[144:147], v[168:171], v[100:103]
	v_mfma_f32_16x16x32_bf16 v[100:103], v[148:151], v[172:175], v[100:103]
	v_mfma_f32_16x16x32_bf16 v[96:99], v[152:155], v[168:171], v[96:99]
	v_mfma_f32_16x16x32_bf16 v[96:99], v[156:159], v[172:175], v[96:99]
	v_mfma_f32_16x16x32_bf16 v[84:87], v[144:147], v[176:179], v[84:87]
	v_mfma_f32_16x16x32_bf16 v[84:87], v[148:151], v[180:183], v[84:87]
	v_mfma_f32_16x16x32_bf16 v[80:83], v[152:155], v[176:179], v[80:83]
	v_mfma_f32_16x16x32_bf16 v[80:83], v[156:159], v[180:183], v[80:83]
	v_mfma_f32_16x16x32_bf16 v[68:71], v[144:147], v[184:187], v[68:71]
	v_mfma_f32_16x16x32_bf16 v[68:71], v[148:151], v[188:191], v[68:71]
	s_setprio 3
	s_barrier
	v_mfma_f32_16x16x32_bf16 v[64:67], v[152:155], v[184:187], v[64:67]
	v_mfma_f32_16x16x32_bf16 v[64:67], v[156:159], v[188:191], v[64:67]
	s_setprio 0
.Lzj_5_0:
	s_add_i32 s66, s26, s15
	v_lshl_add_u64 v[204:205], s[78:79], 0, v[194:195]
	s_mov_b32 m0, s66
	ds_read_b128 v[160:163], v247 offset:16384
	ds_read_b128 v[164:167], v247 offset:17408
	ds_read_b128 v[168:171], v247 offset:18432
	ds_read_b128 v[172:175], v247 offset:19456
	ds_read_b128 v[176:179], v247 offset:20480
	ds_read_b128 v[180:183], v247 offset:21504
	ds_read_b128 v[184:187], v247 offset:22528
	ds_read_b128 v[188:191], v247 offset:23552
	global_load_lds_dwordx4 v[204:205], off
	s_add_i32 m0, s66, 0x2000
	s_add_u32 s66, s78, 0xb0000
	v_lshl_add_u64 v[206:207], s[78:79], 0, v[198:199]
	s_addc_u32 s67, s79, 0
	s_add_i32 s68, s27, s15
	global_load_lds_dwordx4 v[206:207], off
	v_lshl_add_u64 v[208:209], s[66:67], 0, v[194:195]
	s_mov_b32 m0, s68
	global_load_lds_dwordx4 v[208:209], off
	s_add_i32 m0, s68, 0x2000
	v_lshl_add_u64 v[208:209], s[66:67], 0, v[198:199]
	global_load_lds_dwordx4 v[208:209], off
	s_mov_b32 m0, s16
	v_lshl_add_u64 v[208:209], s[80:81], 0, v[192:193]
	global_load_lds_dwordx4 v[208:209], off
	s_mov_b32 m0, s17
	v_lshl_add_u64 v[210:211], s[80:81], 0, v[196:197]
	global_load_lds_dwordx4 v[210:211], off
	s_cmp_eq_u32 s59, -2
	s_waitcnt vmcnt(8) lgkmcnt(0)
	s_barrier
	s_setprio 1
	s_cbranch_scc1 .Lzv_5_1
	v_mfma_f32_16x16x32_bf16 v[60:63], v[120:123], v[160:163], v[60:63]
	v_mfma_f32_16x16x32_bf16 v[60:63], v[124:127], v[164:167], v[60:63]
	v_mfma_f32_16x16x32_bf16 v[56:59], v[128:131], v[160:163], v[56:59]
	v_mfma_f32_16x16x32_bf16 v[56:59], v[132:135], v[164:167], v[56:59]
	v_mfma_f32_16x16x32_bf16 v[44:47], v[120:123], v[168:171], v[44:47]
	v_mfma_f32_16x16x32_bf16 v[44:47], v[124:127], v[172:175], v[44:47]
	v_mfma_f32_16x16x32_bf16 v[40:43], v[128:131], v[168:171], v[40:43]
	v_mfma_f32_16x16x32_bf16 v[40:43], v[132:135], v[172:175], v[40:43]
	v_mfma_f32_16x16x32_bf16 v[28:31], v[120:123], v[176:179], v[28:31]
	v_mfma_f32_16x16x32_bf16 v[28:31], v[124:127], v[180:183], v[28:31]
	v_mfma_f32_16x16x32_bf16 v[24:27], v[128:131], v[176:179], v[24:27]
	v_mfma_f32_16x16x32_bf16 v[24:27], v[132:135], v[180:183], v[24:27]
	v_mfma_f32_16x16x32_bf16 v[12:15], v[120:123], v[184:187], v[12:15]
	v_mfma_f32_16x16x32_bf16 v[12:15], v[124:127], v[188:191], v[12:15]
	v_mfma_f32_16x16x32_bf16 v[8:11], v[128:131], v[184:187], v[8:11]
	v_mfma_f32_16x16x32_bf16 v[8:11], v[132:135], v[188:191], v[8:11]
	v_mfma_f32_16x16x32_bf16 v[52:55], v[144:147], v[160:163], v[52:55]
	v_mfma_f32_16x16x32_bf16 v[52:55], v[148:151], v[164:167], v[52:55]
	v_mfma_f32_16x16x32_bf16 v[48:51], v[152:155], v[160:163], v[48:51]
	v_mfma_f32_16x16x32_bf16 v[48:51], v[156:159], v[164:167], v[48:51]
	v_mfma_f32_16x16x32_bf16 v[36:39], v[144:147], v[168:171], v[36:39]
	v_mfma_f32_16x16x32_bf16 v[36:39], v[148:151], v[172:175], v[36:39]
	v_mfma_f32_16x16x32_bf16 v[32:35], v[152:155], v[168:171], v[32:35]
	v_mfma_f32_16x16x32_bf16 v[32:35], v[156:159], v[172:175], v[32:35]
	v_mfma_f32_16x16x32_bf16 v[20:23], v[144:147], v[176:179], v[20:23]
	v_mfma_f32_16x16x32_bf16 v[20:23], v[148:151], v[180:183], v[20:23]
	v_mfma_f32_16x16x32_bf16 v[16:19], v[152:155], v[176:179], v[16:19]
	v_mfma_f32_16x16x32_bf16 v[16:19], v[156:159], v[180:183], v[16:19]
	v_mfma_f32_16x16x32_bf16 v[4:7], v[144:147], v[184:187], v[4:7]
	v_mfma_f32_16x16x32_bf16 v[4:7], v[148:151], v[188:191], v[4:7]
	s_setprio 3
	s_barrier
	v_mfma_f32_16x16x32_bf16 v[0:3], v[152:155], v[184:187], v[0:3]
	v_mfma_f32_16x16x32_bf16 v[0:3], v[156:159], v[188:191], v[0:3]
	s_setprio 0
.Lzj_5_1:
	s_add_i32 s68, 0, 0x18000
	s_add_i32 s69, 0, 0x1c000
	v_add_u32_e32 v132, s68, v243
	v_add_u32_e32 v156, s69, v243
	ds_read_b128 v[120:123], v132
	ds_read_b128 v[124:127], v132 offset:1024
	ds_read_b128 v[128:131], v132 offset:2048
	ds_read_b128 v[132:135], v132 offset:3072
	ds_read_b128 v[144:147], v156
	ds_read_b128 v[148:151], v156 offset:1024
	ds_read_b128 v[152:155], v156 offset:2048
	ds_read_b128 v[156:159], v156 offset:3072
	s_add_u32 s66, s80, 0xb0000
	s_addc_u32 s67, s81, 0
	s_mov_b32 m0, s18
	v_lshl_add_u64 v[212:213], s[66:67], 0, v[192:193]
	ds_read_b128 v[160:163], v247 offset:32768
	ds_read_b128 v[164:167], v247 offset:33792
	ds_read_b128 v[168:171], v247 offset:34816
	ds_read_b128 v[172:175], v247 offset:35840
	ds_read_b128 v[176:179], v247 offset:36864
	ds_read_b128 v[180:183], v247 offset:37888
	ds_read_b128 v[184:187], v247 offset:38912
	ds_read_b128 v[188:191], v247 offset:39936
	global_load_lds_dwordx4 v[212:213], off
	s_mov_b32 m0, s19
	v_lshl_add_u64 v[212:213], s[66:67], 0, v[196:197]
	global_load_lds_dwordx4 v[212:213], off
	s_waitcnt vmcnt(8) lgkmcnt(0)
	s_barrier
	s_setprio 1
	v_mfma_f32_16x16x32_bf16 v[140:143], v[120:123], v[160:163], v[140:143]
	v_mfma_f32_16x16x32_bf16 v[140:143], v[124:127], v[164:167], v[140:143]
	v_mfma_f32_16x16x32_bf16 v[136:139], v[128:131], v[160:163], v[136:139]
	v_mfma_f32_16x16x32_bf16 v[136:139], v[132:135], v[164:167], v[136:139]
	v_mfma_f32_16x16x32_bf16 v[108:111], v[120:123], v[168:171], v[108:111]
	v_mfma_f32_16x16x32_bf16 v[108:111], v[124:127], v[172:175], v[108:111]
	v_mfma_f32_16x16x32_bf16 v[104:107], v[128:131], v[168:171], v[104:107]
	v_mfma_f32_16x16x32_bf16 v[104:107], v[132:135], v[172:175], v[104:107]
	v_mfma_f32_16x16x32_bf16 v[92:95], v[120:123], v[176:179], v[92:95]
	v_mfma_f32_16x16x32_bf16 v[92:95], v[124:127], v[180:183], v[92:95]
	v_mfma_f32_16x16x32_bf16 v[88:91], v[128:131], v[176:179], v[88:91]
	v_mfma_f32_16x16x32_bf16 v[88:91], v[132:135], v[180:183], v[88:91]
	v_mfma_f32_16x16x32_bf16 v[76:79], v[120:123], v[184:187], v[76:79]
	v_mfma_f32_16x16x32_bf16 v[76:79], v[124:127], v[188:191], v[76:79]
	v_mfma_f32_16x16x32_bf16 v[72:75], v[128:131], v[184:187], v[72:75]
	v_mfma_f32_16x16x32_bf16 v[72:75], v[132:135], v[188:191], v[72:75]
	v_mfma_f32_16x16x32_bf16 v[116:119], v[144:147], v[160:163], v[116:119]
	v_mfma_f32_16x16x32_bf16 v[116:119], v[148:151], v[164:167], v[116:119]
	v_mfma_f32_16x16x32_bf16 v[112:115], v[152:155], v[160:163], v[112:115]
	v_mfma_f32_16x16x32_bf16 v[112:115], v[156:159], v[164:167], v[112:115]
	v_mfma_f32_16x16x32_bf16 v[100:103], v[144:147], v[168:171], v[100:103]
	v_mfma_f32_16x16x32_bf16 v[100:103], v[148:151], v[172:175], v[100:103]
	v_mfma_f32_16x16x32_bf16 v[96:99], v[152:155], v[168:171], v[96:99]
	v_mfma_f32_16x16x32_bf16 v[96:99], v[156:159], v[172:175], v[96:99]
	v_mfma_f32_16x16x32_bf16 v[84:87], v[144:147], v[176:179], v[84:87]
	v_mfma_f32_16x16x32_bf16 v[84:87], v[148:151], v[180:183], v[84:87]
	v_mfma_f32_16x16x32_bf16 v[80:83], v[152:155], v[176:179], v[80:83]
	v_mfma_f32_16x16x32_bf16 v[80:83], v[156:159], v[180:183], v[80:83]
	v_mfma_f32_16x16x32_bf16 v[68:71], v[144:147], v[184:187], v[68:71]
	v_mfma_f32_16x16x32_bf16 v[68:71], v[148:151], v[188:191], v[68:71]
	s_setprio 3
	s_barrier
	v_mfma_f32_16x16x32_bf16 v[64:67], v[152:155], v[184:187], v[64:67]
	v_mfma_f32_16x16x32_bf16 v[64:67], v[156:159], v[188:191], v[64:67]
	s_setprio 0
	s_add_i32 s66, s68, s15
	v_lshl_add_u64 v[204:205], v[204:205], 0, s[48:49]
	s_mov_b32 m0, s66
	ds_read_b128 v[160:163], v247 offset:49152
	ds_read_b128 v[164:167], v247 offset:50176
	ds_read_b128 v[168:171], v247 offset:51200
	ds_read_b128 v[172:175], v247 offset:52224
	ds_read_b128 v[176:179], v247 offset:53248
	ds_read_b128 v[180:183], v247 offset:54272
	ds_read_b128 v[184:187], v247 offset:55296
	ds_read_b128 v[188:191], v247 offset:56320
	global_load_lds_dwordx4 v[204:205], off
	s_add_i32 m0, s66, 0x2000
	s_add_u32 s66, s78, 0xb0080
	v_lshl_add_u64 v[204:205], v[206:207], 0, s[48:49]
	s_addc_u32 s67, s79, 0
	s_add_i32 s68, s69, s15
	global_load_lds_dwordx4 v[204:205], off
	s_mov_b32 m0, s68
	v_lshl_add_u64 v[204:205], s[66:67], 0, v[194:195]
	global_load_lds_dwordx4 v[204:205], off
	s_add_i32 m0, s68, 0x2000
	v_lshl_add_u64 v[204:205], s[66:67], 0, v[198:199]
	global_load_lds_dwordx4 v[204:205], off
	s_mov_b32 m0, s21
	v_lshl_add_u64 v[204:205], v[208:209], 0, s[48:49]
	global_load_lds_dwordx4 v[204:205], off
	s_mov_b32 m0, s22
	v_lshl_add_u64 v[204:205], v[210:211], 0, s[48:49]
	global_load_lds_dwordx4 v[204:205], off
	s_waitcnt vmcnt(8) lgkmcnt(0)
	s_barrier
	s_setprio 1
	v_mfma_f32_16x16x32_bf16 v[60:63], v[120:123], v[160:163], v[60:63]
	v_mfma_f32_16x16x32_bf16 v[60:63], v[124:127], v[164:167], v[60:63]
	v_mfma_f32_16x16x32_bf16 v[56:59], v[128:131], v[160:163], v[56:59]
	v_mfma_f32_16x16x32_bf16 v[56:59], v[132:135], v[164:167], v[56:59]
	v_mfma_f32_16x16x32_bf16 v[44:47], v[120:123], v[168:171], v[44:47]
	v_mfma_f32_16x16x32_bf16 v[44:47], v[124:127], v[172:175], v[44:47]
	v_mfma_f32_16x16x32_bf16 v[40:43], v[128:131], v[168:171], v[40:43]
	v_mfma_f32_16x16x32_bf16 v[40:43], v[132:135], v[172:175], v[40:43]
	v_mfma_f32_16x16x32_bf16 v[28:31], v[120:123], v[176:179], v[28:31]
	v_mfma_f32_16x16x32_bf16 v[28:31], v[124:127], v[180:183], v[28:31]
	v_mfma_f32_16x16x32_bf16 v[24:27], v[128:131], v[176:179], v[24:27]
	v_mfma_f32_16x16x32_bf16 v[24:27], v[132:135], v[180:183], v[24:27]
	v_mfma_f32_16x16x32_bf16 v[12:15], v[120:123], v[184:187], v[12:15]
	v_mfma_f32_16x16x32_bf16 v[12:15], v[124:127], v[188:191], v[12:15]
	v_mfma_f32_16x16x32_bf16 v[8:11], v[128:131], v[184:187], v[8:11]
	v_mfma_f32_16x16x32_bf16 v[8:11], v[132:135], v[188:191], v[8:11]
	v_mfma_f32_16x16x32_bf16 v[52:55], v[144:147], v[160:163], v[52:55]
	v_mfma_f32_16x16x32_bf16 v[52:55], v[148:151], v[164:167], v[52:55]
	v_mfma_f32_16x16x32_bf16 v[48:51], v[152:155], v[160:163], v[48:51]
	v_mfma_f32_16x16x32_bf16 v[48:51], v[156:159], v[164:167], v[48:51]
	v_mfma_f32_16x16x32_bf16 v[36:39], v[144:147], v[168:171], v[36:39]
	v_mfma_f32_16x16x32_bf16 v[36:39], v[148:151], v[172:175], v[36:39]
	v_mfma_f32_16x16x32_bf16 v[32:35], v[152:155], v[168:171], v[32:35]
	v_mfma_f32_16x16x32_bf16 v[32:35], v[156:159], v[172:175], v[32:35]
	v_mfma_f32_16x16x32_bf16 v[20:23], v[144:147], v[176:179], v[20:23]
	v_mfma_f32_16x16x32_bf16 v[20:23], v[148:151], v[180:183], v[20:23]
	v_mfma_f32_16x16x32_bf16 v[16:19], v[152:155], v[176:179], v[16:19]
	v_mfma_f32_16x16x32_bf16 v[16:19], v[156:159], v[180:183], v[16:19]
	v_mfma_f32_16x16x32_bf16 v[4:7], v[144:147], v[184:187], v[4:7]
	v_mfma_f32_16x16x32_bf16 v[4:7], v[148:151], v[188:191], v[4:7]
	s_setprio 3
	s_barrier
	v_mfma_f32_16x16x32_bf16 v[0:3], v[152:155], v[184:187], v[0:3]
	v_mfma_f32_16x16x32_bf16 v[0:3], v[156:159], v[188:191], v[0:3]
	s_setprio 0
	s_add_i32 s59, s59, 2
	s_add_u32 s76, s76, 0x100
	s_addc_u32 s77, s77, 0
	s_add_u32 s55, s55, 0x100
	s_addc_u32 s58, s58, 0
	s_cmp_gt_u32 s59, 41
	s_cbranch_scc0 .LBB0_1299
	s_branch .Lzskip_5

.LBB0_1760:
	ds_read_b128 v[128:131], v181
	ds_read_b128 v[132:135], v181 offset:1024
	ds_read_b128 v[136:139], v181 offset:2048
	ds_read_b128 v[160:163], v181 offset:3072
	ds_read_b128 v[164:167], v182
	ds_read_b128 v[168:171], v182 offset:1024
	ds_read_b128 v[186:189], v182 offset:2048
	ds_read_b128 v[190:193], v182 offset:3072
	s_add_u32 s69, s78, 0xfffc0080
	s_addc_u32 s73, s79, -1
	s_cmp_eq_u32 s68, 12
	s_cselect_b32 s83, s49, s73
	s_cselect_b32 s82, s54, s69
	s_cselect_b32 s81, s47, s67
	s_cselect_b32 s80, s55, s66
	v_lshl_add_u64 v[172:173], s[78:79], 0, v[152:153]
	s_add_i32 m0, s18, 0xc000
	ds_read_b128 v[194:197], v183
	ds_read_b128 v[198:201], v183 offset:1024
	ds_read_b128 v[202:205], v183 offset:2048
	ds_read_b128 v[206:209], v183 offset:3072
	ds_read_b128 v[210:213], v183 offset:4096
	ds_read_b128 v[214:217], v183 offset:5120
	ds_read_b128 v[218:221], v183 offset:6144
	ds_read_b128 v[222:225], v183 offset:7168
	global_load_lds_dwordx4 v[172:173], off
	s_add_i32 m0, s18, 0xe000
	v_lshl_add_u64 v[172:173], s[78:79], 0, v[154:155]
	global_load_lds_dwordx4 v[172:173], off
	s_cmp_eq_u32 s68, -2
	s_waitcnt vmcnt(8) lgkmcnt(0)
	s_barrier
	s_setprio 1
	s_cbranch_scc1 .Lzv_8_0
	v_mfma_f32_16x16x32_bf16 v[124:127], v[128:131], v[194:197], v[124:127]
	v_mfma_f32_16x16x32_bf16 v[124:127], v[132:135], v[198:201], v[124:127]
	v_mfma_f32_16x16x32_bf16 v[120:123], v[136:139], v[194:197], v[120:123]
	v_mfma_f32_16x16x32_bf16 v[120:123], v[160:163], v[198:201], v[120:123]
	v_mfma_f32_16x16x32_bf16 v[108:111], v[128:131], v[202:205], v[108:111]
	v_mfma_f32_16x16x32_bf16 v[108:111], v[132:135], v[206:209], v[108:111]
	v_mfma_f32_16x16x32_bf16 v[104:107], v[136:139], v[202:205], v[104:107]
	v_mfma_f32_16x16x32_bf16 v[104:107], v[160:163], v[206:209], v[104:107]
	v_mfma_f32_16x16x32_bf16 v[92:95], v[128:131], v[210:213], v[92:95]
	v_mfma_f32_16x16x32_bf16 v[92:95], v[132:135], v[214:217], v[92:95]
	v_mfma_f32_16x16x32_bf16 v[88:91], v[136:139], v[210:213], v[88:91]
	v_mfma_f32_16x16x32_bf16 v[88:91], v[160:163], v[214:217], v[88:91]
	v_mfma_f32_16x16x32_bf16 v[76:79], v[128:131], v[218:221], v[76:79]
	v_mfma_f32_16x16x32_bf16 v[76:79], v[132:135], v[222:225], v[76:79]
	v_mfma_f32_16x16x32_bf16 v[72:75], v[136:139], v[218:221], v[72:75]
	v_mfma_f32_16x16x32_bf16 v[72:75], v[160:163], v[222:225], v[72:75]
	v_mfma_f32_16x16x32_bf16 v[116:119], v[164:167], v[194:197], v[116:119]
	v_mfma_f32_16x16x32_bf16 v[116:119], v[168:171], v[198:201], v[116:119]
	v_mfma_f32_16x16x32_bf16 v[112:115], v[186:189], v[194:197], v[112:115]
	v_mfma_f32_16x16x32_bf16 v[112:115], v[190:193], v[198:201], v[112:115]
	v_mfma_f32_16x16x32_bf16 v[100:103], v[164:167], v[202:205], v[100:103]
	v_mfma_f32_16x16x32_bf16 v[100:103], v[168:171], v[206:209], v[100:103]
	v_mfma_f32_16x16x32_bf16 v[96:99], v[186:189], v[202:205], v[96:99]
	v_mfma_f32_16x16x32_bf16 v[96:99], v[190:193], v[206:209], v[96:99]
	v_mfma_f32_16x16x32_bf16 v[84:87], v[164:167], v[210:213], v[84:87]
	v_mfma_f32_16x16x32_bf16 v[84:87], v[168:171], v[214:217], v[84:87]
	v_mfma_f32_16x16x32_bf16 v[80:83], v[186:189], v[210:213], v[80:83]
	v_mfma_f32_16x16x32_bf16 v[80:83], v[190:193], v[214:217], v[80:83]
	v_mfma_f32_16x16x32_bf16 v[68:71], v[164:167], v[218:221], v[68:71]
	v_mfma_f32_16x16x32_bf16 v[68:71], v[168:171], v[222:225], v[68:71]
	s_setprio 3
	s_barrier
	v_mfma_f32_16x16x32_bf16 v[64:67], v[186:189], v[218:221], v[64:67]
	v_mfma_f32_16x16x32_bf16 v[64:67], v[190:193], v[222:225], v[64:67]
	s_setprio 0
.Lzj_8_0:
	s_add_i32 s69, s25, s17
	v_lshl_add_u64 v[172:173], s[80:81], 0, v[142:143]
	s_mov_b32 m0, s69
	ds_read_b128 v[194:197], v183 offset:16384
	ds_read_b128 v[198:201], v183 offset:17408
	ds_read_b128 v[202:205], v183 offset:18432
	ds_read_b128 v[206:209], v183 offset:19456
	ds_read_b128 v[210:213], v183 offset:20480
	ds_read_b128 v[214:217], v183 offset:21504
	ds_read_b128 v[218:221], v183 offset:22528
	ds_read_b128 v[222:225], v183 offset:23552
	global_load_lds_dwordx4 v[172:173], off
	s_add_i32 m0, s69, 0x2000
	s_add_u32 s84, s80, 0x40000
	v_lshl_add_u64 v[226:227], s[80:81], 0, v[146:147]
	s_addc_u32 s85, s81, 0
	s_add_i32 s69, s26, s17
	global_load_lds_dwordx4 v[226:227], off
	v_lshl_add_u64 v[228:229], s[84:85], 0, v[142:143]
	s_mov_b32 m0, s69
	global_load_lds_dwordx4 v[228:229], off
	s_add_i32 m0, s69, 0x2000
	v_lshl_add_u64 v[228:229], s[84:85], 0, v[146:147]
	global_load_lds_dwordx4 v[228:229], off
	s_mov_b32 m0, s18
	v_lshl_add_u64 v[228:229], s[82:83], 0, v[140:141]
	global_load_lds_dwordx4 v[228:229], off
	s_mov_b32 m0, s19
	v_lshl_add_u64 v[230:231], s[82:83], 0, v[144:145]
	global_load_lds_dwordx4 v[230:231], off
	s_cmp_eq_u32 s68, -2
	s_waitcnt vmcnt(8) lgkmcnt(0)
	s_barrier
	s_setprio 1
	s_cbranch_scc1 .Lzv_8_1
	v_mfma_f32_16x16x32_bf16 v[60:63], v[128:131], v[194:197], v[60:63]
	v_mfma_f32_16x16x32_bf16 v[60:63], v[132:135], v[198:201], v[60:63]
	v_mfma_f32_16x16x32_bf16 v[56:59], v[136:139], v[194:197], v[56:59]
	v_mfma_f32_16x16x32_bf16 v[56:59], v[160:163], v[198:201], v[56:59]
	v_mfma_f32_16x16x32_bf16 v[44:47], v[128:131], v[202:205], v[44:47]
	v_mfma_f32_16x16x32_bf16 v[44:47], v[132:135], v[206:209], v[44:47]
	v_mfma_f32_16x16x32_bf16 v[40:43], v[136:139], v[202:205], v[40:43]
	v_mfma_f32_16x16x32_bf16 v[40:43], v[160:163], v[206:209], v[40:43]
	v_mfma_f32_16x16x32_bf16 v[28:31], v[128:131], v[210:213], v[28:31]
	v_mfma_f32_16x16x32_bf16 v[28:31], v[132:135], v[214:217], v[28:31]
	v_mfma_f32_16x16x32_bf16 v[24:27], v[136:139], v[210:213], v[24:27]
	v_mfma_f32_16x16x32_bf16 v[24:27], v[160:163], v[214:217], v[24:27]
	v_mfma_f32_16x16x32_bf16 v[12:15], v[128:131], v[218:221], v[12:15]
	v_mfma_f32_16x16x32_bf16 v[12:15], v[132:135], v[222:225], v[12:15]
	v_mfma_f32_16x16x32_bf16 v[8:11], v[136:139], v[218:221], v[8:11]
	v_mfma_f32_16x16x32_bf16 v[8:11], v[160:163], v[222:225], v[8:11]
	v_mfma_f32_16x16x32_bf16 v[52:55], v[164:167], v[194:197], v[52:55]
	v_mfma_f32_16x16x32_bf16 v[52:55], v[168:171], v[198:201], v[52:55]
	v_mfma_f32_16x16x32_bf16 v[48:51], v[186:189], v[194:197], v[48:51]
	v_mfma_f32_16x16x32_bf16 v[48:51], v[190:193], v[198:201], v[48:51]
	v_mfma_f32_16x16x32_bf16 v[36:39], v[164:167], v[202:205], v[36:39]
	v_mfma_f32_16x16x32_bf16 v[36:39], v[168:171], v[206:209], v[36:39]
	v_mfma_f32_16x16x32_bf16 v[32:35], v[186:189], v[202:205], v[32:35]
	v_mfma_f32_16x16x32_bf16 v[32:35], v[190:193], v[206:209], v[32:35]
	v_mfma_f32_16x16x32_bf16 v[20:23], v[164:167], v[210:213], v[20:23]
	v_mfma_f32_16x16x32_bf16 v[20:23], v[168:171], v[214:217], v[20:23]
	v_mfma_f32_16x16x32_bf16 v[16:19], v[186:189], v[210:213], v[16:19]
	v_mfma_f32_16x16x32_bf16 v[16:19], v[190:193], v[214:217], v[16:19]
	v_mfma_f32_16x16x32_bf16 v[4:7], v[164:167], v[218:221], v[4:7]
	v_mfma_f32_16x16x32_bf16 v[4:7], v[168:171], v[222:225], v[4:7]
	s_setprio 3
	s_barrier
	v_mfma_f32_16x16x32_bf16 v[0:3], v[186:189], v[218:221], v[0:3]
	v_mfma_f32_16x16x32_bf16 v[0:3], v[190:193], v[222:225], v[0:3]
	s_setprio 0
.Lzj_8_1:
	s_add_i32 s69, 0, 0x18000
	v_add_u32_e32 v148, s69, v177
	s_add_i32 s73, 0, 0x1c000
	ds_read_b128 v[128:131], v148
	ds_read_b128 v[132:135], v148 offset:1024
	ds_read_b128 v[136:139], v148 offset:2048
	ds_read_b128 v[160:163], v148 offset:3072
	v_add_u32_e32 v148, s73, v177
	ds_read_b128 v[164:167], v148
	ds_read_b128 v[168:171], v148 offset:1024
	ds_read_b128 v[186:189], v148 offset:2048
	ds_read_b128 v[190:193], v148 offset:3072
	s_add_u32 s82, s82, 0x40000
	s_addc_u32 s83, s83, 0
	s_mov_b32 m0, s20
	v_lshl_add_u64 v[232:233], s[82:83], 0, v[140:141]
	ds_read_b128 v[194:197], v183 offset:32768
	ds_read_b128 v[198:201], v183 offset:33792
	ds_read_b128 v[202:205], v183 offset:34816
	ds_read_b128 v[206:209], v183 offset:35840
	ds_read_b128 v[210:213], v183 offset:36864
	ds_read_b128 v[214:217], v183 offset:37888
	ds_read_b128 v[218:221], v183 offset:38912
	ds_read_b128 v[222:225], v183 offset:39936
	global_load_lds_dwordx4 v[232:233], off
	s_mov_b32 m0, s21
	v_lshl_add_u64 v[232:233], s[82:83], 0, v[144:145]
	global_load_lds_dwordx4 v[232:233], off
	s_waitcnt vmcnt(8) lgkmcnt(0)
	s_barrier
	s_setprio 1
	v_mfma_f32_16x16x32_bf16 v[124:127], v[128:131], v[194:197], v[124:127]
	v_mfma_f32_16x16x32_bf16 v[124:127], v[132:135], v[198:201], v[124:127]
	v_mfma_f32_16x16x32_bf16 v[120:123], v[136:139], v[194:197], v[120:123]
	v_mfma_f32_16x16x32_bf16 v[120:123], v[160:163], v[198:201], v[120:123]
	v_mfma_f32_16x16x32_bf16 v[108:111], v[128:131], v[202:205], v[108:111]
	v_mfma_f32_16x16x32_bf16 v[108:111], v[132:135], v[206:209], v[108:111]
	v_mfma_f32_16x16x32_bf16 v[104:107], v[136:139], v[202:205], v[104:107]
	v_mfma_f32_16x16x32_bf16 v[104:107], v[160:163], v[206:209], v[104:107]
	v_mfma_f32_16x16x32_bf16 v[92:95], v[128:131], v[210:213], v[92:95]
	v_mfma_f32_16x16x32_bf16 v[92:95], v[132:135], v[214:217], v[92:95]
	v_mfma_f32_16x16x32_bf16 v[88:91], v[136:139], v[210:213], v[88:91]
	v_mfma_f32_16x16x32_bf16 v[88:91], v[160:163], v[214:217], v[88:91]
	v_mfma_f32_16x16x32_bf16 v[76:79], v[128:131], v[218:221], v[76:79]
	v_mfma_f32_16x16x32_bf16 v[76:79], v[132:135], v[222:225], v[76:79]
	v_mfma_f32_16x16x32_bf16 v[72:75], v[136:139], v[218:221], v[72:75]
	v_mfma_f32_16x16x32_bf16 v[72:75], v[160:163], v[222:225], v[72:75]
	v_mfma_f32_16x16x32_bf16 v[116:119], v[164:167], v[194:197], v[116:119]
	v_mfma_f32_16x16x32_bf16 v[116:119], v[168:171], v[198:201], v[116:119]
	v_mfma_f32_16x16x32_bf16 v[112:115], v[186:189], v[194:197], v[112:115]
	v_mfma_f32_16x16x32_bf16 v[112:115], v[190:193], v[198:201], v[112:115]
	v_mfma_f32_16x16x32_bf16 v[100:103], v[164:167], v[202:205], v[100:103]
	v_mfma_f32_16x16x32_bf16 v[100:103], v[168:171], v[206:209], v[100:103]
	v_mfma_f32_16x16x32_bf16 v[96:99], v[186:189], v[202:205], v[96:99]
	v_mfma_f32_16x16x32_bf16 v[96:99], v[190:193], v[206:209], v[96:99]
	v_mfma_f32_16x16x32_bf16 v[84:87], v[164:167], v[210:213], v[84:87]
	v_mfma_f32_16x16x32_bf16 v[84:87], v[168:171], v[214:217], v[84:87]
	v_mfma_f32_16x16x32_bf16 v[80:83], v[186:189], v[210:213], v[80:83]
	v_mfma_f32_16x16x32_bf16 v[80:83], v[190:193], v[214:217], v[80:83]
	v_mfma_f32_16x16x32_bf16 v[68:71], v[164:167], v[218:221], v[68:71]
	v_mfma_f32_16x16x32_bf16 v[68:71], v[168:171], v[222:225], v[68:71]
	s_setprio 3
	s_barrier
	v_mfma_f32_16x16x32_bf16 v[64:67], v[186:189], v[218:221], v[64:67]
	v_mfma_f32_16x16x32_bf16 v[64:67], v[190:193], v[222:225], v[64:67]
	s_setprio 0
	s_add_i32 s69, s69, s17
	v_lshl_add_u64 v[172:173], v[172:173], 0, s[10:11]
	s_mov_b32 m0, s69
	ds_read_b128 v[194:197], v183 offset:49152
	ds_read_b128 v[198:201], v183 offset:50176
	ds_read_b128 v[202:205], v183 offset:51200
	ds_read_b128 v[206:209], v183 offset:52224
	ds_read_b128 v[210:213], v183 offset:53248
	ds_read_b128 v[214:217], v183 offset:54272
	ds_read_b128 v[218:221], v183 offset:55296
	ds_read_b128 v[222:225], v183 offset:56320
	global_load_lds_dwordx4 v[172:173], off
	s_add_i32 m0, s69, 0x2000
	s_add_u32 s80, s80, 0x40080
	v_lshl_add_u64 v[172:173], v[226:227], 0, s[10:11]
	s_addc_u32 s81, s81, 0
	s_add_i32 s69, s73, s17
	global_load_lds_dwordx4 v[172:173], off
	s_mov_b32 m0, s69
	v_lshl_add_u64 v[172:173], s[80:81], 0, v[142:143]
	global_load_lds_dwordx4 v[172:173], off
	s_add_i32 m0, s69, 0x2000
	v_lshl_add_u64 v[172:173], s[80:81], 0, v[146:147]
	global_load_lds_dwordx4 v[172:173], off
	s_mov_b32 m0, s23
	v_lshl_add_u64 v[172:173], v[228:229], 0, s[10:11]
	global_load_lds_dwordx4 v[172:173], off
	s_mov_b32 m0, s24
	v_lshl_add_u64 v[172:173], v[230:231], 0, s[10:11]
	global_load_lds_dwordx4 v[172:173], off
	s_waitcnt vmcnt(8) lgkmcnt(0)
	s_barrier
	s_setprio 1
	v_mfma_f32_16x16x32_bf16 v[60:63], v[128:131], v[194:197], v[60:63]
	v_mfma_f32_16x16x32_bf16 v[60:63], v[132:135], v[198:201], v[60:63]
	v_mfma_f32_16x16x32_bf16 v[56:59], v[136:139], v[194:197], v[56:59]
	v_mfma_f32_16x16x32_bf16 v[56:59], v[160:163], v[198:201], v[56:59]
	v_mfma_f32_16x16x32_bf16 v[44:47], v[128:131], v[202:205], v[44:47]
	v_mfma_f32_16x16x32_bf16 v[44:47], v[132:135], v[206:209], v[44:47]
	v_mfma_f32_16x16x32_bf16 v[40:43], v[136:139], v[202:205], v[40:43]
	v_mfma_f32_16x16x32_bf16 v[40:43], v[160:163], v[206:209], v[40:43]
	v_mfma_f32_16x16x32_bf16 v[28:31], v[128:131], v[210:213], v[28:31]
	v_mfma_f32_16x16x32_bf16 v[28:31], v[132:135], v[214:217], v[28:31]
	v_mfma_f32_16x16x32_bf16 v[24:27], v[136:139], v[210:213], v[24:27]
	v_mfma_f32_16x16x32_bf16 v[24:27], v[160:163], v[214:217], v[24:27]
	v_mfma_f32_16x16x32_bf16 v[12:15], v[128:131], v[218:221], v[12:15]
	v_mfma_f32_16x16x32_bf16 v[12:15], v[132:135], v[222:225], v[12:15]
	v_mfma_f32_16x16x32_bf16 v[8:11], v[136:139], v[218:221], v[8:11]
	v_mfma_f32_16x16x32_bf16 v[8:11], v[160:163], v[222:225], v[8:11]
	v_mfma_f32_16x16x32_bf16 v[52:55], v[164:167], v[194:197], v[52:55]
	v_mfma_f32_16x16x32_bf16 v[52:55], v[168:171], v[198:201], v[52:55]
	v_mfma_f32_16x16x32_bf16 v[48:51], v[186:189], v[194:197], v[48:51]
	v_mfma_f32_16x16x32_bf16 v[48:51], v[190:193], v[198:201], v[48:51]
	v_mfma_f32_16x16x32_bf16 v[36:39], v[164:167], v[202:205], v[36:39]
	v_mfma_f32_16x16x32_bf16 v[36:39], v[168:171], v[206:209], v[36:39]
	v_mfma_f32_16x16x32_bf16 v[32:35], v[186:189], v[202:205], v[32:35]
	v_mfma_f32_16x16x32_bf16 v[32:35], v[190:193], v[206:209], v[32:35]
	v_mfma_f32_16x16x32_bf16 v[20:23], v[164:167], v[210:213], v[20:23]
	v_mfma_f32_16x16x32_bf16 v[20:23], v[168:171], v[214:217], v[20:23]
	v_mfma_f32_16x16x32_bf16 v[16:19], v[186:189], v[210:213], v[16:19]
	v_mfma_f32_16x16x32_bf16 v[16:19], v[190:193], v[214:217], v[16:19]
	v_mfma_f32_16x16x32_bf16 v[4:7], v[164:167], v[218:221], v[4:7]
	v_mfma_f32_16x16x32_bf16 v[4:7], v[168:171], v[222:225], v[4:7]
	s_setprio 3
	s_barrier
	v_mfma_f32_16x16x32_bf16 v[0:3], v[186:189], v[218:221], v[0:3]
	v_mfma_f32_16x16x32_bf16 v[0:3], v[190:193], v[222:225], v[0:3]
	s_setprio 0
	s_add_i32 s68, s68, 2
	s_add_u32 s78, s78, 0x100
	s_addc_u32 s79, s79, 0
	s_add_u32 s66, s66, 0x100
	s_addc_u32 s67, s67, 0
	s_cmp_gt_u32 s68, 13
	s_cbranch_scc0 .LBB0_1760
	s_branch .Lzskip_8

.LBB0_2037:
	ds_read_b128 v[120:123], v245
	ds_read_b128 v[124:127], v245 offset:1024
	ds_read_b128 v[128:131], v245 offset:2048
	ds_read_b128 v[132:135], v245 offset:3072
	ds_read_b128 v[144:147], v246
	ds_read_b128 v[148:151], v246 offset:1024
	ds_read_b128 v[152:155], v246 offset:2048
	ds_read_b128 v[156:159], v246 offset:3072
	s_add_u32 s67, s76, 0xfffc0080
	s_addc_u32 s68, s77, -1
	s_cmp_eq_u32 s66, 12
	s_cselect_b32 s81, s53, s68
	s_cselect_b32 s80, s54, s67
	s_cselect_b32 s79, s51, s57
	s_cselect_b32 s78, s55, s56
	v_lshl_add_u64 v[204:205], s[76:77], 0, v[200:201]
	s_add_i32 m0, s16, 0xc000
	ds_read_b128 v[160:163], v247
	ds_read_b128 v[164:167], v247 offset:1024
	ds_read_b128 v[168:171], v247 offset:2048
	ds_read_b128 v[172:175], v247 offset:3072
	ds_read_b128 v[176:179], v247 offset:4096
	ds_read_b128 v[180:183], v247 offset:5120
	ds_read_b128 v[184:187], v247 offset:6144
	ds_read_b128 v[188:191], v247 offset:7168
	global_load_lds_dwordx4 v[204:205], off
	s_add_i32 m0, s16, 0xe000
	v_lshl_add_u64 v[204:205], s[76:77], 0, v[202:203]
	global_load_lds_dwordx4 v[204:205], off
	s_cmp_eq_u32 s66, -2
	s_waitcnt vmcnt(8) lgkmcnt(0)
	s_barrier
	s_setprio 1
	s_cbranch_scc1 .Lzv_9_0
	v_mfma_f32_16x16x32_bf16 v[140:143], v[120:123], v[160:163], v[140:143]
	v_mfma_f32_16x16x32_bf16 v[140:143], v[124:127], v[164:167], v[140:143]
	v_mfma_f32_16x16x32_bf16 v[136:139], v[128:131], v[160:163], v[136:139]
	v_mfma_f32_16x16x32_bf16 v[136:139], v[132:135], v[164:167], v[136:139]
	v_mfma_f32_16x16x32_bf16 v[108:111], v[120:123], v[168:171], v[108:111]
	v_mfma_f32_16x16x32_bf16 v[108:111], v[124:127], v[172:175], v[108:111]
	v_mfma_f32_16x16x32_bf16 v[104:107], v[128:131], v[168:171], v[104:107]
	v_mfma_f32_16x16x32_bf16 v[104:107], v[132:135], v[172:175], v[104:107]
	v_mfma_f32_16x16x32_bf16 v[92:95], v[120:123], v[176:179], v[92:95]
	v_mfma_f32_16x16x32_bf16 v[92:95], v[124:127], v[180:183], v[92:95]
	v_mfma_f32_16x16x32_bf16 v[88:91], v[128:131], v[176:179], v[88:91]
	v_mfma_f32_16x16x32_bf16 v[88:91], v[132:135], v[180:183], v[88:91]
	v_mfma_f32_16x16x32_bf16 v[76:79], v[120:123], v[184:187], v[76:79]
	v_mfma_f32_16x16x32_bf16 v[76:79], v[124:127], v[188:191], v[76:79]
	v_mfma_f32_16x16x32_bf16 v[72:75], v[128:131], v[184:187], v[72:75]
	v_mfma_f32_16x16x32_bf16 v[72:75], v[132:135], v[188:191], v[72:75]
	v_mfma_f32_16x16x32_bf16 v[116:119], v[144:147], v[160:163], v[116:119]
	v_mfma_f32_16x16x32_bf16 v[116:119], v[148:151], v[164:167], v[116:119]
	v_mfma_f32_16x16x32_bf16 v[112:115], v[152:155], v[160:163], v[112:115]
	v_mfma_f32_16x16x32_bf16 v[112:115], v[156:159], v[164:167], v[112:115]
	v_mfma_f32_16x16x32_bf16 v[100:103], v[144:147], v[168:171], v[100:103]
	v_mfma_f32_16x16x32_bf16 v[100:103], v[148:151], v[172:175], v[100:103]
	v_mfma_f32_16x16x32_bf16 v[96:99], v[152:155], v[168:171], v[96:99]
	v_mfma_f32_16x16x32_bf16 v[96:99], v[156:159], v[172:175], v[96:99]
	v_mfma_f32_16x16x32_bf16 v[84:87], v[144:147], v[176:179], v[84:87]
	v_mfma_f32_16x16x32_bf16 v[84:87], v[148:151], v[180:183], v[84:87]
	v_mfma_f32_16x16x32_bf16 v[80:83], v[152:155], v[176:179], v[80:83]
	v_mfma_f32_16x16x32_bf16 v[80:83], v[156:159], v[180:183], v[80:83]
	v_mfma_f32_16x16x32_bf16 v[68:71], v[144:147], v[184:187], v[68:71]
	v_mfma_f32_16x16x32_bf16 v[68:71], v[148:151], v[188:191], v[68:71]
	s_setprio 3
	s_barrier
	v_mfma_f32_16x16x32_bf16 v[64:67], v[152:155], v[184:187], v[64:67]
	v_mfma_f32_16x16x32_bf16 v[64:67], v[156:159], v[188:191], v[64:67]
	s_setprio 0
.Lzj_9_0:
	s_add_i32 s67, s26, s15
	v_lshl_add_u64 v[204:205], s[78:79], 0, v[194:195]
	s_mov_b32 m0, s67
	ds_read_b128 v[160:163], v247 offset:16384
	ds_read_b128 v[164:167], v247 offset:17408
	ds_read_b128 v[168:171], v247 offset:18432
	ds_read_b128 v[172:175], v247 offset:19456
	ds_read_b128 v[176:179], v247 offset:20480
	ds_read_b128 v[180:183], v247 offset:21504
	ds_read_b128 v[184:187], v247 offset:22528
	ds_read_b128 v[188:191], v247 offset:23552
	global_load_lds_dwordx4 v[204:205], off
	s_add_i32 m0, s67, 0x2000
	s_add_u32 s68, s78, 0x40000
	v_lshl_add_u64 v[206:207], s[78:79], 0, v[198:199]
	s_addc_u32 s69, s79, 0
	s_add_i32 s67, s27, s15
	global_load_lds_dwordx4 v[206:207], off
	v_lshl_add_u64 v[208:209], s[68:69], 0, v[194:195]
	s_mov_b32 m0, s67
	global_load_lds_dwordx4 v[208:209], off
	s_add_i32 m0, s67, 0x2000
	v_lshl_add_u64 v[208:209], s[68:69], 0, v[198:199]
	global_load_lds_dwordx4 v[208:209], off
	s_mov_b32 m0, s16
	v_lshl_add_u64 v[208:209], s[80:81], 0, v[192:193]
	global_load_lds_dwordx4 v[208:209], off
	s_mov_b32 m0, s17
	v_lshl_add_u64 v[210:211], s[80:81], 0, v[196:197]
	global_load_lds_dwordx4 v[210:211], off
	s_cmp_eq_u32 s66, -2
	s_waitcnt vmcnt(8) lgkmcnt(0)
	s_barrier
	s_setprio 1
	s_cbranch_scc1 .Lzv_9_1
	v_mfma_f32_16x16x32_bf16 v[60:63], v[120:123], v[160:163], v[60:63]
	v_mfma_f32_16x16x32_bf16 v[60:63], v[124:127], v[164:167], v[60:63]
	v_mfma_f32_16x16x32_bf16 v[56:59], v[128:131], v[160:163], v[56:59]
	v_mfma_f32_16x16x32_bf16 v[56:59], v[132:135], v[164:167], v[56:59]
	v_mfma_f32_16x16x32_bf16 v[44:47], v[120:123], v[168:171], v[44:47]
	v_mfma_f32_16x16x32_bf16 v[44:47], v[124:127], v[172:175], v[44:47]
	v_mfma_f32_16x16x32_bf16 v[40:43], v[128:131], v[168:171], v[40:43]
	v_mfma_f32_16x16x32_bf16 v[40:43], v[132:135], v[172:175], v[40:43]
	v_mfma_f32_16x16x32_bf16 v[28:31], v[120:123], v[176:179], v[28:31]
	v_mfma_f32_16x16x32_bf16 v[28:31], v[124:127], v[180:183], v[28:31]
	v_mfma_f32_16x16x32_bf16 v[24:27], v[128:131], v[176:179], v[24:27]
	v_mfma_f32_16x16x32_bf16 v[24:27], v[132:135], v[180:183], v[24:27]
	v_mfma_f32_16x16x32_bf16 v[12:15], v[120:123], v[184:187], v[12:15]
	v_mfma_f32_16x16x32_bf16 v[12:15], v[124:127], v[188:191], v[12:15]
	v_mfma_f32_16x16x32_bf16 v[8:11], v[128:131], v[184:187], v[8:11]
	v_mfma_f32_16x16x32_bf16 v[8:11], v[132:135], v[188:191], v[8:11]
	v_mfma_f32_16x16x32_bf16 v[52:55], v[144:147], v[160:163], v[52:55]
	v_mfma_f32_16x16x32_bf16 v[52:55], v[148:151], v[164:167], v[52:55]
	v_mfma_f32_16x16x32_bf16 v[48:51], v[152:155], v[160:163], v[48:51]
	v_mfma_f32_16x16x32_bf16 v[48:51], v[156:159], v[164:167], v[48:51]
	v_mfma_f32_16x16x32_bf16 v[36:39], v[144:147], v[168:171], v[36:39]
	v_mfma_f32_16x16x32_bf16 v[36:39], v[148:151], v[172:175], v[36:39]
	v_mfma_f32_16x16x32_bf16 v[32:35], v[152:155], v[168:171], v[32:35]
	v_mfma_f32_16x16x32_bf16 v[32:35], v[156:159], v[172:175], v[32:35]
	v_mfma_f32_16x16x32_bf16 v[20:23], v[144:147], v[176:179], v[20:23]
	v_mfma_f32_16x16x32_bf16 v[20:23], v[148:151], v[180:183], v[20:23]
	v_mfma_f32_16x16x32_bf16 v[16:19], v[152:155], v[176:179], v[16:19]
	v_mfma_f32_16x16x32_bf16 v[16:19], v[156:159], v[180:183], v[16:19]
	v_mfma_f32_16x16x32_bf16 v[4:7], v[144:147], v[184:187], v[4:7]
	v_mfma_f32_16x16x32_bf16 v[4:7], v[148:151], v[188:191], v[4:7]
	s_setprio 3
	s_barrier
	v_mfma_f32_16x16x32_bf16 v[0:3], v[152:155], v[184:187], v[0:3]
	v_mfma_f32_16x16x32_bf16 v[0:3], v[156:159], v[188:191], v[0:3]
	s_setprio 0
.Lzj_9_1:
	s_add_i32 s67, 0, 0x18000
	s_add_i32 s75, 0, 0x1c000
	v_add_u32_e32 v132, s67, v243
	v_add_u32_e32 v156, s75, v243
	ds_read_b128 v[120:123], v132
	ds_read_b128 v[124:127], v132 offset:1024
	ds_read_b128 v[128:131], v132 offset:2048
	ds_read_b128 v[132:135], v132 offset:3072
	ds_read_b128 v[144:147], v156
	ds_read_b128 v[148:151], v156 offset:1024
	ds_read_b128 v[152:155], v156 offset:2048
	ds_read_b128 v[156:159], v156 offset:3072
	s_add_u32 s68, s80, 0x40000
	s_addc_u32 s69, s81, 0
	s_mov_b32 m0, s18
	v_lshl_add_u64 v[212:213], s[68:69], 0, v[192:193]
	ds_read_b128 v[160:163], v247 offset:32768
	ds_read_b128 v[164:167], v247 offset:33792
	ds_read_b128 v[168:171], v247 offset:34816
	ds_read_b128 v[172:175], v247 offset:35840
	ds_read_b128 v[176:179], v247 offset:36864
	ds_read_b128 v[180:183], v247 offset:37888
	ds_read_b128 v[184:187], v247 offset:38912
	ds_read_b128 v[188:191], v247 offset:39936
	global_load_lds_dwordx4 v[212:213], off
	s_mov_b32 m0, s19
	v_lshl_add_u64 v[212:213], s[68:69], 0, v[196:197]
	global_load_lds_dwordx4 v[212:213], off
	s_waitcnt vmcnt(8) lgkmcnt(0)
	s_barrier
	s_setprio 1
	v_mfma_f32_16x16x32_bf16 v[140:143], v[120:123], v[160:163], v[140:143]
	v_mfma_f32_16x16x32_bf16 v[140:143], v[124:127], v[164:167], v[140:143]
	v_mfma_f32_16x16x32_bf16 v[136:139], v[128:131], v[160:163], v[136:139]
	v_mfma_f32_16x16x32_bf16 v[136:139], v[132:135], v[164:167], v[136:139]
	v_mfma_f32_16x16x32_bf16 v[108:111], v[120:123], v[168:171], v[108:111]
	v_mfma_f32_16x16x32_bf16 v[108:111], v[124:127], v[172:175], v[108:111]
	v_mfma_f32_16x16x32_bf16 v[104:107], v[128:131], v[168:171], v[104:107]
	v_mfma_f32_16x16x32_bf16 v[104:107], v[132:135], v[172:175], v[104:107]
	v_mfma_f32_16x16x32_bf16 v[92:95], v[120:123], v[176:179], v[92:95]
	v_mfma_f32_16x16x32_bf16 v[92:95], v[124:127], v[180:183], v[92:95]
	v_mfma_f32_16x16x32_bf16 v[88:91], v[128:131], v[176:179], v[88:91]
	v_mfma_f32_16x16x32_bf16 v[88:91], v[132:135], v[180:183], v[88:91]
	v_mfma_f32_16x16x32_bf16 v[76:79], v[120:123], v[184:187], v[76:79]
	v_mfma_f32_16x16x32_bf16 v[76:79], v[124:127], v[188:191], v[76:79]
	v_mfma_f32_16x16x32_bf16 v[72:75], v[128:131], v[184:187], v[72:75]
	v_mfma_f32_16x16x32_bf16 v[72:75], v[132:135], v[188:191], v[72:75]
	v_mfma_f32_16x16x32_bf16 v[116:119], v[144:147], v[160:163], v[116:119]
	v_mfma_f32_16x16x32_bf16 v[116:119], v[148:151], v[164:167], v[116:119]
	v_mfma_f32_16x16x32_bf16 v[112:115], v[152:155], v[160:163], v[112:115]
	v_mfma_f32_16x16x32_bf16 v[112:115], v[156:159], v[164:167], v[112:115]
	v_mfma_f32_16x16x32_bf16 v[100:103], v[144:147], v[168:171], v[100:103]
	v_mfma_f32_16x16x32_bf16 v[100:103], v[148:151], v[172:175], v[100:103]
	v_mfma_f32_16x16x32_bf16 v[96:99], v[152:155], v[168:171], v[96:99]
	v_mfma_f32_16x16x32_bf16 v[96:99], v[156:159], v[172:175], v[96:99]
	v_mfma_f32_16x16x32_bf16 v[84:87], v[144:147], v[176:179], v[84:87]
	v_mfma_f32_16x16x32_bf16 v[84:87], v[148:151], v[180:183], v[84:87]
	v_mfma_f32_16x16x32_bf16 v[80:83], v[152:155], v[176:179], v[80:83]
	v_mfma_f32_16x16x32_bf16 v[80:83], v[156:159], v[180:183], v[80:83]
	v_mfma_f32_16x16x32_bf16 v[68:71], v[144:147], v[184:187], v[68:71]
	v_mfma_f32_16x16x32_bf16 v[68:71], v[148:151], v[188:191], v[68:71]
	s_setprio 3
	s_barrier
	v_mfma_f32_16x16x32_bf16 v[64:67], v[152:155], v[184:187], v[64:67]
	v_mfma_f32_16x16x32_bf16 v[64:67], v[156:159], v[188:191], v[64:67]
	s_setprio 0
	s_add_i32 s67, s67, s15
	v_lshl_add_u64 v[204:205], v[204:205], 0, s[46:47]
	s_mov_b32 m0, s67
	ds_read_b128 v[160:163], v247 offset:49152
	ds_read_b128 v[164:167], v247 offset:50176
	ds_read_b128 v[168:171], v247 offset:51200
	ds_read_b128 v[172:175], v247 offset:52224
	ds_read_b128 v[176:179], v247 offset:53248
	ds_read_b128 v[180:183], v247 offset:54272
	ds_read_b128 v[184:187], v247 offset:55296
	ds_read_b128 v[188:191], v247 offset:56320
	global_load_lds_dwordx4 v[204:205], off
	s_add_i32 m0, s67, 0x2000
	s_add_u32 s68, s78, 0x40080
	v_lshl_add_u64 v[204:205], v[206:207], 0, s[46:47]
	s_addc_u32 s69, s79, 0
	s_add_i32 s67, s75, s15
	global_load_lds_dwordx4 v[204:205], off
	s_mov_b32 m0, s67
	v_lshl_add_u64 v[204:205], s[68:69], 0, v[194:195]
	global_load_lds_dwordx4 v[204:205], off
	s_add_i32 m0, s67, 0x2000
	v_lshl_add_u64 v[204:205], s[68:69], 0, v[198:199]
	global_load_lds_dwordx4 v[204:205], off
	s_mov_b32 m0, s21
	v_lshl_add_u64 v[204:205], v[208:209], 0, s[46:47]
	global_load_lds_dwordx4 v[204:205], off
	s_mov_b32 m0, s22
	v_lshl_add_u64 v[204:205], v[210:211], 0, s[46:47]
	global_load_lds_dwordx4 v[204:205], off
	s_waitcnt vmcnt(8) lgkmcnt(0)
	s_barrier
	s_setprio 1
	v_mfma_f32_16x16x32_bf16 v[60:63], v[120:123], v[160:163], v[60:63]
	v_mfma_f32_16x16x32_bf16 v[60:63], v[124:127], v[164:167], v[60:63]
	v_mfma_f32_16x16x32_bf16 v[56:59], v[128:131], v[160:163], v[56:59]
	v_mfma_f32_16x16x32_bf16 v[56:59], v[132:135], v[164:167], v[56:59]
	v_mfma_f32_16x16x32_bf16 v[44:47], v[120:123], v[168:171], v[44:47]
	v_mfma_f32_16x16x32_bf16 v[44:47], v[124:127], v[172:175], v[44:47]
	v_mfma_f32_16x16x32_bf16 v[40:43], v[128:131], v[168:171], v[40:43]
	v_mfma_f32_16x16x32_bf16 v[40:43], v[132:135], v[172:175], v[40:43]
	v_mfma_f32_16x16x32_bf16 v[28:31], v[120:123], v[176:179], v[28:31]
	v_mfma_f32_16x16x32_bf16 v[28:31], v[124:127], v[180:183], v[28:31]
	v_mfma_f32_16x16x32_bf16 v[24:27], v[128:131], v[176:179], v[24:27]
	v_mfma_f32_16x16x32_bf16 v[24:27], v[132:135], v[180:183], v[24:27]
	v_mfma_f32_16x16x32_bf16 v[12:15], v[120:123], v[184:187], v[12:15]
	v_mfma_f32_16x16x32_bf16 v[12:15], v[124:127], v[188:191], v[12:15]
	v_mfma_f32_16x16x32_bf16 v[8:11], v[128:131], v[184:187], v[8:11]
	v_mfma_f32_16x16x32_bf16 v[8:11], v[132:135], v[188:191], v[8:11]
	v_mfma_f32_16x16x32_bf16 v[52:55], v[144:147], v[160:163], v[52:55]
	v_mfma_f32_16x16x32_bf16 v[52:55], v[148:151], v[164:167], v[52:55]
	v_mfma_f32_16x16x32_bf16 v[48:51], v[152:155], v[160:163], v[48:51]
	v_mfma_f32_16x16x32_bf16 v[48:51], v[156:159], v[164:167], v[48:51]
	v_mfma_f32_16x16x32_bf16 v[36:39], v[144:147], v[168:171], v[36:39]
	v_mfma_f32_16x16x32_bf16 v[36:39], v[148:151], v[172:175], v[36:39]
	v_mfma_f32_16x16x32_bf16 v[32:35], v[152:155], v[168:171], v[32:35]
	v_mfma_f32_16x16x32_bf16 v[32:35], v[156:159], v[172:175], v[32:35]
	v_mfma_f32_16x16x32_bf16 v[20:23], v[144:147], v[176:179], v[20:23]
	v_mfma_f32_16x16x32_bf16 v[20:23], v[148:151], v[180:183], v[20:23]
	v_mfma_f32_16x16x32_bf16 v[16:19], v[152:155], v[176:179], v[16:19]
	v_mfma_f32_16x16x32_bf16 v[16:19], v[156:159], v[180:183], v[16:19]
	v_mfma_f32_16x16x32_bf16 v[4:7], v[144:147], v[184:187], v[4:7]
	v_mfma_f32_16x16x32_bf16 v[4:7], v[148:151], v[188:191], v[4:7]
	s_setprio 3
	s_barrier
	v_mfma_f32_16x16x32_bf16 v[0:3], v[152:155], v[184:187], v[0:3]
	v_mfma_f32_16x16x32_bf16 v[0:3], v[156:159], v[188:191], v[0:3]
	s_setprio 0
	s_add_i32 s66, s66, 2
	s_add_u32 s76, s76, 0x100
	s_addc_u32 s77, s77, 0
	s_add_u32 s56, s56, 0x100
	s_addc_u32 s57, s57, 0
	s_cmp_gt_u32 s66, 13
	s_cbranch_scc0 .LBB0_2037
	s_branch .Lzskip_9

.LBB0_2192:
	ds_read_b128 v[146:149], v174
	ds_read_b128 v[150:153], v174 offset:1024
	ds_read_b128 v[154:157], v174 offset:2048
	ds_read_b128 v[158:161], v174 offset:3072
	ds_read_b128 v[162:165], v175
	ds_read_b128 v[178:181], v175 offset:1024
	ds_read_b128 v[182:185], v175 offset:2048
	ds_read_b128 v[186:189], v175 offset:3072
	s_add_u32 s70, s58, 0xfffc0080
	s_addc_u32 s71, s59, -1
	s_cmp_eq_u32 s69, 12
	s_cselect_b32 s73, s47, s71
	s_cselect_b32 s72, s53, s70
	s_cselect_b32 s71, s45, s68
	s_cselect_b32 s70, s66, s67
	v_lshl_add_u64 v[166:167], s[58:59], 0, v[136:137]
	s_add_i32 m0, s17, 0xc000
	ds_read_b128 v[190:193], v176
	ds_read_b128 v[194:197], v176 offset:1024
	ds_read_b128 v[198:201], v176 offset:2048
	ds_read_b128 v[202:205], v176 offset:3072
	ds_read_b128 v[206:209], v176 offset:4096
	ds_read_b128 v[210:213], v176 offset:5120
	ds_read_b128 v[214:217], v176 offset:6144
	ds_read_b128 v[218:221], v176 offset:7168
	global_load_lds_dwordx4 v[166:167], off
	s_add_i32 m0, s17, 0xe000
	v_lshl_add_u64 v[166:167], s[58:59], 0, v[140:141]
	global_load_lds_dwordx4 v[166:167], off
	s_cmp_eq_u32 s69, -2
	s_waitcnt vmcnt(8) lgkmcnt(0)
	s_barrier
	s_setprio 1
	s_cbranch_scc1 .Lzv_10_0
	v_mfma_f32_16x16x32_bf16 v[124:127], v[146:149], v[190:193], v[124:127]
	v_mfma_f32_16x16x32_bf16 v[124:127], v[150:153], v[194:197], v[124:127]
	v_mfma_f32_16x16x32_bf16 v[116:119], v[154:157], v[190:193], v[116:119]
	v_mfma_f32_16x16x32_bf16 v[116:119], v[158:161], v[194:197], v[116:119]
	v_mfma_f32_16x16x32_bf16 v[108:111], v[146:149], v[198:201], v[108:111]
	v_mfma_f32_16x16x32_bf16 v[108:111], v[150:153], v[202:205], v[108:111]
	v_mfma_f32_16x16x32_bf16 v[100:103], v[154:157], v[198:201], v[100:103]
	v_mfma_f32_16x16x32_bf16 v[100:103], v[158:161], v[202:205], v[100:103]
	v_mfma_f32_16x16x32_bf16 v[92:95], v[146:149], v[206:209], v[92:95]
	v_mfma_f32_16x16x32_bf16 v[92:95], v[150:153], v[210:213], v[92:95]
	v_mfma_f32_16x16x32_bf16 v[84:87], v[154:157], v[206:209], v[84:87]
	v_mfma_f32_16x16x32_bf16 v[84:87], v[158:161], v[210:213], v[84:87]
	v_mfma_f32_16x16x32_bf16 v[76:79], v[146:149], v[214:217], v[76:79]
	v_mfma_f32_16x16x32_bf16 v[76:79], v[150:153], v[218:221], v[76:79]
	v_mfma_f32_16x16x32_bf16 v[68:71], v[154:157], v[214:217], v[68:71]
	v_mfma_f32_16x16x32_bf16 v[68:71], v[158:161], v[218:221], v[68:71]
	v_mfma_f32_16x16x32_bf16 v[120:123], v[162:165], v[190:193], v[120:123]
	v_mfma_f32_16x16x32_bf16 v[120:123], v[178:181], v[194:197], v[120:123]
	v_mfma_f32_16x16x32_bf16 v[112:115], v[182:185], v[190:193], v[112:115]
	v_mfma_f32_16x16x32_bf16 v[112:115], v[186:189], v[194:197], v[112:115]
	v_mfma_f32_16x16x32_bf16 v[104:107], v[162:165], v[198:201], v[104:107]
	v_mfma_f32_16x16x32_bf16 v[104:107], v[178:181], v[202:205], v[104:107]
	v_mfma_f32_16x16x32_bf16 v[96:99], v[182:185], v[198:201], v[96:99]
	v_mfma_f32_16x16x32_bf16 v[96:99], v[186:189], v[202:205], v[96:99]
	v_mfma_f32_16x16x32_bf16 v[88:91], v[162:165], v[206:209], v[88:91]
	v_mfma_f32_16x16x32_bf16 v[88:91], v[178:181], v[210:213], v[88:91]
	v_mfma_f32_16x16x32_bf16 v[80:83], v[182:185], v[206:209], v[80:83]
	v_mfma_f32_16x16x32_bf16 v[80:83], v[186:189], v[210:213], v[80:83]
	v_mfma_f32_16x16x32_bf16 v[72:75], v[162:165], v[214:217], v[72:75]
	v_mfma_f32_16x16x32_bf16 v[72:75], v[178:181], v[218:221], v[72:75]
	s_setprio 3
	s_barrier
	v_mfma_f32_16x16x32_bf16 v[64:67], v[182:185], v[214:217], v[64:67]
	v_mfma_f32_16x16x32_bf16 v[64:67], v[186:189], v[218:221], v[64:67]
	s_setprio 0
.Lzj_10_0:
	s_add_i32 s74, s26, s16
	v_lshl_add_u64 v[166:167], s[70:71], 0, v[132:133]
	s_mov_b32 m0, s74
	ds_read_b128 v[190:193], v176 offset:16384
	ds_read_b128 v[194:197], v176 offset:17408
	ds_read_b128 v[198:201], v176 offset:18432
	ds_read_b128 v[202:205], v176 offset:19456
	ds_read_b128 v[206:209], v176 offset:20480
	ds_read_b128 v[210:213], v176 offset:21504
	ds_read_b128 v[214:217], v176 offset:22528
	ds_read_b128 v[218:221], v176 offset:23552
	global_load_lds_dwordx4 v[166:167], off
	s_add_i32 m0, s74, 0x2000
	s_add_u32 s74, s70, 0x40000
	v_lshl_add_u64 v[222:223], s[70:71], 0, v[128:129]
	s_addc_u32 s75, s71, 0
	s_add_i32 s76, s27, s16
	global_load_lds_dwordx4 v[222:223], off
	v_lshl_add_u64 v[224:225], s[74:75], 0, v[132:133]
	s_mov_b32 m0, s76
	global_load_lds_dwordx4 v[224:225], off
	s_add_i32 m0, s76, 0x2000
	v_lshl_add_u64 v[224:225], s[74:75], 0, v[128:129]
	global_load_lds_dwordx4 v[224:225], off
	s_mov_b32 m0, s17
	v_lshl_add_u64 v[224:225], s[72:73], 0, v[134:135]
	global_load_lds_dwordx4 v[224:225], off
	s_mov_b32 m0, s18
	v_lshl_add_u64 v[226:227], s[72:73], 0, v[130:131]
	global_load_lds_dwordx4 v[226:227], off
	s_cmp_eq_u32 s69, -2
	s_waitcnt vmcnt(8) lgkmcnt(0)
	s_barrier
	s_setprio 1
	s_cbranch_scc1 .Lzv_10_1
	v_mfma_f32_16x16x32_bf16 v[60:63], v[146:149], v[190:193], v[60:63]
	v_mfma_f32_16x16x32_bf16 v[60:63], v[150:153], v[194:197], v[60:63]
	v_mfma_f32_16x16x32_bf16 v[52:55], v[154:157], v[190:193], v[52:55]
	v_mfma_f32_16x16x32_bf16 v[52:55], v[158:161], v[194:197], v[52:55]
	v_mfma_f32_16x16x32_bf16 v[44:47], v[146:149], v[198:201], v[44:47]
	v_mfma_f32_16x16x32_bf16 v[44:47], v[150:153], v[202:205], v[44:47]
	v_mfma_f32_16x16x32_bf16 v[36:39], v[154:157], v[198:201], v[36:39]
	v_mfma_f32_16x16x32_bf16 v[36:39], v[158:161], v[202:205], v[36:39]
	v_mfma_f32_16x16x32_bf16 v[28:31], v[146:149], v[206:209], v[28:31]
	v_mfma_f32_16x16x32_bf16 v[28:31], v[150:153], v[210:213], v[28:31]
	v_mfma_f32_16x16x32_bf16 v[20:23], v[154:157], v[206:209], v[20:23]
	v_mfma_f32_16x16x32_bf16 v[20:23], v[158:161], v[210:213], v[20:23]
	v_mfma_f32_16x16x32_bf16 v[12:15], v[146:149], v[214:217], v[12:15]
	v_mfma_f32_16x16x32_bf16 v[12:15], v[150:153], v[218:221], v[12:15]
	v_mfma_f32_16x16x32_bf16 v[4:7], v[154:157], v[214:217], v[4:7]
	v_mfma_f32_16x16x32_bf16 v[4:7], v[158:161], v[218:221], v[4:7]
	v_mfma_f32_16x16x32_bf16 v[56:59], v[162:165], v[190:193], v[56:59]
	v_mfma_f32_16x16x32_bf16 v[56:59], v[178:181], v[194:197], v[56:59]
	v_mfma_f32_16x16x32_bf16 v[48:51], v[182:185], v[190:193], v[48:51]
	v_mfma_f32_16x16x32_bf16 v[48:51], v[186:189], v[194:197], v[48:51]
	v_mfma_f32_16x16x32_bf16 v[40:43], v[162:165], v[198:201], v[40:43]
	v_mfma_f32_16x16x32_bf16 v[40:43], v[178:181], v[202:205], v[40:43]
	v_mfma_f32_16x16x32_bf16 v[32:35], v[182:185], v[198:201], v[32:35]
	v_mfma_f32_16x16x32_bf16 v[32:35], v[186:189], v[202:205], v[32:35]
	v_mfma_f32_16x16x32_bf16 v[24:27], v[162:165], v[206:209], v[24:27]
	v_mfma_f32_16x16x32_bf16 v[24:27], v[178:181], v[210:213], v[24:27]
	v_mfma_f32_16x16x32_bf16 v[16:19], v[182:185], v[206:209], v[16:19]
	v_mfma_f32_16x16x32_bf16 v[16:19], v[186:189], v[210:213], v[16:19]
	v_mfma_f32_16x16x32_bf16 v[8:11], v[162:165], v[214:217], v[8:11]
	v_mfma_f32_16x16x32_bf16 v[8:11], v[178:181], v[218:221], v[8:11]
	s_setprio 3
	s_barrier
	v_mfma_f32_16x16x32_bf16 v[0:3], v[182:185], v[214:217], v[0:3]
	v_mfma_f32_16x16x32_bf16 v[0:3], v[186:189], v[218:221], v[0:3]
	s_setprio 0
.Lzj_10_1:
	s_add_i32 s74, 0, 0x18000
	s_add_i32 s75, 0, 0x1c000
	v_add_u32_e32 v158, s74, v171
	v_add_u32_e32 v186, s75, v171
	ds_read_b128 v[146:149], v158
	ds_read_b128 v[150:153], v158 offset:1024
	ds_read_b128 v[154:157], v158 offset:2048
	ds_read_b128 v[158:161], v158 offset:3072
	ds_read_b128 v[162:165], v186
	ds_read_b128 v[178:181], v186 offset:1024
	ds_read_b128 v[182:185], v186 offset:2048
	ds_read_b128 v[186:189], v186 offset:3072
	s_add_u32 s72, s72, 0x40000
	s_addc_u32 s73, s73, 0
	s_mov_b32 m0, s19
	v_lshl_add_u64 v[228:229], s[72:73], 0, v[134:135]
	ds_read_b128 v[190:193], v176 offset:32768
	ds_read_b128 v[194:197], v176 offset:33792
	ds_read_b128 v[198:201], v176 offset:34816
	ds_read_b128 v[202:205], v176 offset:35840
	ds_read_b128 v[206:209], v176 offset:36864
	ds_read_b128 v[210:213], v176 offset:37888
	ds_read_b128 v[214:217], v176 offset:38912
	ds_read_b128 v[218:221], v176 offset:39936
	global_load_lds_dwordx4 v[228:229], off
	s_mov_b32 m0, s20
	v_lshl_add_u64 v[228:229], s[72:73], 0, v[130:131]
	global_load_lds_dwordx4 v[228:229], off
	s_waitcnt vmcnt(8) lgkmcnt(0)
	s_barrier
	s_setprio 1
	v_mfma_f32_16x16x32_bf16 v[124:127], v[146:149], v[190:193], v[124:127]
	v_mfma_f32_16x16x32_bf16 v[124:127], v[150:153], v[194:197], v[124:127]
	v_mfma_f32_16x16x32_bf16 v[116:119], v[154:157], v[190:193], v[116:119]
	v_mfma_f32_16x16x32_bf16 v[116:119], v[158:161], v[194:197], v[116:119]
	v_mfma_f32_16x16x32_bf16 v[108:111], v[146:149], v[198:201], v[108:111]
	v_mfma_f32_16x16x32_bf16 v[108:111], v[150:153], v[202:205], v[108:111]
	v_mfma_f32_16x16x32_bf16 v[100:103], v[154:157], v[198:201], v[100:103]
	v_mfma_f32_16x16x32_bf16 v[100:103], v[158:161], v[202:205], v[100:103]
	v_mfma_f32_16x16x32_bf16 v[92:95], v[146:149], v[206:209], v[92:95]
	v_mfma_f32_16x16x32_bf16 v[92:95], v[150:153], v[210:213], v[92:95]
	v_mfma_f32_16x16x32_bf16 v[84:87], v[154:157], v[206:209], v[84:87]
	v_mfma_f32_16x16x32_bf16 v[84:87], v[158:161], v[210:213], v[84:87]
	v_mfma_f32_16x16x32_bf16 v[76:79], v[146:149], v[214:217], v[76:79]
	v_mfma_f32_16x16x32_bf16 v[76:79], v[150:153], v[218:221], v[76:79]
	v_mfma_f32_16x16x32_bf16 v[68:71], v[154:157], v[214:217], v[68:71]
	v_mfma_f32_16x16x32_bf16 v[68:71], v[158:161], v[218:221], v[68:71]
	v_mfma_f32_16x16x32_bf16 v[120:123], v[162:165], v[190:193], v[120:123]
	v_mfma_f32_16x16x32_bf16 v[120:123], v[178:181], v[194:197], v[120:123]
	v_mfma_f32_16x16x32_bf16 v[112:115], v[182:185], v[190:193], v[112:115]
	v_mfma_f32_16x16x32_bf16 v[112:115], v[186:189], v[194:197], v[112:115]
	v_mfma_f32_16x16x32_bf16 v[104:107], v[162:165], v[198:201], v[104:107]
	v_mfma_f32_16x16x32_bf16 v[104:107], v[178:181], v[202:205], v[104:107]
	v_mfma_f32_16x16x32_bf16 v[96:99], v[182:185], v[198:201], v[96:99]
	v_mfma_f32_16x16x32_bf16 v[96:99], v[186:189], v[202:205], v[96:99]
	v_mfma_f32_16x16x32_bf16 v[88:91], v[162:165], v[206:209], v[88:91]
	v_mfma_f32_16x16x32_bf16 v[88:91], v[178:181], v[210:213], v[88:91]
	v_mfma_f32_16x16x32_bf16 v[80:83], v[182:185], v[206:209], v[80:83]
	v_mfma_f32_16x16x32_bf16 v[80:83], v[186:189], v[210:213], v[80:83]
	v_mfma_f32_16x16x32_bf16 v[72:75], v[162:165], v[214:217], v[72:75]
	v_mfma_f32_16x16x32_bf16 v[72:75], v[178:181], v[218:221], v[72:75]
	s_setprio 3
	s_barrier
	v_mfma_f32_16x16x32_bf16 v[64:67], v[182:185], v[214:217], v[64:67]
	v_mfma_f32_16x16x32_bf16 v[64:67], v[186:189], v[218:221], v[64:67]
	s_setprio 0
	s_add_i32 s72, s74, s16
	v_lshl_add_u64 v[166:167], v[166:167], 0, s[10:11]
	s_mov_b32 m0, s72
	ds_read_b128 v[190:193], v176 offset:49152
	ds_read_b128 v[194:197], v176 offset:50176
	ds_read_b128 v[198:201], v176 offset:51200
	ds_read_b128 v[202:205], v176 offset:52224
	ds_read_b128 v[206:209], v176 offset:53248
	ds_read_b128 v[210:213], v176 offset:54272
	ds_read_b128 v[214:217], v176 offset:55296
	ds_read_b128 v[218:221], v176 offset:56320
	global_load_lds_dwordx4 v[166:167], off
	s_add_i32 m0, s72, 0x2000
	s_add_u32 s70, s70, 0x40080
	v_lshl_add_u64 v[166:167], v[222:223], 0, s[10:11]
	s_addc_u32 s71, s71, 0
	s_add_i32 s72, s75, s16
	global_load_lds_dwordx4 v[166:167], off
	s_mov_b32 m0, s72
	v_lshl_add_u64 v[166:167], s[70:71], 0, v[132:133]
	global_load_lds_dwordx4 v[166:167], off
	s_add_i32 m0, s72, 0x2000
	v_lshl_add_u64 v[166:167], s[70:71], 0, v[128:129]
	global_load_lds_dwordx4 v[166:167], off
	s_mov_b32 m0, s23
	v_lshl_add_u64 v[166:167], v[224:225], 0, s[10:11]
	global_load_lds_dwordx4 v[166:167], off
	s_mov_b32 m0, s24
	v_lshl_add_u64 v[166:167], v[226:227], 0, s[10:11]
	global_load_lds_dwordx4 v[166:167], off
	s_waitcnt vmcnt(8) lgkmcnt(0)
	s_barrier
	s_setprio 1
	v_mfma_f32_16x16x32_bf16 v[60:63], v[146:149], v[190:193], v[60:63]
	v_mfma_f32_16x16x32_bf16 v[60:63], v[150:153], v[194:197], v[60:63]
	v_mfma_f32_16x16x32_bf16 v[52:55], v[154:157], v[190:193], v[52:55]
	v_mfma_f32_16x16x32_bf16 v[52:55], v[158:161], v[194:197], v[52:55]
	v_mfma_f32_16x16x32_bf16 v[44:47], v[146:149], v[198:201], v[44:47]
	v_mfma_f32_16x16x32_bf16 v[44:47], v[150:153], v[202:205], v[44:47]
	v_mfma_f32_16x16x32_bf16 v[36:39], v[154:157], v[198:201], v[36:39]
	v_mfma_f32_16x16x32_bf16 v[36:39], v[158:161], v[202:205], v[36:39]
	v_mfma_f32_16x16x32_bf16 v[28:31], v[146:149], v[206:209], v[28:31]
	v_mfma_f32_16x16x32_bf16 v[28:31], v[150:153], v[210:213], v[28:31]
	v_mfma_f32_16x16x32_bf16 v[20:23], v[154:157], v[206:209], v[20:23]
	v_mfma_f32_16x16x32_bf16 v[20:23], v[158:161], v[210:213], v[20:23]
	v_mfma_f32_16x16x32_bf16 v[12:15], v[146:149], v[214:217], v[12:15]
	v_mfma_f32_16x16x32_bf16 v[12:15], v[150:153], v[218:221], v[12:15]
	v_mfma_f32_16x16x32_bf16 v[4:7], v[154:157], v[214:217], v[4:7]
	v_mfma_f32_16x16x32_bf16 v[4:7], v[158:161], v[218:221], v[4:7]
	v_mfma_f32_16x16x32_bf16 v[56:59], v[162:165], v[190:193], v[56:59]
	v_mfma_f32_16x16x32_bf16 v[56:59], v[178:181], v[194:197], v[56:59]
	v_mfma_f32_16x16x32_bf16 v[48:51], v[182:185], v[190:193], v[48:51]
	v_mfma_f32_16x16x32_bf16 v[48:51], v[186:189], v[194:197], v[48:51]
	v_mfma_f32_16x16x32_bf16 v[40:43], v[162:165], v[198:201], v[40:43]
	v_mfma_f32_16x16x32_bf16 v[40:43], v[178:181], v[202:205], v[40:43]
	v_mfma_f32_16x16x32_bf16 v[32:35], v[182:185], v[198:201], v[32:35]
	v_mfma_f32_16x16x32_bf16 v[32:35], v[186:189], v[202:205], v[32:35]
	v_mfma_f32_16x16x32_bf16 v[24:27], v[162:165], v[206:209], v[24:27]
	v_mfma_f32_16x16x32_bf16 v[24:27], v[178:181], v[210:213], v[24:27]
	v_mfma_f32_16x16x32_bf16 v[16:19], v[182:185], v[206:209], v[16:19]
	v_mfma_f32_16x16x32_bf16 v[16:19], v[186:189], v[210:213], v[16:19]
	v_mfma_f32_16x16x32_bf16 v[8:11], v[162:165], v[214:217], v[8:11]
	v_mfma_f32_16x16x32_bf16 v[8:11], v[178:181], v[218:221], v[8:11]
	s_setprio 3
	s_barrier
	v_mfma_f32_16x16x32_bf16 v[0:3], v[182:185], v[214:217], v[0:3]
	v_mfma_f32_16x16x32_bf16 v[0:3], v[186:189], v[218:221], v[0:3]
	s_setprio 0
	s_add_i32 s69, s69, 2
	s_add_u32 s58, s58, 0x100
	s_addc_u32 s59, s59, 0
	s_add_u32 s67, s67, 0x100
	s_addc_u32 s68, s68, 0
	s_cmp_gt_u32 s69, 13
	s_cbranch_scc0 .LBB0_2192
	s_branch .Lzskip_10

.LBB0_2341:
	ds_read_b128 v[128:131], v197
	ds_read_b128 v[132:135], v197 offset:1024
	ds_read_b128 v[136:139], v197 offset:2048
	ds_read_b128 v[140:143], v197 offset:3072
	ds_read_b128 v[144:147], v198
	ds_read_b128 v[148:151], v198 offset:1024
	ds_read_b128 v[152:155], v198 offset:2048
	ds_read_b128 v[156:159], v198 offset:3072
	s_add_u32 s18, s16, 0xfff50080
	s_addc_u32 s19, s17, -1
	s_cmp_eq_u32 s45, 40
	s_cselect_b32 s21, s5, s19
	s_cselect_b32 s20, s4, s18
	s_cselect_b32 s19, s15, s44
	s_cselect_b32 s18, s14, s43
	v_lshl_add_u64 v[192:193], s[16:17], 0, v[172:173]
	s_add_i32 m0, s25, 0xc000
	ds_read_b128 v[160:163], v199
	ds_read_b128 v[180:183], v199 offset:1024
	ds_read_b128 v[184:187], v199 offset:2048
	ds_read_b128 v[188:191], v199 offset:3072
	ds_read_b128 v[200:203], v199 offset:4096
	ds_read_b128 v[204:207], v199 offset:5120
	ds_read_b128 v[208:211], v199 offset:6144
	ds_read_b128 v[212:215], v199 offset:7168
	global_load_lds_dwordx4 v[192:193], off
	s_add_i32 m0, s25, 0xe000
	v_lshl_add_u64 v[192:193], s[16:17], 0, v[174:175]
	global_load_lds_dwordx4 v[192:193], off
	s_cmp_eq_u32 s45, -2
	s_waitcnt vmcnt(8) lgkmcnt(0)
	s_barrier
	s_setprio 1
	s_cbranch_scc1 .Lzv_11_0
	v_mfma_f32_16x16x32_bf16 v[124:127], v[128:131], v[160:163], v[124:127]
	v_mfma_f32_16x16x32_bf16 v[124:127], v[132:135], v[180:183], v[124:127]
	v_mfma_f32_16x16x32_bf16 v[120:123], v[136:139], v[160:163], v[120:123]
	v_mfma_f32_16x16x32_bf16 v[120:123], v[140:143], v[180:183], v[120:123]
	v_mfma_f32_16x16x32_bf16 v[108:111], v[128:131], v[184:187], v[108:111]
	v_mfma_f32_16x16x32_bf16 v[108:111], v[132:135], v[188:191], v[108:111]
	v_mfma_f32_16x16x32_bf16 v[104:107], v[136:139], v[184:187], v[104:107]
	v_mfma_f32_16x16x32_bf16 v[104:107], v[140:143], v[188:191], v[104:107]
	v_mfma_f32_16x16x32_bf16 v[96:99], v[128:131], v[200:203], v[96:99]
	v_mfma_f32_16x16x32_bf16 v[96:99], v[132:135], v[204:207], v[96:99]
	v_mfma_f32_16x16x32_bf16 v[88:91], v[136:139], v[200:203], v[88:91]
	v_mfma_f32_16x16x32_bf16 v[88:91], v[140:143], v[204:207], v[88:91]
	v_mfma_f32_16x16x32_bf16 v[80:83], v[128:131], v[208:211], v[80:83]
	v_mfma_f32_16x16x32_bf16 v[80:83], v[132:135], v[212:215], v[80:83]
	v_mfma_f32_16x16x32_bf16 v[72:75], v[136:139], v[208:211], v[72:75]
	v_mfma_f32_16x16x32_bf16 v[72:75], v[140:143], v[212:215], v[72:75]
	v_mfma_f32_16x16x32_bf16 v[116:119], v[144:147], v[160:163], v[116:119]
	v_mfma_f32_16x16x32_bf16 v[116:119], v[148:151], v[180:183], v[116:119]
	v_mfma_f32_16x16x32_bf16 v[112:115], v[152:155], v[160:163], v[112:115]
	v_mfma_f32_16x16x32_bf16 v[112:115], v[156:159], v[180:183], v[112:115]
	v_mfma_f32_16x16x32_bf16 v[100:103], v[144:147], v[184:187], v[100:103]
	v_mfma_f32_16x16x32_bf16 v[100:103], v[148:151], v[188:191], v[100:103]
	v_mfma_f32_16x16x32_bf16 v[92:95], v[152:155], v[184:187], v[92:95]
	v_mfma_f32_16x16x32_bf16 v[92:95], v[156:159], v[188:191], v[92:95]
	v_mfma_f32_16x16x32_bf16 v[84:87], v[144:147], v[200:203], v[84:87]
	v_mfma_f32_16x16x32_bf16 v[84:87], v[148:151], v[204:207], v[84:87]
	v_mfma_f32_16x16x32_bf16 v[76:79], v[152:155], v[200:203], v[76:79]
	v_mfma_f32_16x16x32_bf16 v[76:79], v[156:159], v[204:207], v[76:79]
	v_mfma_f32_16x16x32_bf16 v[68:71], v[144:147], v[208:211], v[68:71]
	v_mfma_f32_16x16x32_bf16 v[68:71], v[148:151], v[212:215], v[68:71]
	s_setprio 3
	s_barrier
	v_mfma_f32_16x16x32_bf16 v[64:67], v[152:155], v[208:211], v[64:67]
	v_mfma_f32_16x16x32_bf16 v[64:67], v[156:159], v[212:215], v[64:67]
	s_setprio 0
.Lzj_11_0:
	s_add_i32 s46, s37, s24
	v_lshl_add_u64 v[192:193], s[18:19], 0, v[166:167]
	s_mov_b32 m0, s46
	ds_read_b128 v[160:163], v199 offset:16384
	ds_read_b128 v[180:183], v199 offset:17408
	ds_read_b128 v[184:187], v199 offset:18432
	ds_read_b128 v[188:191], v199 offset:19456
	ds_read_b128 v[200:203], v199 offset:20480
	ds_read_b128 v[204:207], v199 offset:21504
	ds_read_b128 v[208:211], v199 offset:22528
	ds_read_b128 v[212:215], v199 offset:23552
	global_load_lds_dwordx4 v[192:193], off
	s_add_i32 m0, s46, 0x2000
	s_add_u32 s46, s18, 0xb0000
	v_lshl_add_u64 v[216:217], s[18:19], 0, v[170:171]
	s_addc_u32 s47, s19, 0
	s_add_i32 s48, s38, s24
	global_load_lds_dwordx4 v[216:217], off
	v_lshl_add_u64 v[218:219], s[46:47], 0, v[166:167]
	s_mov_b32 m0, s48
	global_load_lds_dwordx4 v[218:219], off
	s_add_i32 m0, s48, 0x2000
	v_lshl_add_u64 v[218:219], s[46:47], 0, v[170:171]
	global_load_lds_dwordx4 v[218:219], off
	s_mov_b32 m0, s25
	v_lshl_add_u64 v[218:219], s[20:21], 0, v[164:165]
	global_load_lds_dwordx4 v[218:219], off
	s_mov_b32 m0, s26
	v_lshl_add_u64 v[220:221], s[20:21], 0, v[168:169]
	global_load_lds_dwordx4 v[220:221], off
	s_cmp_eq_u32 s45, -2
	s_waitcnt vmcnt(8) lgkmcnt(0)
	s_barrier
	s_setprio 1
	s_cbranch_scc1 .Lzv_11_1
	v_mfma_f32_16x16x32_bf16 v[60:63], v[128:131], v[160:163], v[60:63]
	v_mfma_f32_16x16x32_bf16 v[60:63], v[132:135], v[180:183], v[60:63]
	v_mfma_f32_16x16x32_bf16 v[56:59], v[136:139], v[160:163], v[56:59]
	v_mfma_f32_16x16x32_bf16 v[56:59], v[140:143], v[180:183], v[56:59]
	v_mfma_f32_16x16x32_bf16 v[48:51], v[128:131], v[184:187], v[48:51]
	v_mfma_f32_16x16x32_bf16 v[48:51], v[132:135], v[188:191], v[48:51]
	v_mfma_f32_16x16x32_bf16 v[40:43], v[136:139], v[184:187], v[40:43]
	v_mfma_f32_16x16x32_bf16 v[40:43], v[140:143], v[188:191], v[40:43]
	v_mfma_f32_16x16x32_bf16 v[32:35], v[128:131], v[200:203], v[32:35]
	v_mfma_f32_16x16x32_bf16 v[32:35], v[132:135], v[204:207], v[32:35]
	v_mfma_f32_16x16x32_bf16 v[24:27], v[136:139], v[200:203], v[24:27]
	v_mfma_f32_16x16x32_bf16 v[24:27], v[140:143], v[204:207], v[24:27]
	v_mfma_f32_16x16x32_bf16 v[16:19], v[128:131], v[208:211], v[16:19]
	v_mfma_f32_16x16x32_bf16 v[16:19], v[132:135], v[212:215], v[16:19]
	v_mfma_f32_16x16x32_bf16 v[8:11], v[136:139], v[208:211], v[8:11]
	v_mfma_f32_16x16x32_bf16 v[8:11], v[140:143], v[212:215], v[8:11]
	v_mfma_f32_16x16x32_bf16 v[52:55], v[144:147], v[160:163], v[52:55]
	v_mfma_f32_16x16x32_bf16 v[52:55], v[148:151], v[180:183], v[52:55]
	v_mfma_f32_16x16x32_bf16 v[44:47], v[152:155], v[160:163], v[44:47]
	v_mfma_f32_16x16x32_bf16 v[44:47], v[156:159], v[180:183], v[44:47]
	v_mfma_f32_16x16x32_bf16 v[36:39], v[144:147], v[184:187], v[36:39]
	v_mfma_f32_16x16x32_bf16 v[36:39], v[148:151], v[188:191], v[36:39]
	v_mfma_f32_16x16x32_bf16 v[28:31], v[152:155], v[184:187], v[28:31]
	v_mfma_f32_16x16x32_bf16 v[28:31], v[156:159], v[188:191], v[28:31]
	v_mfma_f32_16x16x32_bf16 v[20:23], v[144:147], v[200:203], v[20:23]
	v_mfma_f32_16x16x32_bf16 v[20:23], v[148:151], v[204:207], v[20:23]
	v_mfma_f32_16x16x32_bf16 v[12:15], v[152:155], v[200:203], v[12:15]
	v_mfma_f32_16x16x32_bf16 v[12:15], v[156:159], v[204:207], v[12:15]
	v_mfma_f32_16x16x32_bf16 v[4:7], v[144:147], v[208:211], v[4:7]
	v_mfma_f32_16x16x32_bf16 v[4:7], v[148:151], v[212:215], v[4:7]
	s_setprio 3
	s_barrier
	v_mfma_f32_16x16x32_bf16 v[0:3], v[152:155], v[208:211], v[0:3]
	v_mfma_f32_16x16x32_bf16 v[0:3], v[156:159], v[212:215], v[0:3]
	s_setprio 0
.Lzj_11_1:
	s_add_i32 s46, 0, 0x18000
	s_add_i32 s47, 0, 0x1c000
	v_add_u32_e32 v140, s46, v195
	v_add_u32_e32 v156, s47, v195
	ds_read_b128 v[128:131], v140
	ds_read_b128 v[132:135], v140 offset:1024
	ds_read_b128 v[136:139], v140 offset:2048
	ds_read_b128 v[140:143], v140 offset:3072
	ds_read_b128 v[144:147], v156
	ds_read_b128 v[148:151], v156 offset:1024
	ds_read_b128 v[152:155], v156 offset:2048
	ds_read_b128 v[156:159], v156 offset:3072
	s_add_u32 s20, s20, 0xb0000
	s_addc_u32 s21, s21, 0
	s_mov_b32 m0, s27
	v_lshl_add_u64 v[222:223], s[20:21], 0, v[164:165]
	ds_read_b128 v[160:163], v199 offset:32768
	ds_read_b128 v[180:183], v199 offset:33792
	ds_read_b128 v[184:187], v199 offset:34816
	ds_read_b128 v[188:191], v199 offset:35840
	ds_read_b128 v[200:203], v199 offset:36864
	ds_read_b128 v[204:207], v199 offset:37888
	ds_read_b128 v[208:211], v199 offset:38912
	ds_read_b128 v[212:215], v199 offset:39936
	global_load_lds_dwordx4 v[222:223], off
	s_mov_b32 m0, s28
	v_lshl_add_u64 v[222:223], s[20:21], 0, v[168:169]
	global_load_lds_dwordx4 v[222:223], off
	s_waitcnt vmcnt(8) lgkmcnt(0)
	s_barrier
	s_setprio 1
	v_mfma_f32_16x16x32_bf16 v[124:127], v[128:131], v[160:163], v[124:127]
	v_mfma_f32_16x16x32_bf16 v[124:127], v[132:135], v[180:183], v[124:127]
	v_mfma_f32_16x16x32_bf16 v[120:123], v[136:139], v[160:163], v[120:123]
	v_mfma_f32_16x16x32_bf16 v[120:123], v[140:143], v[180:183], v[120:123]
	v_mfma_f32_16x16x32_bf16 v[108:111], v[128:131], v[184:187], v[108:111]
	v_mfma_f32_16x16x32_bf16 v[108:111], v[132:135], v[188:191], v[108:111]
	v_mfma_f32_16x16x32_bf16 v[104:107], v[136:139], v[184:187], v[104:107]
	v_mfma_f32_16x16x32_bf16 v[104:107], v[140:143], v[188:191], v[104:107]
	v_mfma_f32_16x16x32_bf16 v[96:99], v[128:131], v[200:203], v[96:99]
	v_mfma_f32_16x16x32_bf16 v[96:99], v[132:135], v[204:207], v[96:99]
	v_mfma_f32_16x16x32_bf16 v[88:91], v[136:139], v[200:203], v[88:91]
	v_mfma_f32_16x16x32_bf16 v[88:91], v[140:143], v[204:207], v[88:91]
	v_mfma_f32_16x16x32_bf16 v[80:83], v[128:131], v[208:211], v[80:83]
	v_mfma_f32_16x16x32_bf16 v[80:83], v[132:135], v[212:215], v[80:83]
	v_mfma_f32_16x16x32_bf16 v[72:75], v[136:139], v[208:211], v[72:75]
	v_mfma_f32_16x16x32_bf16 v[72:75], v[140:143], v[212:215], v[72:75]
	v_mfma_f32_16x16x32_bf16 v[116:119], v[144:147], v[160:163], v[116:119]
	v_mfma_f32_16x16x32_bf16 v[116:119], v[148:151], v[180:183], v[116:119]
	v_mfma_f32_16x16x32_bf16 v[112:115], v[152:155], v[160:163], v[112:115]
	v_mfma_f32_16x16x32_bf16 v[112:115], v[156:159], v[180:183], v[112:115]
	v_mfma_f32_16x16x32_bf16 v[100:103], v[144:147], v[184:187], v[100:103]
	v_mfma_f32_16x16x32_bf16 v[100:103], v[148:151], v[188:191], v[100:103]
	v_mfma_f32_16x16x32_bf16 v[92:95], v[152:155], v[184:187], v[92:95]
	v_mfma_f32_16x16x32_bf16 v[92:95], v[156:159], v[188:191], v[92:95]
	v_mfma_f32_16x16x32_bf16 v[84:87], v[144:147], v[200:203], v[84:87]
	v_mfma_f32_16x16x32_bf16 v[84:87], v[148:151], v[204:207], v[84:87]
	v_mfma_f32_16x16x32_bf16 v[76:79], v[152:155], v[200:203], v[76:79]
	v_mfma_f32_16x16x32_bf16 v[76:79], v[156:159], v[204:207], v[76:79]
	v_mfma_f32_16x16x32_bf16 v[68:71], v[144:147], v[208:211], v[68:71]
	v_mfma_f32_16x16x32_bf16 v[68:71], v[148:151], v[212:215], v[68:71]
	s_setprio 3
	s_barrier
	v_mfma_f32_16x16x32_bf16 v[64:67], v[152:155], v[208:211], v[64:67]
	v_mfma_f32_16x16x32_bf16 v[64:67], v[156:159], v[212:215], v[64:67]
	s_setprio 0
	s_add_i32 s20, s46, s24
	v_lshl_add_u64 v[192:193], v[192:193], 0, s[8:9]
	s_mov_b32 m0, s20
	ds_read_b128 v[160:163], v199 offset:49152
	ds_read_b128 v[180:183], v199 offset:50176
	ds_read_b128 v[184:187], v199 offset:51200
	ds_read_b128 v[188:191], v199 offset:52224
	ds_read_b128 v[200:203], v199 offset:53248
	ds_read_b128 v[204:207], v199 offset:54272
	ds_read_b128 v[208:211], v199 offset:55296
	ds_read_b128 v[212:215], v199 offset:56320
	global_load_lds_dwordx4 v[192:193], off
	s_add_i32 m0, s20, 0x2000
	s_add_u32 s18, s18, 0xb0080
	v_lshl_add_u64 v[192:193], v[216:217], 0, s[8:9]
	s_addc_u32 s19, s19, 0
	s_add_i32 s20, s47, s24
	global_load_lds_dwordx4 v[192:193], off
	s_mov_b32 m0, s20
	v_lshl_add_u64 v[192:193], s[18:19], 0, v[166:167]
	global_load_lds_dwordx4 v[192:193], off
	s_add_i32 m0, s20, 0x2000
	v_lshl_add_u64 v[192:193], s[18:19], 0, v[170:171]
	global_load_lds_dwordx4 v[192:193], off
	s_mov_b32 m0, s33
	v_lshl_add_u64 v[192:193], v[218:219], 0, s[8:9]
	global_load_lds_dwordx4 v[192:193], off
	s_mov_b32 m0, s35
	v_lshl_add_u64 v[192:193], v[220:221], 0, s[8:9]
	global_load_lds_dwordx4 v[192:193], off
	s_waitcnt vmcnt(8) lgkmcnt(0)
	s_barrier
	s_setprio 1
	v_mfma_f32_16x16x32_bf16 v[60:63], v[128:131], v[160:163], v[60:63]
	v_mfma_f32_16x16x32_bf16 v[60:63], v[132:135], v[180:183], v[60:63]
	v_mfma_f32_16x16x32_bf16 v[56:59], v[136:139], v[160:163], v[56:59]
	v_mfma_f32_16x16x32_bf16 v[56:59], v[140:143], v[180:183], v[56:59]
	v_mfma_f32_16x16x32_bf16 v[48:51], v[128:131], v[184:187], v[48:51]
	v_mfma_f32_16x16x32_bf16 v[48:51], v[132:135], v[188:191], v[48:51]
	v_mfma_f32_16x16x32_bf16 v[40:43], v[136:139], v[184:187], v[40:43]
	v_mfma_f32_16x16x32_bf16 v[40:43], v[140:143], v[188:191], v[40:43]
	v_mfma_f32_16x16x32_bf16 v[32:35], v[128:131], v[200:203], v[32:35]
	v_mfma_f32_16x16x32_bf16 v[32:35], v[132:135], v[204:207], v[32:35]
	v_mfma_f32_16x16x32_bf16 v[24:27], v[136:139], v[200:203], v[24:27]
	v_mfma_f32_16x16x32_bf16 v[24:27], v[140:143], v[204:207], v[24:27]
	v_mfma_f32_16x16x32_bf16 v[16:19], v[128:131], v[208:211], v[16:19]
	v_mfma_f32_16x16x32_bf16 v[16:19], v[132:135], v[212:215], v[16:19]
	v_mfma_f32_16x16x32_bf16 v[8:11], v[136:139], v[208:211], v[8:11]
	v_mfma_f32_16x16x32_bf16 v[8:11], v[140:143], v[212:215], v[8:11]
	v_mfma_f32_16x16x32_bf16 v[52:55], v[144:147], v[160:163], v[52:55]
	v_mfma_f32_16x16x32_bf16 v[52:55], v[148:151], v[180:183], v[52:55]
	v_mfma_f32_16x16x32_bf16 v[44:47], v[152:155], v[160:163], v[44:47]
	v_mfma_f32_16x16x32_bf16 v[44:47], v[156:159], v[180:183], v[44:47]
	v_mfma_f32_16x16x32_bf16 v[36:39], v[144:147], v[184:187], v[36:39]
	v_mfma_f32_16x16x32_bf16 v[36:39], v[148:151], v[188:191], v[36:39]
	v_mfma_f32_16x16x32_bf16 v[28:31], v[152:155], v[184:187], v[28:31]
	v_mfma_f32_16x16x32_bf16 v[28:31], v[156:159], v[188:191], v[28:31]
	v_mfma_f32_16x16x32_bf16 v[20:23], v[144:147], v[200:203], v[20:23]
	v_mfma_f32_16x16x32_bf16 v[20:23], v[148:151], v[204:207], v[20:23]
	v_mfma_f32_16x16x32_bf16 v[12:15], v[152:155], v[200:203], v[12:15]
	v_mfma_f32_16x16x32_bf16 v[12:15], v[156:159], v[204:207], v[12:15]
	v_mfma_f32_16x16x32_bf16 v[4:7], v[144:147], v[208:211], v[4:7]
	v_mfma_f32_16x16x32_bf16 v[4:7], v[148:151], v[212:215], v[4:7]
	s_setprio 3
	s_barrier
	v_mfma_f32_16x16x32_bf16 v[0:3], v[152:155], v[208:211], v[0:3]
	v_mfma_f32_16x16x32_bf16 v[0:3], v[156:159], v[212:215], v[0:3]
	s_setprio 0
	s_add_i32 s45, s45, 2
	s_add_u32 s16, s16, 0x100
	s_addc_u32 s17, s17, 0
	s_add_u32 s43, s43, 0x100
	s_addc_u32 s44, s44, 0
	s_cmp_gt_u32 s45, 41
	s_cbranch_scc0 .LBB0_2341
	s_branch .Lzskip_11
